# K-loops: LDS A-fragment read addresses via one precomputed VGPR + immediate offsets (18 v_add_u32 removed from load waves)
# speedup vs baseline: 1.0279x; 1.0148x over previous
; #define PG8_STAGE(bufoff, gbase, voff) do { _Pragma("unroll") for (int _i = 0; _i < 2; ++_i) \
;         __builtin_amdgcn_global_load_lds((const unsigned*)((const char*)(gbase) + (voff)[_i]), (LAS unsigned*)(lds + (bufoff) + ldsw + _i * 8192), 16, 0, 0); } while (0)
; #define PG8_WAIT_V(n) asm volatile("s_waitcnt vmcnt(" #n ")" ::: "memory")
; #define PG8_BAR __builtin_amdgcn_s_barrier()
; template <class Epi>
; __device__ __forceinline__ void gemm_phase(ldsp lds, const Gemm g, const StaticOrder& S, const Epi& E) {
;     const int tid = threadIdx.x, wid = __builtin_amdgcn_readfirstlane(tid >> 6), lane = tid & 63, wr = wid >> 2, wc = wid & 3, fr = lane & 15, fq = lane >> 4;
;     const int K = g.K, nt = K / BK;
;     unsigned voffA[2], voffB[2];
; #pragma unroll
;     for (int i = 0; i < 2; ++i) { int R, C; stage_rc(tid * 16 + i * 8192, R, C); const int Rb = (R & ~31) + perm32(R & 31);
;         voffA[i] = (unsigned)(R * K + C) * 2u; voffB[i] = (unsigned)(Rb * K + C) * 2u; }
;     const size_t kstep = (size_t)(BK * 2);
;     const size_t hstep = (size_t)HALF * K * 2;
;     const size_t tstep = 2 * hstep;
;     const unsigned ldsw = (unsigned)wid * 1024u;
;     const int aoff = lds_byte(wr * 64 + fr, fq * 8), boff = lds_byte(wc * 32 + fr, fq * 8);
;     ...
;     Unit cur, nxt; int ui = 0;
;     if (!S.next(0, cur)) return;
;     f32x4 acc[2][2][4][2];
; #pragma unroll
;     for (int a = 0; a < 2; ++a)
; #pragma unroll
;         for (int b = 0; b < 2; ++b)
; #pragma unroll
;             for (int m = 0; m < 4; ++m)
; #pragma unroll
;                 for (int n = 0; n < 2; ++n) acc[a][b][m][n] = (f32x4){0.f, 0.f, 0.f, 0.f};
;     bf16x8 At[4][2], B0[2][2], B1[2][2];
;     unsigned pre[Epi::NPRE > 0 ? Epi::NPRE : 1];
;     const char* cA = (const char*)g.A + (size_t)cur.pm * tstep; const char* cB = (const char*)g.Bt + (size_t)cur.pn * tstep;
;     PG8_STAGE(PG8_SB(0, 0), cB, voffB); PG8_STAGE(PG8_SA(0, 0), cA, voffA); PG8_STAGE(PG8_SB(0, 1), cB + hstep, voffB); PG8_STAGE(PG8_SA(0, 1), cA + hstep, voffA);
;     if (wr == 1) PG8_BAR;
;     PG8_WAIT_V(4); PG8_BAR;
;     PG8_STAGE(PG8_SB(1, 0), cB + kstep, voffB); PG8_STAGE(PG8_SA(1, 0), cA + kstep, voffA); PG8_STAGE(PG8_SB(1, 1), cB + hstep + kstep, voffB);
;     PG8_WAIT_V(6); PG8_BAR;
.LBB0_127:
	v_readlane_b32 s28, v246, 48
	v_readlane_b32 s29, v246, 49
	s_add_u32 s10, s28, 0x13340000
	s_addc_u32 s11, s29, 0
	s_add_u32 s12, s28, 0x15340000
	s_addc_u32 s13, s29, 0
	s_add_u32 s14, s28, 0x19340000
	s_addc_u32 s15, s29, 0
	s_add_u32 s16, s28, 0x1d340000
	s_addc_u32 s17, s29, 0
	s_add_u32 s18, s28, 0x1f340000
	s_addc_u32 s19, s29, 0
	s_add_u32 s20, s28, 0x27340000
	s_mov_b64 s[22:23], 0x80
	s_addc_u32 s21, s29, 0
	s_and_b32 s5, s3, 3
	s_add_i32 m0, s45, 0x18000
	v_lshl_add_u64 v[6:7], v[6:7], 0, s[22:23]
	s_lshl_b32 s3, s2, 13
	s_lshl_b32 s7, s5, 12
	s_waitcnt vmcnt(4)
	s_barrier
	global_load_lds_dwordx4 v[6:7], off
	v_lshl_add_u64 v[4:5], v[4:5], 0, s[22:23]
	s_add_i32 m0, s45, 0x1a000
	s_add_i32 s52, s45, 0x8000
	s_add_i32 s53, s45, 0xa000
	global_load_lds_dwordx4 v[4:5], off
	v_lshl_add_u64 v[2:3], v[2:3], 0, s[22:23]
	s_mov_b32 m0, s52
	s_add_u32 s24, s36, 0x80080
	global_load_lds_dwordx4 v[2:3], off
	v_lshl_add_u64 v[0:1], v[0:1], 0, s[22:23]
	s_mov_b32 m0, s53
	s_addc_u32 s25, s37, 0
	global_load_lds_dwordx4 v[0:1], off
	s_add_i32 m0, s45, 0x1c000
	v_lshl_add_u64 v[0:1], s[24:25], 0, v[130:131]
	global_load_lds_dwordx4 v[0:1], off
	v_lshl_add_u64 v[0:1], s[24:25], 0, v[134:135]
	s_add_i32 m0, s45, 0x1e000
	v_lshlrev_b32_e32 v4, 2, v220
	global_load_lds_dwordx4 v[0:1], off
	v_lshrrev_b32_e32 v0, 4, v220
	v_and_b32_e32 v0, 3, v0
	v_and_b32_e32 v1, 15, v220
	v_lshlrev_b32_e32 v3, 4, v0
	v_lshl_or_b32 v180, s2, 6, v1
	v_lshl_or_b32 v1, v1, 6, v3
	v_and_b32_e32 v4, 32, v4
	v_bitop3_b32 v5, v1, s3, v4 bitop3:0xde
	v_lshlrev_b32_e32 v1, 6, v220
	s_movk_i32 s2, 0x3c0
	v_and_or_b32 v1, v1, s2, v3
	s_cmp_eq_u32 s5, 0
	v_lshlrev_b32_e32 v2, 3, v0
	v_bitop3_b32 v181, s7, v1, v4 bitop3:0xf6
	v_add_u32_e32 v247, 0x10000, v181
	s_cselect_b64 s[2:3], -1, 0
	v_cmp_gt_u32_e32 vcc, 2, v0
	v_lshlrev_b32_e32 v0, 5, v0
	v_mov_b32_e32 v1, v131
	s_and_b64 s[24:25], s[2:3], vcc
	v_lshl_add_u64 v[0:1], s[28:29], 0, v[0:1]
	s_mov_b64 s[2:3], 0x1c0000
	v_lshl_add_u64 v[136:137], v[0:1], 0, s[2:3]
	v_lshlrev_b32_e32 v0, 9, v220
	v_and_b32_e32 v0, 0x70000, v0
	v_lshlrev_b32_e32 v1, 12, v10
	v_or3_b32 v0, v8, v0, v1
	v_add_u32_e32 v138, v0, v9
	v_lshlrev_b32_e32 v0, 5, v11
	s_waitcnt vmcnt(6)
	v_and_b32_e32 v0, 0xf0000, v0
	v_or3_b32 v0, v8, v0, v1
	s_ashr_i32 s54, s62, 31
	s_mov_b32 s55, s62
	s_ashr_i32 s56, s96, 31
	v_lshl_or_b32 v182, s5, 5, v2
	v_mov_b32_e32 v139, v131
	v_add_u32_e32 v140, v0, v9
	v_mov_b32_e32 v141, v131
	v_mov_b64_e32 v[142:143], 0xf80
	v_mov_b64_e32 v[144:145], 0xf7f
	s_add_i32 s57, 0, 0x10000
	v_add_u32_e32 v183, 0, v5
	s_add_i32 s58, 0, 0x14000
	v_readlane_b32 s30, v246, 50
	v_readlane_b32 s31, v246, 51
	s_barrier
	s_branch .LBB0_130

; #define PG8_STAGE(bufoff, gbase, voff) do { _Pragma("unroll") for (int _i = 0; _i < 2; ++_i) \
;         __builtin_amdgcn_global_load_lds((const unsigned*)((const char*)(gbase) + (voff)[_i]), (LAS unsigned*)(lds + (bufoff) + ldsw + _i * 8192), 16, 0, 0); } while (0)
; #define PG8_LDA(dst, b, h) do { _Pragma("unroll") for (int m = 0; m < 4; ++m) _Pragma("unroll") for (int k = 0; k < 2; ++k) dst[m][k] = *(const LAS bf16x8*)(lds + PG8_SA(b, h) + aoff + m * 2048 + k * 1024); } while (0)
; #define PG8_LDB(dst, b, h) do { _Pragma("unroll") for (int n = 0; n < 2; ++n) _Pragma("unroll") for (int k = 0; k < 2; ++k) dst[n][k] = *(const LAS bf16x8*)(lds + PG8_SB(b, h) + boff + n * 2048 + k * 1024); } while (0)
; #define PG8_MMA(ai, bj, At, Bt) do { __builtin_amdgcn_s_setprio(1); _Pragma("unroll") for (int m = 0; m < 4; ++m) _Pragma("unroll") for (int n = 0; n < 2; ++n) _Pragma("unroll") for (int k = 0; k < 2; ++k) \
;         acc[ai][bj][m][n] = __builtin_amdgcn_mfma_f32_16x16x32_bf16(Bt[n][k], At[m][k], acc[ai][bj][m][n], 0, 0, 0); __builtin_amdgcn_s_setprio(0); } while (0)
; #define PG8_BAR __builtin_amdgcn_s_barrier()
; template <class Epi>
; __device__ __forceinline__ void gemm_phase(ldsp lds, const Gemm g, const StaticOrder& S, const Epi& E) {
;     ...
;         for (int t = 0; t < nt; t += 2) {
;             const bool last = (t == nt - 2);
;             const char* a1 = cA + (size_t)(t + 1) * kstep;
;             const char* a2 = last ? nA : cA + (size_t)(t + 2) * kstep; const char* b2 = last ? nB : cB + (size_t)(t + 2) * kstep;
;             const char* a3 = a2 + kstep; const char* b3 = b2 + kstep;
;             if constexpr (Epi::NPRE > 0) { if (last) E.pre(pre, cur, wr, fr); }
;             if constexpr (Epi::MID_T > 0) { if (t == Epi::MID_T) E.mid(acc, cur, wr, wc, fr, fq); }
;             PG8_LDB(B0, 0, 0); PG8_SCHED; PG8_LDA(At, 0, 0); PG8_STAGE(PG8_SA(1, 1), a1 + hstep, voffA);
;             PG8_WAIT_L(8); PG8_WAIT_V(10); PG8_BAR; PG8_WAIT_L(0); PG8_MMA(0, 0, At, B0); PG8_BAR; PG8_SCHED;
;             PG8_LDB(B1, 0, 1); PG8_STAGE(PG8_SB(0, 0), b2, voffB);
;             PG8_WAIT_V(10); PG8_BAR; PG8_WAIT_L(0); PG8_MMA(0, 1, At, B1); PG8_BAR;
;             PG8_LDA(At, 0, 1); PG8_STAGE(PG8_SA(0, 0), a2, voffA);
;             PG8_WAIT_V(10); PG8_BAR; PG8_WAIT_L(0); PG8_MMA(1, 0, At, B0); PG8_BAR; PG8_SCHED;
;             PG8_STAGE(PG8_SB(0, 1), b2 + hstep, voffB);
.LBB0_133:
	ds_read_b128 v[166:169], v247 offset:0
	ds_read_b128 v[170:173], v247 offset:1024
	ds_read_b128 v[174:177], v247 offset:2048
	ds_read_b128 v[184:187], v247 offset:3072
	s_add_u32 s38, s4, 0xfff80080
	s_addc_u32 s39, s5, -1
	s_and_b64 s[36:37], s[36:37], exec
	s_cselect_b32 s39, s7, s39
	s_cselect_b32 s38, s29, s38
	s_cselect_b32 s37, s27, s42
	s_cselect_b32 s36, s40, s41
	s_add_i32 m0, s45, 0xc000
	ds_read_b128 v[188:191], v183
	ds_read_b128 v[192:195], v183 offset:1024
	ds_read_b128 v[196:199], v183 offset:2048
	ds_read_b128 v[200:203], v183 offset:3072
	ds_read_b128 v[204:207], v183 offset:4096
	ds_read_b128 v[208:211], v183 offset:5120
	ds_read_b128 v[212:215], v183 offset:6144
	ds_read_b128 v[216:219], v183 offset:7168
	global_load_lds_dwordx4 v138, s[4:5]
	s_add_i32 m0, s45, 0xe000
	s_nop 0
	global_load_lds_dwordx4 v140, s[4:5]
	s_waitcnt lgkmcnt(8)
	s_waitcnt vmcnt(10)
	s_barrier
	s_waitcnt lgkmcnt(0)
	s_setprio 1
	s_waitcnt lgkmcnt(0)
	v_mfma_f32_16x16x32_bf16 v[60:63], v[166:169], v[188:191], v[60:63]
	v_mfma_f32_16x16x32_bf16 v[56:59], v[174:177], v[188:191], v[56:59]
	v_mfma_f32_16x16x32_bf16 v[52:55], v[166:169], v[196:199], v[52:55]
	v_mfma_f32_16x16x32_bf16 v[48:51], v[174:177], v[196:199], v[48:51]
	v_mfma_f32_16x16x32_bf16 v[44:47], v[166:169], v[204:207], v[44:47]
	v_mfma_f32_16x16x32_bf16 v[40:43], v[174:177], v[204:207], v[40:43]
	v_mfma_f32_16x16x32_bf16 v[36:39], v[166:169], v[212:215], v[36:39]
	v_mfma_f32_16x16x32_bf16 v[32:35], v[174:177], v[212:215], v[32:35]
	v_mfma_f32_16x16x32_bf16 v[60:63], v[170:173], v[192:195], v[60:63]
	v_mfma_f32_16x16x32_bf16 v[56:59], v[184:187], v[192:195], v[56:59]
	v_mfma_f32_16x16x32_bf16 v[52:55], v[170:173], v[200:203], v[52:55]
	v_mfma_f32_16x16x32_bf16 v[48:51], v[184:187], v[200:203], v[48:51]
	v_mfma_f32_16x16x32_bf16 v[44:47], v[170:173], v[208:211], v[44:47]
	v_mfma_f32_16x16x32_bf16 v[40:43], v[184:187], v[208:211], v[40:43]
	v_mfma_f32_16x16x32_bf16 v[36:39], v[170:173], v[216:219], v[36:39]
	s_barrier
	v_mfma_f32_16x16x32_bf16 v[32:35], v[184:187], v[216:219], v[32:35]
	s_setprio 0
	s_add_i32 s59, s57, s44
	s_add_u32 s98, s36, 0x80
	s_addc_u32 s99, s37, 0
	s_mov_b32 m0, s59
	ds_read_b128 v[222:225], v247 offset:16384
	ds_read_b128 v[226:229], v247 offset:17408
	ds_read_b128 v[230:233], v247 offset:18432
	ds_read_b128 v[234:237], v247 offset:19456
	global_load_lds_dwordx4 v130, s[36:37]
	s_add_i32 m0, s59, 0x2000
	s_nop 0
	global_load_lds_dwordx4 v134, s[36:37]
	s_waitcnt vmcnt(10)
	s_barrier
	s_waitcnt lgkmcnt(0)
	s_setprio 1
	s_waitcnt lgkmcnt(0)
	v_mfma_f32_16x16x32_bf16 v[124:127], v[222:225], v[188:191], v[124:127]
	v_mfma_f32_16x16x32_bf16 v[120:123], v[230:233], v[188:191], v[120:123]
	v_mfma_f32_16x16x32_bf16 v[116:119], v[222:225], v[196:199], v[116:119]
	v_mfma_f32_16x16x32_bf16 v[112:115], v[230:233], v[196:199], v[112:115]
	v_mfma_f32_16x16x32_bf16 v[108:111], v[222:225], v[204:207], v[108:111]
	v_mfma_f32_16x16x32_bf16 v[104:107], v[230:233], v[204:207], v[104:107]
	v_mfma_f32_16x16x32_bf16 v[100:103], v[222:225], v[212:215], v[100:103]
	v_mfma_f32_16x16x32_bf16 v[96:99], v[230:233], v[212:215], v[96:99]
	v_mfma_f32_16x16x32_bf16 v[124:127], v[226:229], v[192:195], v[124:127]
	v_mfma_f32_16x16x32_bf16 v[120:123], v[234:237], v[192:195], v[120:123]
	v_mfma_f32_16x16x32_bf16 v[116:119], v[226:229], v[200:203], v[116:119]
	v_mfma_f32_16x16x32_bf16 v[112:115], v[234:237], v[200:203], v[112:115]
	v_mfma_f32_16x16x32_bf16 v[108:111], v[226:229], v[208:211], v[108:111]
	v_mfma_f32_16x16x32_bf16 v[104:107], v[234:237], v[208:211], v[104:107]
	v_mfma_f32_16x16x32_bf16 v[100:103], v[226:229], v[216:219], v[100:103]
	s_barrier
	v_mfma_f32_16x16x32_bf16 v[96:99], v[234:237], v[216:219], v[96:99]
	s_setprio 0
	s_mov_b32 m0, s45
	s_add_u32 s100, s38, 0x80
	s_addc_u32 s101, s39, 0
	ds_read_b128 v[188:191], v183 offset:16384
	ds_read_b128 v[192:195], v183 offset:17408
	ds_read_b128 v[196:199], v183 offset:18432
	ds_read_b128 v[200:203], v183 offset:19456
	ds_read_b128 v[204:207], v183 offset:20480
	ds_read_b128 v[208:211], v183 offset:21504
	ds_read_b128 v[212:215], v183 offset:22528
	ds_read_b128 v[216:219], v183 offset:23552
	global_load_lds_dwordx4 v128, s[38:39]
	s_mov_b32 m0, s46
	s_nop 0
	global_load_lds_dwordx4 v132, s[38:39]
	s_waitcnt vmcnt(10)
	s_barrier
	s_waitcnt lgkmcnt(0)
	s_setprio 1
	s_waitcnt lgkmcnt(0)
	v_mfma_f32_16x16x32_bf16 v[28:31], v[166:169], v[188:191], v[28:31]
	v_mfma_f32_16x16x32_bf16 v[24:27], v[174:177], v[188:191], v[24:27]
	v_mfma_f32_16x16x32_bf16 v[20:23], v[166:169], v[196:199], v[20:23]
	v_mfma_f32_16x16x32_bf16 v[16:19], v[174:177], v[196:199], v[16:19]
	v_mfma_f32_16x16x32_bf16 v[12:15], v[166:169], v[204:207], v[12:15]
	v_mfma_f32_16x16x32_bf16 v[8:11], v[174:177], v[204:207], v[8:11]
	v_mfma_f32_16x16x32_bf16 v[4:7], v[166:169], v[212:215], v[4:7]
	v_mfma_f32_16x16x32_bf16 v[0:3], v[174:177], v[212:215], v[0:3]
	v_mfma_f32_16x16x32_bf16 v[28:31], v[170:173], v[192:195], v[28:31]
	v_mfma_f32_16x16x32_bf16 v[24:27], v[184:187], v[192:195], v[24:27]
	v_mfma_f32_16x16x32_bf16 v[20:23], v[170:173], v[200:203], v[20:23]
	v_mfma_f32_16x16x32_bf16 v[16:19], v[184:187], v[200:203], v[16:19]
	v_mfma_f32_16x16x32_bf16 v[12:15], v[170:173], v[208:211], v[12:15]
	v_mfma_f32_16x16x32_bf16 v[8:11], v[184:187], v[208:211], v[8:11]
	v_mfma_f32_16x16x32_bf16 v[4:7], v[170:173], v[216:219], v[4:7]
	s_barrier
	v_mfma_f32_16x16x32_bf16 v[0:3], v[184:187], v[216:219], v[0:3]
	s_setprio 0
	s_add_u32 s60, s36, 0x80000
	s_addc_u32 s61, s37, 0
	s_add_i32 s59, s58, s44
	s_mov_b32 m0, s59
	s_nop 0
	global_load_lds_dwordx4 v130, s[60:61]
	s_add_i32 m0, s59, 0x2000
	s_nop 0
	global_load_lds_dwordx4 v134, s[60:61]
	s_waitcnt vmcnt(10)
	s_barrier
; #define PG8_STAGE(bufoff, gbase, voff) do { _Pragma("unroll") for (int _i = 0; _i < 2; ++_i) \
;         __builtin_amdgcn_global_load_lds((const unsigned*)((const char*)(gbase) + (voff)[_i]), (LAS unsigned*)(lds + (bufoff) + ldsw + _i * 8192), 16, 0, 0); } while (0)
; #define PG8_LDA(dst, b, h) do { _Pragma("unroll") for (int m = 0; m < 4; ++m) _Pragma("unroll") for (int k = 0; k < 2; ++k) dst[m][k] = *(const LAS bf16x8*)(lds + PG8_SA(b, h) + aoff + m * 2048 + k * 1024); } while (0)
; #define PG8_LDB(dst, b, h) do { _Pragma("unroll") for (int n = 0; n < 2; ++n) _Pragma("unroll") for (int k = 0; k < 2; ++k) dst[n][k] = *(const LAS bf16x8*)(lds + PG8_SB(b, h) + boff + n * 2048 + k * 1024); } while (0)
; #define PG8_MMA(ai, bj, At, Bt) do { __builtin_amdgcn_s_setprio(1); _Pragma("unroll") for (int m = 0; m < 4; ++m) _Pragma("unroll") for (int n = 0; n < 2; ++n) _Pragma("unroll") for (int k = 0; k < 2; ++k) \
;         acc[ai][bj][m][n] = __builtin_amdgcn_mfma_f32_16x16x32_bf16(Bt[n][k], At[m][k], acc[ai][bj][m][n], 0, 0, 0); __builtin_amdgcn_s_setprio(0); } while (0)
; #define PG8_WAIT_V(n) asm volatile("s_waitcnt vmcnt(" #n ")" ::: "memory")
; #define PG8_WAIT_L(n) asm volatile("s_waitcnt lgkmcnt(" #n ")" ::: "memory")
; #define PG8_BAR __builtin_amdgcn_s_barrier()
; #define PG8_SCHED __builtin_amdgcn_sched_barrier(0)
; template <class Epi>
; __device__ __forceinline__ void gemm_phase(ldsp lds, const Gemm g, const StaticOrder& S, const Epi& E) {
;     ...
;             PG8_WAIT_V(10); PG8_BAR; PG8_MMA(1, 1, At, B1); PG8_BAR;
;             PG8_LDB(B0, 1, 0); PG8_SCHED; PG8_LDA(At, 1, 0); PG8_STAGE(PG8_SA(0, 1), a2 + hstep, voffA);
;             PG8_WAIT_L(8); PG8_WAIT_V(10); PG8_BAR; PG8_WAIT_L(0); PG8_MMA(0, 0, At, B0); PG8_BAR; PG8_SCHED;
;             PG8_LDB(B1, 1, 1); PG8_STAGE(PG8_SB(1, 0), b3, voffB);
;             PG8_WAIT_V(10); PG8_BAR; PG8_WAIT_L(0); PG8_MMA(0, 1, At, B1); PG8_BAR;
;             PG8_LDA(At, 1, 1); PG8_STAGE(PG8_SA(1, 0), a3, voffA);
	s_setprio 1
	v_mfma_f32_16x16x32_bf16 v[92:95], v[222:225], v[188:191], v[92:95]
	v_mfma_f32_16x16x32_bf16 v[88:91], v[230:233], v[188:191], v[88:91]
	v_mfma_f32_16x16x32_bf16 v[84:87], v[222:225], v[196:199], v[84:87]
	v_mfma_f32_16x16x32_bf16 v[80:83], v[230:233], v[196:199], v[80:83]
	v_mfma_f32_16x16x32_bf16 v[76:79], v[222:225], v[204:207], v[76:79]
	v_mfma_f32_16x16x32_bf16 v[72:75], v[230:233], v[204:207], v[72:75]
	v_mfma_f32_16x16x32_bf16 v[68:71], v[222:225], v[212:215], v[68:71]
	v_mfma_f32_16x16x32_bf16 v[64:67], v[230:233], v[212:215], v[64:67]
	v_mfma_f32_16x16x32_bf16 v[92:95], v[226:229], v[192:195], v[92:95]
	v_mfma_f32_16x16x32_bf16 v[88:91], v[234:237], v[192:195], v[88:91]
	v_mfma_f32_16x16x32_bf16 v[84:87], v[226:229], v[200:203], v[84:87]
	v_mfma_f32_16x16x32_bf16 v[80:83], v[234:237], v[200:203], v[80:83]
	v_mfma_f32_16x16x32_bf16 v[76:79], v[226:229], v[208:211], v[76:79]
	v_mfma_f32_16x16x32_bf16 v[72:75], v[234:237], v[208:211], v[72:75]
	v_mfma_f32_16x16x32_bf16 v[68:71], v[226:229], v[216:219], v[68:71]
	s_barrier
	v_mfma_f32_16x16x32_bf16 v[64:67], v[234:237], v[216:219], v[64:67]
	s_setprio 0
	s_add_i32 s59, 0, 0x18000
	ds_read_b128 v[166:169], v247 offset:32768
	ds_read_b128 v[170:173], v247 offset:33792
	ds_read_b128 v[174:177], v247 offset:34816
	ds_read_b128 v[184:187], v247 offset:35840
	s_add_u32 s38, s38, 0x80000
	s_addc_u32 s39, s39, 0
	s_mov_b32 m0, s47
	ds_read_b128 v[188:191], v183 offset:32768
	ds_read_b128 v[192:195], v183 offset:33792
	ds_read_b128 v[196:199], v183 offset:34816
	ds_read_b128 v[200:203], v183 offset:35840
	ds_read_b128 v[204:207], v183 offset:36864
	ds_read_b128 v[208:211], v183 offset:37888
	ds_read_b128 v[212:215], v183 offset:38912
	ds_read_b128 v[216:219], v183 offset:39936
	global_load_lds_dwordx4 v128, s[38:39]
	s_mov_b32 m0, s50
	s_nop 0
	global_load_lds_dwordx4 v132, s[38:39]
	s_waitcnt lgkmcnt(8)
	s_waitcnt vmcnt(10)
	s_barrier
	s_waitcnt lgkmcnt(0)
	s_setprio 1
	s_waitcnt lgkmcnt(0)
	v_mfma_f32_16x16x32_bf16 v[60:63], v[166:169], v[188:191], v[60:63]
	v_mfma_f32_16x16x32_bf16 v[56:59], v[174:177], v[188:191], v[56:59]
	v_mfma_f32_16x16x32_bf16 v[52:55], v[166:169], v[196:199], v[52:55]
	v_mfma_f32_16x16x32_bf16 v[48:51], v[174:177], v[196:199], v[48:51]
	v_mfma_f32_16x16x32_bf16 v[44:47], v[166:169], v[204:207], v[44:47]
	v_mfma_f32_16x16x32_bf16 v[40:43], v[174:177], v[204:207], v[40:43]
	v_mfma_f32_16x16x32_bf16 v[36:39], v[166:169], v[212:215], v[36:39]
	v_mfma_f32_16x16x32_bf16 v[32:35], v[174:177], v[212:215], v[32:35]
	v_mfma_f32_16x16x32_bf16 v[60:63], v[170:173], v[192:195], v[60:63]
	v_mfma_f32_16x16x32_bf16 v[56:59], v[184:187], v[192:195], v[56:59]
	v_mfma_f32_16x16x32_bf16 v[52:55], v[170:173], v[200:203], v[52:55]
	v_mfma_f32_16x16x32_bf16 v[48:51], v[184:187], v[200:203], v[48:51]
	v_mfma_f32_16x16x32_bf16 v[44:47], v[170:173], v[208:211], v[44:47]
	v_mfma_f32_16x16x32_bf16 v[40:43], v[184:187], v[208:211], v[40:43]
	v_mfma_f32_16x16x32_bf16 v[36:39], v[170:173], v[216:219], v[36:39]
	s_barrier
	v_mfma_f32_16x16x32_bf16 v[32:35], v[184:187], v[216:219], v[32:35]
	s_setprio 0
	s_add_i32 s38, 0, 0x1c000
	s_add_i32 s39, s59, s44
	s_mov_b32 m0, s39
	ds_read_b128 v[222:225], v247 offset:49152
	ds_read_b128 v[226:229], v247 offset:50176
	ds_read_b128 v[230:233], v247 offset:51200
	ds_read_b128 v[234:237], v247 offset:52224
	global_load_lds_dwordx4 v130, s[98:99]
	s_add_i32 m0, s39, 0x2000
	s_nop 0
	global_load_lds_dwordx4 v134, s[98:99]
	s_waitcnt vmcnt(10)
	s_barrier
; #define PG8_STAGE(bufoff, gbase, voff) do { _Pragma("unroll") for (int _i = 0; _i < 2; ++_i) \
;         __builtin_amdgcn_global_load_lds((const unsigned*)((const char*)(gbase) + (voff)[_i]), (LAS unsigned*)(lds + (bufoff) + ldsw + _i * 8192), 16, 0, 0); } while (0)
; #define PG8_MMA(ai, bj, At, Bt) do { __builtin_amdgcn_s_setprio(1); _Pragma("unroll") for (int m = 0; m < 4; ++m) _Pragma("unroll") for (int n = 0; n < 2; ++n) _Pragma("unroll") for (int k = 0; k < 2; ++k) \
;         acc[ai][bj][m][n] = __builtin_amdgcn_mfma_f32_16x16x32_bf16(Bt[n][k], At[m][k], acc[ai][bj][m][n], 0, 0, 0); __builtin_amdgcn_s_setprio(0); } while (0)
; #define PG8_WAIT_V(n) asm volatile("s_waitcnt vmcnt(" #n ")" ::: "memory")
; #define PG8_WAIT_L(n) asm volatile("s_waitcnt lgkmcnt(" #n ")" ::: "memory")
; #define PG8_BAR __builtin_amdgcn_s_barrier()
; #define PG8_SCHED __builtin_amdgcn_sched_barrier(0)
; template <class Epi>
; __device__ __forceinline__ void gemm_phase(ldsp lds, const Gemm g, const StaticOrder& S, const Epi& E) {
;     ...
;             PG8_WAIT_V(10); PG8_BAR; PG8_WAIT_L(0); PG8_MMA(1, 0, At, B0); PG8_BAR; PG8_SCHED;
;             PG8_STAGE(PG8_SB(1, 1), b3 + hstep, voffB);
;             PG8_WAIT_V(10); PG8_BAR; PG8_MMA(1, 1, At, B1); PG8_BAR;
;         }
	s_waitcnt lgkmcnt(0)
	s_setprio 1
	s_waitcnt lgkmcnt(0)
	v_mfma_f32_16x16x32_bf16 v[124:127], v[222:225], v[188:191], v[124:127]
	v_mfma_f32_16x16x32_bf16 v[120:123], v[230:233], v[188:191], v[120:123]
	v_mfma_f32_16x16x32_bf16 v[116:119], v[222:225], v[196:199], v[116:119]
	v_mfma_f32_16x16x32_bf16 v[112:115], v[230:233], v[196:199], v[112:115]
	v_mfma_f32_16x16x32_bf16 v[108:111], v[222:225], v[204:207], v[108:111]
	v_mfma_f32_16x16x32_bf16 v[104:107], v[230:233], v[204:207], v[104:107]
	v_mfma_f32_16x16x32_bf16 v[100:103], v[222:225], v[212:215], v[100:103]
	v_mfma_f32_16x16x32_bf16 v[96:99], v[230:233], v[212:215], v[96:99]
	v_mfma_f32_16x16x32_bf16 v[124:127], v[226:229], v[192:195], v[124:127]
	v_mfma_f32_16x16x32_bf16 v[120:123], v[234:237], v[192:195], v[120:123]
	v_mfma_f32_16x16x32_bf16 v[116:119], v[226:229], v[200:203], v[116:119]
	v_mfma_f32_16x16x32_bf16 v[112:115], v[234:237], v[200:203], v[112:115]
	v_mfma_f32_16x16x32_bf16 v[108:111], v[226:229], v[208:211], v[108:111]
	v_mfma_f32_16x16x32_bf16 v[104:107], v[234:237], v[208:211], v[104:107]
	v_mfma_f32_16x16x32_bf16 v[100:103], v[226:229], v[216:219], v[100:103]
	s_barrier
	v_mfma_f32_16x16x32_bf16 v[96:99], v[234:237], v[216:219], v[96:99]
	s_setprio 0
	s_mov_b32 m0, s52
	ds_read_b128 v[188:191], v183 offset:49152
	ds_read_b128 v[192:195], v183 offset:50176
	ds_read_b128 v[196:199], v183 offset:51200
	ds_read_b128 v[200:203], v183 offset:52224
	ds_read_b128 v[204:207], v183 offset:53248
	ds_read_b128 v[208:211], v183 offset:54272
	ds_read_b128 v[212:215], v183 offset:55296
	ds_read_b128 v[216:219], v183 offset:56320
	global_load_lds_dwordx4 v128, s[100:101]
	s_mov_b32 m0, s53
	s_nop 0
	global_load_lds_dwordx4 v132, s[100:101]
	s_waitcnt vmcnt(10)
	s_barrier
	s_waitcnt lgkmcnt(0)
	s_setprio 1
	s_waitcnt lgkmcnt(0)
	v_mfma_f32_16x16x32_bf16 v[28:31], v[166:169], v[188:191], v[28:31]
	v_mfma_f32_16x16x32_bf16 v[24:27], v[174:177], v[188:191], v[24:27]
	v_mfma_f32_16x16x32_bf16 v[20:23], v[166:169], v[196:199], v[20:23]
	v_mfma_f32_16x16x32_bf16 v[16:19], v[174:177], v[196:199], v[16:19]
	v_mfma_f32_16x16x32_bf16 v[12:15], v[166:169], v[204:207], v[12:15]
	v_mfma_f32_16x16x32_bf16 v[8:11], v[174:177], v[204:207], v[8:11]
	v_mfma_f32_16x16x32_bf16 v[4:7], v[166:169], v[212:215], v[4:7]
	v_mfma_f32_16x16x32_bf16 v[0:3], v[174:177], v[212:215], v[0:3]
	v_mfma_f32_16x16x32_bf16 v[28:31], v[170:173], v[192:195], v[28:31]
	v_mfma_f32_16x16x32_bf16 v[24:27], v[184:187], v[192:195], v[24:27]
	v_mfma_f32_16x16x32_bf16 v[20:23], v[170:173], v[200:203], v[20:23]
	v_mfma_f32_16x16x32_bf16 v[16:19], v[184:187], v[200:203], v[16:19]
	v_mfma_f32_16x16x32_bf16 v[12:15], v[170:173], v[208:211], v[12:15]
	v_mfma_f32_16x16x32_bf16 v[8:11], v[184:187], v[208:211], v[8:11]
	v_mfma_f32_16x16x32_bf16 v[4:7], v[170:173], v[216:219], v[4:7]
	s_barrier
	v_mfma_f32_16x16x32_bf16 v[0:3], v[184:187], v[216:219], v[0:3]
	s_setprio 0
	s_add_u32 s36, s36, 0x80080
	s_addc_u32 s37, s37, 0
	s_add_i32 s38, s38, s44
	s_mov_b32 m0, s38
	s_nop 0
	global_load_lds_dwordx4 v130, s[36:37]
	s_add_i32 m0, s38, 0x2000
	s_nop 0
	global_load_lds_dwordx4 v134, s[36:37]
	s_waitcnt vmcnt(10)
	s_barrier
	s_setprio 1
	v_mfma_f32_16x16x32_bf16 v[92:95], v[222:225], v[188:191], v[92:95]
	v_mfma_f32_16x16x32_bf16 v[88:91], v[230:233], v[188:191], v[88:91]
	v_mfma_f32_16x16x32_bf16 v[84:87], v[222:225], v[196:199], v[84:87]
	v_mfma_f32_16x16x32_bf16 v[80:83], v[230:233], v[196:199], v[80:83]
	v_mfma_f32_16x16x32_bf16 v[76:79], v[222:225], v[204:207], v[76:79]
	v_mfma_f32_16x16x32_bf16 v[72:75], v[230:233], v[204:207], v[72:75]
	v_mfma_f32_16x16x32_bf16 v[68:71], v[222:225], v[212:215], v[68:71]
	v_mfma_f32_16x16x32_bf16 v[64:67], v[230:233], v[212:215], v[64:67]
	v_mfma_f32_16x16x32_bf16 v[92:95], v[226:229], v[192:195], v[92:95]
	v_mfma_f32_16x16x32_bf16 v[88:91], v[234:237], v[192:195], v[88:91]
	v_mfma_f32_16x16x32_bf16 v[84:87], v[226:229], v[200:203], v[84:87]
	v_mfma_f32_16x16x32_bf16 v[80:83], v[234:237], v[200:203], v[80:83]
	v_mfma_f32_16x16x32_bf16 v[76:79], v[226:229], v[208:211], v[76:79]
	v_mfma_f32_16x16x32_bf16 v[72:75], v[234:237], v[208:211], v[72:75]
	v_mfma_f32_16x16x32_bf16 v[68:71], v[226:229], v[216:219], v[68:71]
	s_barrier
	v_mfma_f32_16x16x32_bf16 v[64:67], v[234:237], v[216:219], v[64:67]
	s_setprio 0
	s_add_i32 s43, s43, 2
	s_add_u32 s4, s4, 0x100
	s_addc_u32 s5, s5, 0
	s_add_u32 s41, s41, 0x100
	s_addc_u32 s42, s42, 0
	s_cmp_gt_u32 s43, 29
	s_cbranch_scc1 .LBB0_136

; #define PG8_STAGE(bufoff, gbase, voff) do { _Pragma("unroll") for (int _i = 0; _i < 2; ++_i) \
;         __builtin_amdgcn_global_load_lds((const unsigned*)((const char*)(gbase) + (voff)[_i]), (LAS unsigned*)(lds + (bufoff) + ldsw + _i * 8192), 16, 0, 0); } while (0)
; #define PG8_WAIT_V(n) asm volatile("s_waitcnt vmcnt(" #n ")" ::: "memory")
; #define PG8_BAR __builtin_amdgcn_s_barrier()
; template <class Epi>
; __device__ __forceinline__ void gemm_phase(ldsp lds, const Gemm g, const StaticOrder& S, const Epi& E) {
;     const int tid = threadIdx.x, wid = __builtin_amdgcn_readfirstlane(tid >> 6), lane = tid & 63, wr = wid >> 2, wc = wid & 3, fr = lane & 15, fq = lane >> 4;
;     const int K = g.K, nt = K / BK;
;     unsigned voffA[2], voffB[2];
; #pragma unroll
;     for (int i = 0; i < 2; ++i) { int R, C; stage_rc(tid * 16 + i * 8192, R, C); const int Rb = (R & ~31) + perm32(R & 31);
;         voffA[i] = (unsigned)(R * K + C) * 2u; voffB[i] = (unsigned)(Rb * K + C) * 2u; }
;     const size_t kstep = (size_t)(BK * 2);
;     const size_t hstep = (size_t)HALF * K * 2;
;     const size_t tstep = 2 * hstep;
;     const unsigned ldsw = (unsigned)wid * 1024u;
;     const int aoff = lds_byte(wr * 64 + fr, fq * 8), boff = lds_byte(wc * 32 + fr, fq * 8);
;     ...
;     Unit cur, nxt; int ui = 0;
;     if (!S.next(0, cur)) return;
;     f32x4 acc[2][2][4][2];
; #pragma unroll
;     for (int a = 0; a < 2; ++a)
; #pragma unroll
;         for (int b = 0; b < 2; ++b)
; #pragma unroll
;             for (int m = 0; m < 4; ++m)
; #pragma unroll
;                 for (int n = 0; n < 2; ++n) acc[a][b][m][n] = (f32x4){0.f, 0.f, 0.f, 0.f};
;     bf16x8 At[4][2], B0[2][2], B1[2][2];
;     unsigned pre[Epi::NPRE > 0 ? Epi::NPRE : 1];
;     const char* cA = (const char*)g.A + (size_t)cur.pm * tstep; const char* cB = (const char*)g.Bt + (size_t)cur.pn * tstep;
;     PG8_STAGE(PG8_SB(0, 0), cB, voffB); PG8_STAGE(PG8_SA(0, 0), cA, voffA); PG8_STAGE(PG8_SB(0, 1), cB + hstep, voffB); PG8_STAGE(PG8_SA(0, 1), cA + hstep, voffA);
;     if (wr == 1) PG8_BAR;
;     PG8_WAIT_V(4); PG8_BAR;
;     PG8_STAGE(PG8_SB(1, 0), cB + kstep, voffB); PG8_STAGE(PG8_SA(1, 0), cA + kstep, voffA); PG8_STAGE(PG8_SB(1, 1), cB + hstep + kstep, voffB);
;     PG8_WAIT_V(6); PG8_BAR;
.LBB0_566:
	s_add_u32 s6, s36, 0x2f340000
	s_addc_u32 s7, s37, 0
	s_lshl_b32 s8, s8, 5
	s_and_b32 s13, s8, 0x60
	s_mov_b64 s[8:9], 0x80
	s_add_i32 m0, s19, 0x18000
	v_lshl_add_u64 v[6:7], v[6:7], 0, s[8:9]
	s_lshl_b32 s12, s3, 13
	s_lshl_b32 s14, s13, 7
	s_waitcnt vmcnt(4)
	s_barrier
	global_load_lds_dwordx4 v[6:7], off
	v_lshl_add_u64 v[4:5], v[4:5], 0, s[8:9]
	s_add_i32 m0, s19, 0x1a000
	s_add_i32 s34, s19, 0x8000
	s_add_i32 s35, s19, 0xa000
	global_load_lds_dwordx4 v[4:5], off
	v_lshl_add_u64 v[2:3], v[2:3], 0, s[8:9]
	s_mov_b32 m0, s34
	s_add_u32 s10, s22, 0x20080
	global_load_lds_dwordx4 v[2:3], off
	v_lshl_add_u64 v[0:1], v[0:1], 0, s[8:9]
	s_mov_b32 m0, s35
	s_addc_u32 s11, s23, 0
	global_load_lds_dwordx4 v[0:1], off
	s_add_i32 m0, s19, 0x1c000
	v_lshl_add_u64 v[0:1], s[10:11], 0, v[178:179]
	global_load_lds_dwordx4 v[0:1], off
	v_lshl_add_u64 v[0:1], s[10:11], 0, v[182:183]
	s_add_i32 m0, s19, 0x1e000
	s_sext_i32_i8 s41, s2
	global_load_lds_dwordx4 v[0:1], off
	v_and_b32_e32 v0, 15, v220
	v_lshlrev_b32_e32 v1, 1, v11
	v_lshlrev_b32_e32 v2, 2, v220
	v_lshlrev_b32_e32 v3, 6, v220
	s_movk_i32 s2, 0x3c0
	v_lshl_or_b32 v216, s3, 6, v0
	v_lshl_or_b32 v0, v0, 6, v1
	v_and_b32_e32 v2, 32, v2
	v_and_or_b32 v1, v3, s2, v1
	v_bitop3_b32 v217, s14, v1, v2 bitop3:0xf6
	v_add_u32_e32 v247, 0x10000, v217
	v_lshlrev_b32_e32 v1, 7, v220
	v_bitop3_b32 v0, v0, s12, v2 bitop3:0xde
	v_and_b32_e32 v1, 0x1c000, v1
	v_lshlrev_b32_e32 v2, 10, v10
	v_or3_b32 v1, v8, v1, v2
	v_add_u32_e32 v184, v1, v9
	v_lshlrev_b32_e32 v1, 3, v12
	s_waitcnt vmcnt(6)
	v_and_b32_e32 v1, 0x3c000, v1
	v_or3_b32 v1, v8, v1, v2
	s_add_i32 s38, 0, 0x10000
	s_add_i32 s39, 0, 0x14000
	s_ashr_i32 s36, s62, 31
	s_mov_b32 s37, s62
	v_or_b32_e32 v218, s13, v11
	v_mov_b32_e32 v185, v179
	v_add_u32_e32 v186, v1, v9
	v_mov_b32_e32 v187, v179
	v_mov_b64_e32 v[188:189], 0x100
	v_mov_b64_e32 v[190:191], 0xff
	v_add_u32_e32 v219, s38, v217
	v_add_u32_e32 v221, 0, v0
	v_add_u32_e32 v222, s39, v217
	s_movk_i32 s40, 0xc00
	s_barrier

; #define PG8_STAGE(bufoff, gbase, voff) do { _Pragma("unroll") for (int _i = 0; _i < 2; ++_i) \
;         __builtin_amdgcn_global_load_lds((const unsigned*)((const char*)(gbase) + (voff)[_i]), (LAS unsigned*)(lds + (bufoff) + ldsw + _i * 8192), 16, 0, 0); } while (0)
; #define PG8_LDA(dst, b, h) do { _Pragma("unroll") for (int m = 0; m < 4; ++m) _Pragma("unroll") for (int k = 0; k < 2; ++k) dst[m][k] = *(const LAS bf16x8*)(lds + PG8_SA(b, h) + aoff + m * 2048 + k * 1024); } while (0)
; #define PG8_LDB(dst, b, h) do { _Pragma("unroll") for (int n = 0; n < 2; ++n) _Pragma("unroll") for (int k = 0; k < 2; ++k) dst[n][k] = *(const LAS bf16x8*)(lds + PG8_SB(b, h) + boff + n * 2048 + k * 1024); } while (0)
; #define PG8_MMA(ai, bj, At, Bt) do { __builtin_amdgcn_s_setprio(1); _Pragma("unroll") for (int m = 0; m < 4; ++m) _Pragma("unroll") for (int n = 0; n < 2; ++n) _Pragma("unroll") for (int k = 0; k < 2; ++k) \
;         acc[ai][bj][m][n] = __builtin_amdgcn_mfma_f32_16x16x32_bf16(Bt[n][k], At[m][k], acc[ai][bj][m][n], 0, 0, 0); __builtin_amdgcn_s_setprio(0); } while (0)
; #define PG8_BAR __builtin_amdgcn_s_barrier()
; template <class Epi>
; __device__ __forceinline__ void gemm_phase(ldsp lds, const Gemm g, const StaticOrder& S, const Epi& E) {
;     ...
;         for (int t = 0; t < nt; t += 2) {
;             const bool last = (t == nt - 2);
;             const char* a1 = cA + (size_t)(t + 1) * kstep;
;             const char* a2 = last ? nA : cA + (size_t)(t + 2) * kstep; const char* b2 = last ? nB : cB + (size_t)(t + 2) * kstep;
;             const char* a3 = a2 + kstep; const char* b3 = b2 + kstep;
;             if constexpr (Epi::NPRE > 0) { if (last) E.pre(pre, cur, wr, fr); }
;             if constexpr (Epi::MID_T > 0) { if (t == Epi::MID_T) E.mid(acc, cur, wr, wc, fr, fq); }
;             PG8_LDB(B0, 0, 0); PG8_SCHED; PG8_LDA(At, 0, 0); PG8_STAGE(PG8_SA(1, 1), a1 + hstep, voffA);
;             PG8_WAIT_L(8); PG8_WAIT_V(10); PG8_BAR; PG8_WAIT_L(0); PG8_MMA(0, 0, At, B0); PG8_BAR; PG8_SCHED;
;             PG8_LDB(B1, 0, 1); PG8_STAGE(PG8_SB(0, 0), b2, voffB);
;             PG8_WAIT_V(10); PG8_BAR; PG8_WAIT_L(0); PG8_MMA(0, 1, At, B1); PG8_BAR;
;             PG8_LDA(At, 0, 1); PG8_STAGE(PG8_SA(0, 0), a2, voffA);
;             PG8_WAIT_V(10); PG8_BAR; PG8_WAIT_L(0); PG8_MMA(1, 0, At, B0); PG8_BAR; PG8_SCHED;
;             PG8_STAGE(PG8_SB(0, 1), b2 + hstep, voffB);
.LBB0_574:
	ds_read_b128 v[128:131], v219
	ds_read_b128 v[132:135], v219 offset:1024
	ds_read_b128 v[136:139], v219 offset:2048
	ds_read_b128 v[140:143], v219 offset:3072
	s_add_u32 s22, s20, 0xfffe0080
	s_addc_u32 s23, s21, -1
	s_cmp_eq_u32 s46, 4
	s_cselect_b32 s25, s13, s23
	s_cselect_b32 s24, s42, s22
	s_cselect_b32 s23, s11, s45
	s_cselect_b32 s22, s43, s44
	s_add_i32 m0, s19, 0xc000
	ds_read_b128 v[144:147], v221
	ds_read_b128 v[148:151], v221 offset:1024
	ds_read_b128 v[152:155], v221 offset:2048
	ds_read_b128 v[156:159], v221 offset:3072
	ds_read_b128 v[160:163], v221 offset:4096
	ds_read_b128 v[164:167], v221 offset:5120
	ds_read_b128 v[168:171], v221 offset:6144
	ds_read_b128 v[172:175], v221 offset:7168
	global_load_lds_dwordx4 v184, s[20:21]
	s_add_i32 m0, s19, 0xe000
	s_nop 0
	global_load_lds_dwordx4 v186, s[20:21]
	s_waitcnt lgkmcnt(8)
	s_waitcnt vmcnt(10)
	s_barrier
	s_waitcnt lgkmcnt(0)
	s_setprio 1
	s_waitcnt lgkmcnt(0)
	v_mfma_f32_16x16x32_bf16 v[124:127], v[128:131], v[144:147], v[124:127]
	v_mfma_f32_16x16x32_bf16 v[120:123], v[136:139], v[144:147], v[120:123]
	v_mfma_f32_16x16x32_bf16 v[116:119], v[128:131], v[152:155], v[116:119]
	v_mfma_f32_16x16x32_bf16 v[112:115], v[136:139], v[152:155], v[112:115]
	v_mfma_f32_16x16x32_bf16 v[108:111], v[128:131], v[160:163], v[108:111]
	v_mfma_f32_16x16x32_bf16 v[104:107], v[136:139], v[160:163], v[104:107]
	v_mfma_f32_16x16x32_bf16 v[100:103], v[128:131], v[168:171], v[100:103]
	v_mfma_f32_16x16x32_bf16 v[96:99], v[136:139], v[168:171], v[96:99]
	v_mfma_f32_16x16x32_bf16 v[124:127], v[132:135], v[148:151], v[124:127]
	v_mfma_f32_16x16x32_bf16 v[120:123], v[140:143], v[148:151], v[120:123]
	v_mfma_f32_16x16x32_bf16 v[116:119], v[132:135], v[156:159], v[116:119]
	v_mfma_f32_16x16x32_bf16 v[112:115], v[140:143], v[156:159], v[112:115]
	v_mfma_f32_16x16x32_bf16 v[108:111], v[132:135], v[164:167], v[108:111]
	v_mfma_f32_16x16x32_bf16 v[104:107], v[140:143], v[164:167], v[104:107]
	v_mfma_f32_16x16x32_bf16 v[100:103], v[132:135], v[172:175], v[100:103]
	s_barrier
	v_mfma_f32_16x16x32_bf16 v[96:99], v[140:143], v[172:175], v[96:99]
	s_setprio 0
	s_add_i32 s47, s38, s28
	s_add_u32 s98, s22, 0x80
	s_addc_u32 s99, s23, 0
	s_mov_b32 m0, s47
	ds_read_b128 v[192:195], v222
	ds_read_b128 v[196:199], v222 offset:1024
	ds_read_b128 v[200:203], v222 offset:2048
	ds_read_b128 v[204:207], v222 offset:3072
	global_load_lds_dwordx4 v178, s[22:23]
	s_add_i32 m0, s47, 0x2000
	s_nop 0
	global_load_lds_dwordx4 v182, s[22:23]
	s_waitcnt vmcnt(10)
	s_barrier
	s_waitcnt lgkmcnt(0)
	s_setprio 1
	s_waitcnt lgkmcnt(0)
	v_mfma_f32_16x16x32_bf16 v[60:63], v[192:195], v[144:147], v[60:63]
	v_mfma_f32_16x16x32_bf16 v[56:59], v[200:203], v[144:147], v[56:59]
	v_mfma_f32_16x16x32_bf16 v[52:55], v[192:195], v[152:155], v[52:55]
	v_mfma_f32_16x16x32_bf16 v[48:51], v[200:203], v[152:155], v[48:51]
	v_mfma_f32_16x16x32_bf16 v[44:47], v[192:195], v[160:163], v[44:47]
	v_mfma_f32_16x16x32_bf16 v[40:43], v[200:203], v[160:163], v[40:43]
	v_mfma_f32_16x16x32_bf16 v[36:39], v[192:195], v[168:171], v[36:39]
	v_mfma_f32_16x16x32_bf16 v[32:35], v[200:203], v[168:171], v[32:35]
	v_mfma_f32_16x16x32_bf16 v[60:63], v[196:199], v[148:151], v[60:63]
	v_mfma_f32_16x16x32_bf16 v[56:59], v[204:207], v[148:151], v[56:59]
	v_mfma_f32_16x16x32_bf16 v[52:55], v[196:199], v[156:159], v[52:55]
	v_mfma_f32_16x16x32_bf16 v[48:51], v[204:207], v[156:159], v[48:51]
	v_mfma_f32_16x16x32_bf16 v[44:47], v[196:199], v[164:167], v[44:47]
	v_mfma_f32_16x16x32_bf16 v[40:43], v[204:207], v[164:167], v[40:43]
	v_mfma_f32_16x16x32_bf16 v[36:39], v[196:199], v[172:175], v[36:39]
	s_barrier
	v_mfma_f32_16x16x32_bf16 v[32:35], v[204:207], v[172:175], v[32:35]
	s_setprio 0
	s_mov_b32 m0, s19
	s_add_u32 s100, s24, 0x80
	s_addc_u32 s101, s25, 0
	ds_read_b128 v[144:147], v221 offset:16384
	ds_read_b128 v[148:151], v221 offset:17408
	ds_read_b128 v[152:155], v221 offset:18432
	ds_read_b128 v[156:159], v221 offset:19456
	ds_read_b128 v[160:163], v221 offset:20480
	ds_read_b128 v[164:167], v221 offset:21504
	ds_read_b128 v[168:171], v221 offset:22528
	ds_read_b128 v[172:175], v221 offset:23552
	global_load_lds_dwordx4 v176, s[24:25]
	s_mov_b32 m0, s29
	s_nop 0
	global_load_lds_dwordx4 v180, s[24:25]
	s_waitcnt vmcnt(10)
	s_barrier
	s_waitcnt lgkmcnt(0)
	s_setprio 1
	s_waitcnt lgkmcnt(0)
	v_mfma_f32_16x16x32_bf16 v[92:95], v[128:131], v[144:147], v[92:95]
	v_mfma_f32_16x16x32_bf16 v[88:91], v[136:139], v[144:147], v[88:91]
	v_mfma_f32_16x16x32_bf16 v[84:87], v[128:131], v[152:155], v[84:87]
	v_mfma_f32_16x16x32_bf16 v[80:83], v[136:139], v[152:155], v[80:83]
	v_mfma_f32_16x16x32_bf16 v[76:79], v[128:131], v[160:163], v[76:79]
	v_mfma_f32_16x16x32_bf16 v[72:75], v[136:139], v[160:163], v[72:75]
	v_mfma_f32_16x16x32_bf16 v[68:71], v[128:131], v[168:171], v[68:71]
	v_mfma_f32_16x16x32_bf16 v[64:67], v[136:139], v[168:171], v[64:67]
	v_mfma_f32_16x16x32_bf16 v[92:95], v[132:135], v[148:151], v[92:95]
	v_mfma_f32_16x16x32_bf16 v[88:91], v[140:143], v[148:151], v[88:91]
	v_mfma_f32_16x16x32_bf16 v[84:87], v[132:135], v[156:159], v[84:87]
	v_mfma_f32_16x16x32_bf16 v[80:83], v[140:143], v[156:159], v[80:83]
	v_mfma_f32_16x16x32_bf16 v[76:79], v[132:135], v[164:167], v[76:79]
	v_mfma_f32_16x16x32_bf16 v[72:75], v[140:143], v[164:167], v[72:75]
	v_mfma_f32_16x16x32_bf16 v[68:71], v[132:135], v[172:175], v[68:71]
	s_barrier
	v_mfma_f32_16x16x32_bf16 v[64:67], v[140:143], v[172:175], v[64:67]
	s_setprio 0
	s_add_u32 s50, s22, 0x20000
	s_addc_u32 s51, s23, 0
	s_add_i32 s47, s39, s28
	s_mov_b32 m0, s47
	s_nop 0
	global_load_lds_dwordx4 v178, s[50:51]
	s_add_i32 m0, s47, 0x2000
	s_nop 0
	global_load_lds_dwordx4 v182, s[50:51]
	s_waitcnt vmcnt(10)
	s_barrier
; #define PG8_STAGE(bufoff, gbase, voff) do { _Pragma("unroll") for (int _i = 0; _i < 2; ++_i) \
;         __builtin_amdgcn_global_load_lds((const unsigned*)((const char*)(gbase) + (voff)[_i]), (LAS unsigned*)(lds + (bufoff) + ldsw + _i * 8192), 16, 0, 0); } while (0)
; #define PG8_LDA(dst, b, h) do { _Pragma("unroll") for (int m = 0; m < 4; ++m) _Pragma("unroll") for (int k = 0; k < 2; ++k) dst[m][k] = *(const LAS bf16x8*)(lds + PG8_SA(b, h) + aoff + m * 2048 + k * 1024); } while (0)
; #define PG8_LDB(dst, b, h) do { _Pragma("unroll") for (int n = 0; n < 2; ++n) _Pragma("unroll") for (int k = 0; k < 2; ++k) dst[n][k] = *(const LAS bf16x8*)(lds + PG8_SB(b, h) + boff + n * 2048 + k * 1024); } while (0)
; #define PG8_MMA(ai, bj, At, Bt) do { __builtin_amdgcn_s_setprio(1); _Pragma("unroll") for (int m = 0; m < 4; ++m) _Pragma("unroll") for (int n = 0; n < 2; ++n) _Pragma("unroll") for (int k = 0; k < 2; ++k) \
;         acc[ai][bj][m][n] = __builtin_amdgcn_mfma_f32_16x16x32_bf16(Bt[n][k], At[m][k], acc[ai][bj][m][n], 0, 0, 0); __builtin_amdgcn_s_setprio(0); } while (0)
; #define PG8_WAIT_V(n) asm volatile("s_waitcnt vmcnt(" #n ")" ::: "memory")
; #define PG8_WAIT_L(n) asm volatile("s_waitcnt lgkmcnt(" #n ")" ::: "memory")
; #define PG8_BAR __builtin_amdgcn_s_barrier()
; #define PG8_SCHED __builtin_amdgcn_sched_barrier(0)
; template <class Epi>
; __device__ __forceinline__ void gemm_phase(ldsp lds, const Gemm g, const StaticOrder& S, const Epi& E) {
;     ...
;             PG8_WAIT_V(10); PG8_BAR; PG8_MMA(1, 1, At, B1); PG8_BAR;
;             PG8_LDB(B0, 1, 0); PG8_SCHED; PG8_LDA(At, 1, 0); PG8_STAGE(PG8_SA(0, 1), a2 + hstep, voffA);
;             PG8_WAIT_L(8); PG8_WAIT_V(10); PG8_BAR; PG8_WAIT_L(0); PG8_MMA(0, 0, At, B0); PG8_BAR; PG8_SCHED;
;             PG8_LDB(B1, 1, 1); PG8_STAGE(PG8_SB(1, 0), b3, voffB);
;             PG8_WAIT_V(10); PG8_BAR; PG8_WAIT_L(0); PG8_MMA(0, 1, At, B1); PG8_BAR;
;             PG8_LDA(At, 1, 1); PG8_STAGE(PG8_SA(1, 0), a3, voffA);
	s_setprio 1
	v_mfma_f32_16x16x32_bf16 v[28:31], v[192:195], v[144:147], v[28:31]
	v_mfma_f32_16x16x32_bf16 v[24:27], v[200:203], v[144:147], v[24:27]
	v_mfma_f32_16x16x32_bf16 v[20:23], v[192:195], v[152:155], v[20:23]
	v_mfma_f32_16x16x32_bf16 v[16:19], v[200:203], v[152:155], v[16:19]
	v_mfma_f32_16x16x32_bf16 v[12:15], v[192:195], v[160:163], v[12:15]
	v_mfma_f32_16x16x32_bf16 v[8:11], v[200:203], v[160:163], v[8:11]
	v_mfma_f32_16x16x32_bf16 v[4:7], v[192:195], v[168:171], v[4:7]
	v_mfma_f32_16x16x32_bf16 v[0:3], v[200:203], v[168:171], v[0:3]
	v_mfma_f32_16x16x32_bf16 v[28:31], v[196:199], v[148:151], v[28:31]
	v_mfma_f32_16x16x32_bf16 v[24:27], v[204:207], v[148:151], v[24:27]
	v_mfma_f32_16x16x32_bf16 v[20:23], v[196:199], v[156:159], v[20:23]
	v_mfma_f32_16x16x32_bf16 v[16:19], v[204:207], v[156:159], v[16:19]
	v_mfma_f32_16x16x32_bf16 v[12:15], v[196:199], v[164:167], v[12:15]
	v_mfma_f32_16x16x32_bf16 v[8:11], v[204:207], v[164:167], v[8:11]
	v_mfma_f32_16x16x32_bf16 v[4:7], v[196:199], v[172:175], v[4:7]
	s_barrier
	v_mfma_f32_16x16x32_bf16 v[0:3], v[204:207], v[172:175], v[0:3]
	s_setprio 0
	s_add_i32 s47, 0, 0x18000
	ds_read_b128 v[128:131], v247 offset:32768
	ds_read_b128 v[132:135], v247 offset:33792
	ds_read_b128 v[136:139], v247 offset:34816
	ds_read_b128 v[140:143], v247 offset:35840
	s_add_u32 s24, s24, 0x20000
	s_addc_u32 s25, s25, 0
	s_mov_b32 m0, s30
	ds_read_b128 v[144:147], v221 offset:32768
	ds_read_b128 v[148:151], v221 offset:33792
	ds_read_b128 v[152:155], v221 offset:34816
	ds_read_b128 v[156:159], v221 offset:35840
	ds_read_b128 v[160:163], v221 offset:36864
	ds_read_b128 v[164:167], v221 offset:37888
	ds_read_b128 v[168:171], v221 offset:38912
	ds_read_b128 v[172:175], v221 offset:39936
	global_load_lds_dwordx4 v176, s[24:25]
	s_mov_b32 m0, s31
	s_nop 0
	global_load_lds_dwordx4 v180, s[24:25]
	s_waitcnt lgkmcnt(8)
	s_waitcnt vmcnt(10)
	s_barrier
	s_waitcnt lgkmcnt(0)
	s_setprio 1
	s_waitcnt lgkmcnt(0)
	v_mfma_f32_16x16x32_bf16 v[124:127], v[128:131], v[144:147], v[124:127]
	v_mfma_f32_16x16x32_bf16 v[120:123], v[136:139], v[144:147], v[120:123]
	v_mfma_f32_16x16x32_bf16 v[116:119], v[128:131], v[152:155], v[116:119]
	v_mfma_f32_16x16x32_bf16 v[112:115], v[136:139], v[152:155], v[112:115]
	v_mfma_f32_16x16x32_bf16 v[108:111], v[128:131], v[160:163], v[108:111]
	v_mfma_f32_16x16x32_bf16 v[104:107], v[136:139], v[160:163], v[104:107]
	v_mfma_f32_16x16x32_bf16 v[100:103], v[128:131], v[168:171], v[100:103]
	v_mfma_f32_16x16x32_bf16 v[96:99], v[136:139], v[168:171], v[96:99]
	v_mfma_f32_16x16x32_bf16 v[124:127], v[132:135], v[148:151], v[124:127]
	v_mfma_f32_16x16x32_bf16 v[120:123], v[140:143], v[148:151], v[120:123]
	v_mfma_f32_16x16x32_bf16 v[116:119], v[132:135], v[156:159], v[116:119]
	v_mfma_f32_16x16x32_bf16 v[112:115], v[140:143], v[156:159], v[112:115]
	v_mfma_f32_16x16x32_bf16 v[108:111], v[132:135], v[164:167], v[108:111]
	v_mfma_f32_16x16x32_bf16 v[104:107], v[140:143], v[164:167], v[104:107]
	v_mfma_f32_16x16x32_bf16 v[100:103], v[132:135], v[172:175], v[100:103]
	s_barrier
	v_mfma_f32_16x16x32_bf16 v[96:99], v[140:143], v[172:175], v[96:99]
	s_setprio 0
	s_add_i32 s24, 0, 0x1c000
	s_add_i32 s25, s47, s28
	s_mov_b32 m0, s25
	ds_read_b128 v[192:195], v247 offset:49152
	ds_read_b128 v[196:199], v247 offset:50176
	ds_read_b128 v[200:203], v247 offset:51200
	ds_read_b128 v[204:207], v247 offset:52224
	global_load_lds_dwordx4 v178, s[98:99]
	s_add_i32 m0, s25, 0x2000
	s_nop 0
	global_load_lds_dwordx4 v182, s[98:99]
	s_waitcnt vmcnt(10)
	s_barrier
	s_waitcnt lgkmcnt(0)
	s_setprio 1
	s_waitcnt lgkmcnt(0)
	v_mfma_f32_16x16x32_bf16 v[60:63], v[192:195], v[144:147], v[60:63]
	v_mfma_f32_16x16x32_bf16 v[56:59], v[200:203], v[144:147], v[56:59]
	v_mfma_f32_16x16x32_bf16 v[52:55], v[192:195], v[152:155], v[52:55]
	v_mfma_f32_16x16x32_bf16 v[48:51], v[200:203], v[152:155], v[48:51]
	v_mfma_f32_16x16x32_bf16 v[44:47], v[192:195], v[160:163], v[44:47]
	v_mfma_f32_16x16x32_bf16 v[40:43], v[200:203], v[160:163], v[40:43]
	v_mfma_f32_16x16x32_bf16 v[36:39], v[192:195], v[168:171], v[36:39]
	v_mfma_f32_16x16x32_bf16 v[32:35], v[200:203], v[168:171], v[32:35]
	v_mfma_f32_16x16x32_bf16 v[60:63], v[196:199], v[148:151], v[60:63]
	v_mfma_f32_16x16x32_bf16 v[56:59], v[204:207], v[148:151], v[56:59]
	v_mfma_f32_16x16x32_bf16 v[52:55], v[196:199], v[156:159], v[52:55]
	v_mfma_f32_16x16x32_bf16 v[48:51], v[204:207], v[156:159], v[48:51]
	v_mfma_f32_16x16x32_bf16 v[44:47], v[196:199], v[164:167], v[44:47]
	v_mfma_f32_16x16x32_bf16 v[40:43], v[204:207], v[164:167], v[40:43]
	v_mfma_f32_16x16x32_bf16 v[36:39], v[196:199], v[172:175], v[36:39]
	s_barrier
	v_mfma_f32_16x16x32_bf16 v[32:35], v[204:207], v[172:175], v[32:35]
	s_setprio 0
	s_mov_b32 m0, s34
	ds_read_b128 v[144:147], v221 offset:49152
	ds_read_b128 v[148:151], v221 offset:50176
	ds_read_b128 v[152:155], v221 offset:51200
	ds_read_b128 v[156:159], v221 offset:52224
	ds_read_b128 v[160:163], v221 offset:53248
	ds_read_b128 v[164:167], v221 offset:54272
	ds_read_b128 v[168:171], v221 offset:55296
	ds_read_b128 v[172:175], v221 offset:56320
	global_load_lds_dwordx4 v176, s[100:101]
	s_mov_b32 m0, s35
	s_nop 0
	global_load_lds_dwordx4 v180, s[100:101]
	s_waitcnt vmcnt(10)
	s_barrier
; #define PG8_STAGE(bufoff, gbase, voff) do { _Pragma("unroll") for (int _i = 0; _i < 2; ++_i) \
;         __builtin_amdgcn_global_load_lds((const unsigned*)((const char*)(gbase) + (voff)[_i]), (LAS unsigned*)(lds + (bufoff) + ldsw + _i * 8192), 16, 0, 0); } while (0)
; #define PG8_MMA(ai, bj, At, Bt) do { __builtin_amdgcn_s_setprio(1); _Pragma("unroll") for (int m = 0; m < 4; ++m) _Pragma("unroll") for (int n = 0; n < 2; ++n) _Pragma("unroll") for (int k = 0; k < 2; ++k) \
;         acc[ai][bj][m][n] = __builtin_amdgcn_mfma_f32_16x16x32_bf16(Bt[n][k], At[m][k], acc[ai][bj][m][n], 0, 0, 0); __builtin_amdgcn_s_setprio(0); } while (0)
; #define PG8_WAIT_V(n) asm volatile("s_waitcnt vmcnt(" #n ")" ::: "memory")
; #define PG8_WAIT_L(n) asm volatile("s_waitcnt lgkmcnt(" #n ")" ::: "memory")
; #define PG8_BAR __builtin_amdgcn_s_barrier()
; #define PG8_SCHED __builtin_amdgcn_sched_barrier(0)
; template <class Epi>
; __device__ __forceinline__ void gemm_phase(ldsp lds, const Gemm g, const StaticOrder& S, const Epi& E) {
;     ...
;             PG8_WAIT_V(10); PG8_BAR; PG8_WAIT_L(0); PG8_MMA(1, 0, At, B0); PG8_BAR; PG8_SCHED;
;             PG8_STAGE(PG8_SB(1, 1), b3 + hstep, voffB);
;             PG8_WAIT_V(10); PG8_BAR; PG8_MMA(1, 1, At, B1); PG8_BAR;
;         }
;     __device__ __forceinline__ void operator()(EPI_ARGS) const {
;         const int row0 = u.pm * 256 + wr * 64 + fr, col0 = u.pn * 256 + wc * 32 + 8 * fq;
; #pragma unroll
;         for (int bj = 0; bj < 2; ++bj) { const f32x4 b0 = *(const f32x4*)(bias + col0 + bj * 128), b1 = *(const f32x4*)(bias + col0 + bj * 128 + 4);
;             u32x4 hw[2][4];
; #pragma unroll
;             for (int ai = 0; ai < 2; ++ai)
; #pragma unroll
;                 for (int m = 0; m < 4; ++m) hw[ai][m] = *(const u32x4*)(H + (size_t)(row0 + ai * 128 + m * 16) * 512 + col0 + bj * 128);
	s_waitcnt lgkmcnt(0)
	s_setprio 1
	s_waitcnt lgkmcnt(0)
	v_mfma_f32_16x16x32_bf16 v[92:95], v[128:131], v[144:147], v[92:95]
	v_mfma_f32_16x16x32_bf16 v[88:91], v[136:139], v[144:147], v[88:91]
	v_mfma_f32_16x16x32_bf16 v[84:87], v[128:131], v[152:155], v[84:87]
	v_mfma_f32_16x16x32_bf16 v[80:83], v[136:139], v[152:155], v[80:83]
	v_mfma_f32_16x16x32_bf16 v[76:79], v[128:131], v[160:163], v[76:79]
	v_mfma_f32_16x16x32_bf16 v[72:75], v[136:139], v[160:163], v[72:75]
	v_mfma_f32_16x16x32_bf16 v[68:71], v[128:131], v[168:171], v[68:71]
	v_mfma_f32_16x16x32_bf16 v[64:67], v[136:139], v[168:171], v[64:67]
	v_mfma_f32_16x16x32_bf16 v[92:95], v[132:135], v[148:151], v[92:95]
	v_mfma_f32_16x16x32_bf16 v[88:91], v[140:143], v[148:151], v[88:91]
	v_mfma_f32_16x16x32_bf16 v[84:87], v[132:135], v[156:159], v[84:87]
	v_mfma_f32_16x16x32_bf16 v[80:83], v[140:143], v[156:159], v[80:83]
	v_mfma_f32_16x16x32_bf16 v[76:79], v[132:135], v[164:167], v[76:79]
	v_mfma_f32_16x16x32_bf16 v[72:75], v[140:143], v[164:167], v[72:75]
	v_mfma_f32_16x16x32_bf16 v[68:71], v[132:135], v[172:175], v[68:71]
	s_barrier
	v_mfma_f32_16x16x32_bf16 v[64:67], v[140:143], v[172:175], v[64:67]
	s_setprio 0
	s_add_u32 s22, s22, 0x20080
	s_addc_u32 s23, s23, 0
	s_add_i32 s24, s24, s28
	s_mov_b32 m0, s24
	s_nop 0
	global_load_lds_dwordx4 v178, s[22:23]
	s_add_i32 m0, s24, 0x2000
	s_nop 0
	global_load_lds_dwordx4 v182, s[22:23]
	s_waitcnt vmcnt(10)
	s_barrier
	s_setprio 1
	v_mfma_f32_16x16x32_bf16 v[28:31], v[192:195], v[144:147], v[28:31]
	v_mfma_f32_16x16x32_bf16 v[24:27], v[200:203], v[144:147], v[24:27]
	v_mfma_f32_16x16x32_bf16 v[20:23], v[192:195], v[152:155], v[20:23]
	v_mfma_f32_16x16x32_bf16 v[16:19], v[200:203], v[152:155], v[16:19]
	v_mfma_f32_16x16x32_bf16 v[12:15], v[192:195], v[160:163], v[12:15]
	v_mfma_f32_16x16x32_bf16 v[8:11], v[200:203], v[160:163], v[8:11]
	v_mfma_f32_16x16x32_bf16 v[4:7], v[192:195], v[168:171], v[4:7]
	v_mfma_f32_16x16x32_bf16 v[0:3], v[200:203], v[168:171], v[0:3]
	v_mfma_f32_16x16x32_bf16 v[28:31], v[196:199], v[148:151], v[28:31]
	v_mfma_f32_16x16x32_bf16 v[24:27], v[204:207], v[148:151], v[24:27]
	v_mfma_f32_16x16x32_bf16 v[20:23], v[196:199], v[156:159], v[20:23]
	v_mfma_f32_16x16x32_bf16 v[16:19], v[204:207], v[156:159], v[16:19]
	v_mfma_f32_16x16x32_bf16 v[12:15], v[196:199], v[164:167], v[12:15]
	v_mfma_f32_16x16x32_bf16 v[8:11], v[204:207], v[164:167], v[8:11]
	v_mfma_f32_16x16x32_bf16 v[4:7], v[196:199], v[172:175], v[4:7]
	s_barrier
	v_mfma_f32_16x16x32_bf16 v[0:3], v[204:207], v[172:175], v[0:3]
	s_setprio 0
	s_add_i32 s46, s46, 2
	s_add_u32 s20, s20, 0x100
	s_addc_u32 s21, s21, 0
	s_add_u32 s44, s44, 0x100
	s_addc_u32 s45, s45, 0
	s_cmp_gt_u32 s46, 5
	s_cbranch_scc0 .LBB0_574
	v_lshl_or_b32 v136, s41, 8, v218
	v_readlane_b32 s72, v246, 6
	v_ashrrev_i32_e32 v137, 31, v136
	v_readlane_b32 s86, v246, 20
	v_readlane_b32 s87, v246, 21
	v_lshl_add_u32 v140, s18, 8, v216
	v_ashrrev_i32_e32 v141, 31, v140
	v_lshl_add_u64 v[192:193], v[136:137], 2, s[86:87]
	v_lshlrev_b64 v[194:195], 1, v[136:137]
	global_load_dwordx4 v[132:135], v[192:193], off
	global_load_dwordx4 v[128:131], v[192:193], off offset:16
	v_lshlrev_b64 v[136:137], 10, v[140:141]
	v_lshl_add_u64 v[150:151], s[4:5], 0, v[194:195]
	v_lshl_add_u64 v[142:143], v[150:151], 0, v[136:137]
	global_load_dwordx4 v[136:139], v[142:143], off
	v_or_b32_e32 v210, 16, v140
	v_or_b32_e32 v206, 48, v140
	v_add_u32_e32 v204, 0x80, v140
	v_add_u32_e32 v198, 0xb0, v140
	v_ashrrev_i32_e32 v211, 31, v210
	v_ashrrev_i32_e32 v207, 31, v206
	v_ashrrev_i32_e32 v205, 31, v204
	v_ashrrev_i32_e32 v199, 31, v198
	v_lshlrev_b64 v[144:145], 10, v[210:211]
	v_lshlrev_b64 v[152:153], 10, v[206:207]
	v_lshlrev_b64 v[154:155], 10, v[204:205]
	v_lshlrev_b64 v[160:161], 10, v[198:199]
	v_lshl_add_u64 v[148:149], v[150:151], 0, v[144:145]
	v_lshl_add_u64 v[144:145], v[150:151], 0, v[152:153]
	v_lshl_add_u64 v[168:169], v[150:151], 0, v[154:155]
	v_lshl_add_u64 v[212:213], v[150:151], 0, v[160:161]
	global_load_dwordx4 v[152:155], v[148:149], off
	global_load_dwordx4 v[160:163], v[142:143], off offset:256
	v_or_b32_e32 v208, 32, v140
	v_add_u32_e32 v202, 0x90, v140
	v_add_u32_e32 v200, 0xa0, v140
	v_ashrrev_i32_e32 v209, 31, v208
	v_ashrrev_i32_e32 v203, 31, v202
	v_ashrrev_i32_e32 v201, 31, v200
	v_lshlrev_b64 v[146:147], 10, v[208:209]
	v_lshlrev_b64 v[156:157], 10, v[202:203]
	v_lshlrev_b64 v[158:159], 10, v[200:201]
	v_lshl_add_u64 v[146:147], v[150:151], 0, v[146:147]
	v_lshl_add_u64 v[166:167], v[150:151], 0, v[156:157]
	v_lshl_add_u64 v[164:165], v[150:151], 0, v[158:159]
	v_mov_b64_e32 v[196:197], s[6:7]
	s_and_b64 vcc, exec, s[2:3]
	s_mov_b32 s18, s12
	s_mov_b32 s41, s10
	s_mov_b64 s[22:23], s[16:17]
	v_readlane_b32 s73, v246, 7
	v_readlane_b32 s74, v246, 8
	v_readlane_b32 s75, v246, 9
	v_readlane_b32 s76, v246, 10
	v_readlane_b32 s77, v246, 11
	v_readlane_b32 s78, v246, 12
	v_readlane_b32 s79, v246, 13
	v_readlane_b32 s80, v246, 14
	v_readlane_b32 s81, v246, 15
	v_readlane_b32 s82, v246, 16
	v_readlane_b32 s83, v246, 17
	v_readlane_b32 s84, v246, 18
	v_readlane_b32 s85, v246, 19
	s_waitcnt vmcnt(0)
; __device__ __forceinline__ float sigm(float x) { return __builtin_amdgcn_rcpf(1.0f + __builtin_amdgcn_exp2f(-1.4426950408889634f * x)); }
;     __device__ __forceinline__ void operator()(EPI_ARGS) const {
;     ...
;         for (int bj = 0; bj < 2; ++bj) { const f32x4 b0 = *(const f32x4*)(bias + col0 + bj * 128), b1 = *(const f32x4*)(bias + col0 + bj * 128 + 4);
;             u32x4 hw[2][4];
; #pragma unroll
;             for (int ai = 0; ai < 2; ++ai)
; #pragma unroll
;                 for (int m = 0; m < 4; ++m) hw[ai][m] = *(const u32x4*)(H + (size_t)(row0 + ai * 128 + m * 16) * 512 + col0 + bj * 128);
; #pragma unroll
;             for (int ai = 0; ai < 2; ++ai)
; #pragma unroll
;                 for (int m = 0; m < 4; ++m) { const size_t off = (size_t)(row0 + ai * 128 + m * 16) * 512 + col0 + bj * 128;
;                     f32x4 h0, h1; unpack8(hw[ai][m], h0, h1);
;                     f32x4 v0 = acc[ai][bj][m][0] + b0, v1 = acc[ai][bj][m][1] + b1;
; #pragma unroll
;                     for (int j = 0; j < 4; ++j) { v0[j] = h0[j] * sigm(v0[j]); v1[j] = h1[j] * sigm(v1[j]); }
;                     *(u32x4*)(O + (size_t)(row0 + ai * 128 + m * 16) * KAB + 1024 + col0 + bj * 128) = pack8(v0, v1); } }
	v_pk_add_f32 v[124:125], v[124:125], v[132:133]
	v_pk_add_f32 v[126:127], v[126:127], v[134:135]
	v_pk_add_f32 v[122:123], v[122:123], v[130:131]
	v_pk_add_f32 v[120:121], v[120:121], v[128:129]
	v_mul_f32_e32 v124, 0xbfb8aa3b, v124
	v_mul_f32_e32 v125, 0xbfb8aa3b, v125
	v_mul_f32_e32 v120, 0xbfb8aa3b, v120
	v_mul_f32_e32 v141, 0xbfb8aa3b, v121
	v_mul_f32_e32 v126, 0xbfb8aa3b, v126
	v_mul_f32_e32 v142, 0xbfb8aa3b, v122
	v_mul_f32_e32 v127, 0xbfb8aa3b, v127
	v_mul_f32_e32 v143, 0xbfb8aa3b, v123
	v_exp_f32_e32 v150, v124
	v_exp_f32_e32 v156, v125
	v_exp_f32_e32 v151, v120
	v_lshlrev_b32_e32 v120, 16, v136
	v_and_b32_e32 v121, 0xffff0000, v136
	v_exp_f32_e32 v136, v141
	v_lshlrev_b32_e32 v122, 16, v138
	v_and_b32_e32 v123, 0xffff0000, v138
	v_exp_f32_e32 v138, v126
	v_exp_f32_e32 v141, v142
	v_exp_f32_e32 v142, v127
	v_lshlrev_b32_e32 v124, 16, v137
	v_and_b32_e32 v125, 0xffff0000, v137
	v_exp_f32_e32 v137, v143
	v_lshlrev_b32_e32 v126, 16, v139
	v_and_b32_e32 v127, 0xffff0000, v139
	v_add_f32_e32 v139, 1.0, v150
	v_add_f32_e32 v150, 1.0, v156
	v_add_f32_e32 v143, 1.0, v151
	v_add_f32_e32 v151, 1.0, v136
	v_add_f32_e32 v156, 1.0, v138
	v_add_f32_e32 v141, 1.0, v141
	v_add_f32_e32 v157, 1.0, v142
	v_add_f32_e32 v158, 1.0, v137
	v_rcp_f32_e32 v136, v139
	v_rcp_f32_e32 v137, v150
	v_rcp_f32_e32 v138, v143
	v_rcp_f32_e32 v139, v151
	v_rcp_f32_e32 v142, v156
	v_rcp_f32_e32 v150, v141
	v_rcp_f32_e32 v143, v157
	v_rcp_f32_e32 v151, v158
	v_pk_mul_f32 v[120:121], v[136:137], v[120:121]
	v_pk_mul_f32 v[122:123], v[138:139], v[122:123]
	v_pk_mul_f32 v[124:125], v[142:143], v[124:125]
	v_pk_mul_f32 v[126:127], v[150:151], v[126:127]
	v_cvt_pk_bf16_f32 v224, v120, v121
	v_mad_i64_i32 v[120:121], s[20:21], v140, s40, v[196:197]
	v_cvt_pk_bf16_f32 v225, v124, v125
	v_cvt_pk_bf16_f32 v226, v122, v123
	v_cvt_pk_bf16_f32 v227, v126, v127
	v_lshl_add_u64 v[214:215], v[120:121], 0, v[194:195]
	global_load_dwordx4 v[156:159], v[148:149], off offset:256
	global_load_dwordx4 v[228:231], v[146:147], off
	s_nop 0
	global_load_dwordx4 v[148:151], v[146:147], off offset:256
	global_load_dwordx4 v[232:235], v[144:145], off
	s_nop 0
	global_load_dwordx4 v[144:147], v[144:145], off offset:256
	s_nop 0
	global_load_dwordx4 v[236:239], v[168:169], off
	global_load_dwordx4 v[140:143], v[168:169], off offset:256
	global_load_dwordx4 v[172:175], v[166:167], off
	global_load_dwordx4 v[136:139], v[166:167], off offset:256
	s_nop 0
	global_load_dwordx4 v[168:171], v[164:165], off
	global_load_dwordx4 v[124:127], v[164:165], off offset:256
	s_nop 0
	global_load_dwordx4 v[164:167], v[212:213], off
	global_load_dwordx4 v[120:123], v[212:213], off offset:256
	v_pk_add_f32 v[116:117], v[116:117], v[132:133]
	v_pk_add_f32 v[114:115], v[114:115], v[130:131]
	v_mul_f32_e32 v116, 0xbfb8aa3b, v116
	v_mul_f32_e32 v117, 0xbfb8aa3b, v117
	v_exp_f32_e32 v116, v116
	v_exp_f32_e32 v117, v117
	v_pk_add_f32 v[118:119], v[118:119], v[134:135]
	v_pk_add_f32 v[112:113], v[112:113], v[128:129]
	v_add_f32_e32 v116, 1.0, v116
	v_add_f32_e32 v117, 1.0, v117
	v_rcp_f32_e32 v116, v116
	v_rcp_f32_e32 v117, v117
	v_mul_f32_e32 v114, 0xbfb8aa3b, v114
	v_mul_f32_e32 v112, 0xbfb8aa3b, v112
	v_mul_f32_e32 v113, 0xbfb8aa3b, v113
	v_lshlrev_b32_e32 v212, 16, v152
	v_and_b32_e32 v213, 0xffff0000, v152
	v_mul_f32_e32 v118, 0xbfb8aa3b, v118
	v_exp_f32_e32 v152, v114
	v_mul_f32_e32 v114, 0xbfb8aa3b, v119
	v_exp_f32_e32 v112, v112
	v_exp_f32_e32 v113, v113
	v_exp_f32_e32 v118, v118
	v_exp_f32_e32 v119, v114
	v_mul_f32_e32 v115, 0xbfb8aa3b, v115
	v_pk_mul_f32 v[116:117], v[116:117], v[212:213]
	v_lshlrev_b32_e32 v212, 16, v154
	v_and_b32_e32 v213, 0xffff0000, v154
	v_exp_f32_e32 v154, v115
	v_pk_add_f32 v[108:109], v[108:109], v[132:133]
	v_pk_add_f32 v[104:105], v[104:105], v[128:129]
	v_mul_f32_e32 v108, 0xbfb8aa3b, v108
	v_mul_f32_e32 v109, 0xbfb8aa3b, v109
	v_add_f32_e32 v112, 1.0, v112
	v_add_f32_e32 v113, 1.0, v113
	v_add_f32_e32 v118, 1.0, v118
	v_add_f32_e32 v119, 1.0, v119
	v_exp_f32_e32 v108, v108
	v_mul_f32_e32 v104, 0xbfb8aa3b, v104
	v_exp_f32_e32 v109, v109
	v_mul_f32_e32 v105, 0xbfb8aa3b, v105
	v_rcp_f32_e32 v112, v112
	v_rcp_f32_e32 v113, v113
	v_rcp_f32_e32 v114, v118
	v_add_f32_e32 v118, 1.0, v152
	v_rcp_f32_e32 v115, v119
	v_add_f32_e32 v119, 1.0, v154
	v_exp_f32_e32 v104, v104
	v_exp_f32_e32 v105, v105
	v_rcp_f32_e32 v118, v118
	v_rcp_f32_e32 v119, v119
	v_lshlrev_b32_e32 v152, 16, v153
	v_and_b32_e32 v153, 0xffff0000, v153
	v_add_f32_e32 v108, 1.0, v108
	v_add_f32_e32 v109, 1.0, v109
	v_pk_mul_f32 v[112:113], v[112:113], v[212:213]
	v_pk_mul_f32 v[152:153], v[114:115], v[152:153]
	v_lshlrev_b32_e32 v114, 16, v155
	v_and_b32_e32 v115, 0xffff0000, v155
	v_rcp_f32_e32 v108, v108
	v_add_f32_e32 v104, 1.0, v104
	v_rcp_f32_e32 v109, v109
	v_add_f32_e32 v105, 1.0, v105
	v_pk_mul_f32 v[118:119], v[118:119], v[114:115]
	v_cvt_pk_bf16_f32 v114, v116, v117
	v_cvt_pk_bf16_f32 v116, v112, v113
	v_mad_i64_i32 v[112:113], s[20:21], v210, s40, v[196:197]
	v_rcp_f32_e32 v104, v104
	v_rcp_f32_e32 v105, v105
	v_cvt_pk_bf16_f32 v115, v152, v153
	v_cvt_pk_bf16_f32 v117, v118, v119
	v_lshl_add_u64 v[112:113], v[112:113], 0, v[194:195]
	global_store_dwordx4 v[112:113], v[114:117], off offset:2048
	v_pk_add_f32 v[106:107], v[106:107], v[130:131]
	v_pk_add_f32 v[110:111], v[110:111], v[134:135]
	s_waitcnt vmcnt(0)
; __device__ __forceinline__ float sigm(float x) { return __builtin_amdgcn_rcpf(1.0f + __builtin_amdgcn_exp2f(-1.4426950408889634f * x)); }
;     __device__ __forceinline__ void operator()(EPI_ARGS) const {
;     ...
;             for (int ai = 0; ai < 2; ++ai)
; #pragma unroll
;                 for (int m = 0; m < 4; ++m) { const size_t off = (size_t)(row0 + ai * 128 + m * 16) * 512 + col0 + bj * 128;
;                     f32x4 h0, h1; unpack8(hw[ai][m], h0, h1);
;                     f32x4 v0 = acc[ai][bj][m][0] + b0, v1 = acc[ai][bj][m][1] + b1;
; #pragma unroll
;                     for (int j = 0; j < 4; ++j) { v0[j] = h0[j] * sigm(v0[j]); v1[j] = h1[j] * sigm(v1[j]); }
;                     *(u32x4*)(O + (size_t)(row0 + ai * 128 + m * 16) * KAB + 1024 + col0 + bj * 128) = pack8(v0, v1); } }
	v_lshlrev_b32_e32 v114, 16, v228
	v_and_b32_e32 v115, 0xffff0000, v228
	v_pk_mul_f32 v[108:109], v[108:109], v[114:115]
	v_lshlrev_b32_e32 v114, 16, v230
	v_and_b32_e32 v115, 0xffff0000, v230
	v_mul_f32_e32 v106, 0xbfb8aa3b, v106
	v_mul_f32_e32 v110, 0xbfb8aa3b, v110
	v_pk_mul_f32 v[104:105], v[104:105], v[114:115]
	v_exp_f32_e32 v114, v106
	v_mul_f32_e32 v106, 0xbfb8aa3b, v111
	v_exp_f32_e32 v110, v110
	v_exp_f32_e32 v111, v106
	v_mul_f32_e32 v107, 0xbfb8aa3b, v107
	v_exp_f32_e32 v116, v107
	v_pk_add_f32 v[100:101], v[100:101], v[132:133]
	v_pk_add_f32 v[96:97], v[96:97], v[128:129]
	v_mul_f32_e32 v100, 0xbfb8aa3b, v100
	v_mul_f32_e32 v101, 0xbfb8aa3b, v101
	v_add_f32_e32 v110, 1.0, v110
	v_add_f32_e32 v111, 1.0, v111
	v_exp_f32_e32 v100, v100
	v_mul_f32_e32 v96, 0xbfb8aa3b, v96
	v_exp_f32_e32 v101, v101
	v_mul_f32_e32 v97, 0xbfb8aa3b, v97
	v_rcp_f32_e32 v106, v110
	v_add_f32_e32 v110, 1.0, v114
	v_rcp_f32_e32 v107, v111
	v_add_f32_e32 v111, 1.0, v116
	v_exp_f32_e32 v96, v96
	v_exp_f32_e32 v97, v97
	v_rcp_f32_e32 v110, v110
	v_rcp_f32_e32 v111, v111
	v_lshlrev_b32_e32 v114, 16, v229
	v_and_b32_e32 v115, 0xffff0000, v229
	v_add_f32_e32 v100, 1.0, v100
	v_add_f32_e32 v101, 1.0, v101
	v_pk_mul_f32 v[114:115], v[106:107], v[114:115]
	v_lshlrev_b32_e32 v106, 16, v231
	v_and_b32_e32 v107, 0xffff0000, v231
	v_rcp_f32_e32 v100, v100
	v_add_f32_e32 v96, 1.0, v96
	v_rcp_f32_e32 v101, v101
	v_add_f32_e32 v97, 1.0, v97
	v_pk_mul_f32 v[110:111], v[110:111], v[106:107]
	v_cvt_pk_bf16_f32 v106, v108, v109
	v_cvt_pk_bf16_f32 v108, v104, v105
	v_mad_i64_i32 v[104:105], s[20:21], v208, s40, v[196:197]
	v_rcp_f32_e32 v96, v96
	v_rcp_f32_e32 v97, v97
	v_cvt_pk_bf16_f32 v107, v114, v115
	v_cvt_pk_bf16_f32 v109, v110, v111
	v_lshl_add_u64 v[104:105], v[104:105], 0, v[194:195]
	global_store_dwordx4 v[104:105], v[106:109], off offset:2048
	v_pk_add_f32 v[98:99], v[98:99], v[130:131]
	v_pk_add_f32 v[102:103], v[102:103], v[134:135]
	v_lshlrev_b32_e32 v106, 16, v232
	v_and_b32_e32 v107, 0xffff0000, v232
	v_pk_mul_f32 v[100:101], v[100:101], v[106:107]
	v_lshlrev_b32_e32 v106, 16, v234
	v_and_b32_e32 v107, 0xffff0000, v234
	v_mul_f32_e32 v98, 0xbfb8aa3b, v98
	v_mul_f32_e32 v102, 0xbfb8aa3b, v102
	v_pk_mul_f32 v[96:97], v[96:97], v[106:107]
	v_exp_f32_e32 v106, v98
	v_mul_f32_e32 v98, 0xbfb8aa3b, v103
	v_exp_f32_e32 v102, v102
	v_exp_f32_e32 v103, v98
	v_mul_f32_e32 v99, 0xbfb8aa3b, v99
	v_exp_f32_e32 v108, v99
	v_pk_add_f32 v[92:93], v[92:93], v[132:133]
	v_pk_add_f32 v[88:89], v[88:89], v[128:129]
	v_mul_f32_e32 v92, 0xbfb8aa3b, v92
	v_mul_f32_e32 v93, 0xbfb8aa3b, v93
	v_add_f32_e32 v102, 1.0, v102
	v_add_f32_e32 v103, 1.0, v103
	v_exp_f32_e32 v92, v92
	v_mul_f32_e32 v88, 0xbfb8aa3b, v88
	v_exp_f32_e32 v93, v93
	v_mul_f32_e32 v89, 0xbfb8aa3b, v89
	v_rcp_f32_e32 v98, v102
	v_add_f32_e32 v102, 1.0, v106
	v_rcp_f32_e32 v99, v103
	v_add_f32_e32 v103, 1.0, v108
	v_exp_f32_e32 v88, v88
	v_exp_f32_e32 v89, v89
	v_rcp_f32_e32 v102, v102
	v_rcp_f32_e32 v103, v103
	v_lshlrev_b32_e32 v106, 16, v233
	v_and_b32_e32 v107, 0xffff0000, v233
	v_add_f32_e32 v92, 1.0, v92
	v_add_f32_e32 v93, 1.0, v93
	v_pk_mul_f32 v[106:107], v[98:99], v[106:107]
	v_lshlrev_b32_e32 v98, 16, v235
	v_and_b32_e32 v99, 0xffff0000, v235
	v_rcp_f32_e32 v92, v92
	v_add_f32_e32 v88, 1.0, v88
	v_rcp_f32_e32 v93, v93
	v_add_f32_e32 v89, 1.0, v89
	v_pk_mul_f32 v[102:103], v[102:103], v[98:99]
	v_cvt_pk_bf16_f32 v98, v100, v101
	v_cvt_pk_bf16_f32 v100, v96, v97
	v_mad_i64_i32 v[96:97], s[20:21], v206, s40, v[196:197]
	v_rcp_f32_e32 v88, v88
	v_rcp_f32_e32 v89, v89
	v_cvt_pk_bf16_f32 v99, v106, v107
	v_cvt_pk_bf16_f32 v101, v102, v103
	v_lshl_add_u64 v[96:97], v[96:97], 0, v[194:195]
	global_store_dwordx4 v[96:97], v[98:101], off offset:2048
	v_pk_add_f32 v[90:91], v[90:91], v[130:131]
	v_pk_add_f32 v[94:95], v[94:95], v[134:135]
	v_lshlrev_b32_e32 v98, 16, v236
	v_and_b32_e32 v99, 0xffff0000, v236
	v_pk_mul_f32 v[92:93], v[92:93], v[98:99]
	v_lshlrev_b32_e32 v98, 16, v238
	v_and_b32_e32 v99, 0xffff0000, v238
	v_mul_f32_e32 v90, 0xbfb8aa3b, v90
	v_mul_f32_e32 v94, 0xbfb8aa3b, v94
	v_pk_mul_f32 v[88:89], v[88:89], v[98:99]
	v_exp_f32_e32 v98, v90
	v_mul_f32_e32 v90, 0xbfb8aa3b, v95
	v_exp_f32_e32 v94, v94
	v_exp_f32_e32 v95, v90
	v_mul_f32_e32 v91, 0xbfb8aa3b, v91
	v_exp_f32_e32 v100, v91
	v_pk_add_f32 v[84:85], v[84:85], v[132:133]
	v_pk_add_f32 v[80:81], v[80:81], v[128:129]
	v_mul_f32_e32 v84, 0xbfb8aa3b, v84
	v_mul_f32_e32 v85, 0xbfb8aa3b, v85
	v_add_f32_e32 v94, 1.0, v94
	v_add_f32_e32 v95, 1.0, v95
	v_exp_f32_e32 v84, v84
	v_mul_f32_e32 v80, 0xbfb8aa3b, v80
	v_exp_f32_e32 v85, v85
	v_mul_f32_e32 v81, 0xbfb8aa3b, v81
	v_rcp_f32_e32 v90, v94
	v_add_f32_e32 v94, 1.0, v98
	v_rcp_f32_e32 v91, v95
	v_add_f32_e32 v95, 1.0, v100
	v_exp_f32_e32 v80, v80
	v_exp_f32_e32 v81, v81
	v_rcp_f32_e32 v94, v94
	v_rcp_f32_e32 v95, v95
	v_lshlrev_b32_e32 v98, 16, v237
	v_and_b32_e32 v99, 0xffff0000, v237
	v_add_f32_e32 v84, 1.0, v84
	v_add_f32_e32 v85, 1.0, v85
	v_pk_mul_f32 v[98:99], v[90:91], v[98:99]
	v_lshlrev_b32_e32 v90, 16, v239
	v_and_b32_e32 v91, 0xffff0000, v239
	v_rcp_f32_e32 v84, v84
	v_add_f32_e32 v80, 1.0, v80
	v_rcp_f32_e32 v85, v85
	v_add_f32_e32 v81, 1.0, v81
	v_pk_mul_f32 v[94:95], v[94:95], v[90:91]
	v_cvt_pk_bf16_f32 v90, v92, v93
	v_cvt_pk_bf16_f32 v92, v88, v89
	v_mad_i64_i32 v[88:89], s[20:21], v204, s40, v[196:197]
	v_rcp_f32_e32 v80, v80
	v_rcp_f32_e32 v81, v81
	v_cvt_pk_bf16_f32 v91, v98, v99
	v_cvt_pk_bf16_f32 v93, v94, v95
	v_lshl_add_u64 v[88:89], v[88:89], 0, v[194:195]
	global_store_dwordx4 v[88:89], v[90:93], off offset:2048
	v_pk_add_f32 v[82:83], v[82:83], v[130:131]
; __device__ __forceinline__ float sigm(float x) { return __builtin_amdgcn_rcpf(1.0f + __builtin_amdgcn_exp2f(-1.4426950408889634f * x)); }
;     __device__ __forceinline__ void operator()(EPI_ARGS) const {
;     ...
;         for (int bj = 0; bj < 2; ++bj) { const f32x4 b0 = *(const f32x4*)(bias + col0 + bj * 128), b1 = *(const f32x4*)(bias + col0 + bj * 128 + 4);
;             u32x4 hw[2][4];
; #pragma unroll
;             for (int ai = 0; ai < 2; ++ai)
; #pragma unroll
;                 for (int m = 0; m < 4; ++m) hw[ai][m] = *(const u32x4*)(H + (size_t)(row0 + ai * 128 + m * 16) * 512 + col0 + bj * 128);
; #pragma unroll
;             for (int ai = 0; ai < 2; ++ai)
; #pragma unroll
;                 for (int m = 0; m < 4; ++m) { const size_t off = (size_t)(row0 + ai * 128 + m * 16) * 512 + col0 + bj * 128;
;                     f32x4 h0, h1; unpack8(hw[ai][m], h0, h1);
;                     f32x4 v0 = acc[ai][bj][m][0] + b0, v1 = acc[ai][bj][m][1] + b1;
; #pragma unroll
;                     for (int j = 0; j < 4; ++j) { v0[j] = h0[j] * sigm(v0[j]); v1[j] = h1[j] * sigm(v1[j]); }
;                     *(u32x4*)(O + (size_t)(row0 + ai * 128 + m * 16) * KAB + 1024 + col0 + bj * 128) = pack8(v0, v1); } }
	v_pk_add_f32 v[86:87], v[86:87], v[134:135]
	v_lshlrev_b32_e32 v90, 16, v172
	v_and_b32_e32 v91, 0xffff0000, v172
	v_pk_mul_f32 v[84:85], v[84:85], v[90:91]
	v_lshlrev_b32_e32 v90, 16, v174
	v_and_b32_e32 v91, 0xffff0000, v174
	v_mul_f32_e32 v82, 0xbfb8aa3b, v82
	v_mul_f32_e32 v86, 0xbfb8aa3b, v86
	v_pk_mul_f32 v[80:81], v[80:81], v[90:91]
	v_exp_f32_e32 v90, v82
	v_mul_f32_e32 v82, 0xbfb8aa3b, v87
	v_exp_f32_e32 v86, v86
	v_exp_f32_e32 v87, v82
	v_mul_f32_e32 v83, 0xbfb8aa3b, v83
	v_exp_f32_e32 v92, v83
	v_pk_add_f32 v[76:77], v[76:77], v[132:133]
	v_pk_add_f32 v[72:73], v[72:73], v[128:129]
	v_mul_f32_e32 v76, 0xbfb8aa3b, v76
	v_mul_f32_e32 v77, 0xbfb8aa3b, v77
	v_add_f32_e32 v86, 1.0, v86
	v_add_f32_e32 v87, 1.0, v87
	v_exp_f32_e32 v76, v76
	v_mul_f32_e32 v72, 0xbfb8aa3b, v72
	v_exp_f32_e32 v77, v77
	v_mul_f32_e32 v73, 0xbfb8aa3b, v73
	v_rcp_f32_e32 v82, v86
	v_add_f32_e32 v86, 1.0, v90
	v_rcp_f32_e32 v83, v87
	v_add_f32_e32 v87, 1.0, v92
	v_exp_f32_e32 v72, v72
	v_exp_f32_e32 v73, v73
	v_rcp_f32_e32 v86, v86
	v_rcp_f32_e32 v87, v87
	v_lshlrev_b32_e32 v90, 16, v173
	v_and_b32_e32 v91, 0xffff0000, v173
	v_add_f32_e32 v76, 1.0, v76
	v_add_f32_e32 v77, 1.0, v77
	v_pk_mul_f32 v[90:91], v[82:83], v[90:91]
	v_lshlrev_b32_e32 v82, 16, v175
	v_and_b32_e32 v83, 0xffff0000, v175
	v_rcp_f32_e32 v76, v76
	v_add_f32_e32 v72, 1.0, v72
	v_rcp_f32_e32 v77, v77
	v_add_f32_e32 v73, 1.0, v73
	v_pk_mul_f32 v[86:87], v[86:87], v[82:83]
	v_cvt_pk_bf16_f32 v82, v84, v85
	v_cvt_pk_bf16_f32 v84, v80, v81
	v_mad_i64_i32 v[80:81], s[20:21], v202, s40, v[196:197]
	v_rcp_f32_e32 v72, v72
	v_rcp_f32_e32 v73, v73
	v_cvt_pk_bf16_f32 v83, v90, v91
	v_cvt_pk_bf16_f32 v85, v86, v87
	v_lshl_add_u64 v[80:81], v[80:81], 0, v[194:195]
	global_store_dwordx4 v[80:81], v[82:85], off offset:2048
	v_pk_add_f32 v[74:75], v[74:75], v[130:131]
	v_pk_add_f32 v[78:79], v[78:79], v[134:135]
	v_lshlrev_b32_e32 v82, 16, v168
	v_and_b32_e32 v83, 0xffff0000, v168
	v_pk_mul_f32 v[76:77], v[76:77], v[82:83]
	v_lshlrev_b32_e32 v82, 16, v170
	v_and_b32_e32 v83, 0xffff0000, v170
	v_mul_f32_e32 v74, 0xbfb8aa3b, v74
	v_mul_f32_e32 v78, 0xbfb8aa3b, v78
	v_pk_mul_f32 v[72:73], v[72:73], v[82:83]
	v_exp_f32_e32 v82, v74
	v_mul_f32_e32 v74, 0xbfb8aa3b, v79
	v_exp_f32_e32 v78, v78
	v_exp_f32_e32 v79, v74
	v_mul_f32_e32 v75, 0xbfb8aa3b, v75
	v_exp_f32_e32 v84, v75
	v_pk_add_f32 v[68:69], v[68:69], v[132:133]
	v_pk_add_f32 v[64:65], v[64:65], v[128:129]
	v_mul_f32_e32 v68, 0xbfb8aa3b, v68
	v_mul_f32_e32 v69, 0xbfb8aa3b, v69
	v_exp_f32_e32 v68, v68
	v_mul_f32_e32 v64, 0xbfb8aa3b, v64
	v_exp_f32_e32 v69, v69
	v_mul_f32_e32 v65, 0xbfb8aa3b, v65
	v_add_f32_e32 v78, 1.0, v78
	v_add_f32_e32 v79, 1.0, v79
	v_exp_f32_e32 v64, v64
	v_exp_f32_e32 v65, v65
	v_rcp_f32_e32 v74, v78
	v_add_f32_e32 v78, 1.0, v82
	v_rcp_f32_e32 v75, v79
	v_add_f32_e32 v79, 1.0, v84
	v_rcp_f32_e32 v78, v78
	v_rcp_f32_e32 v79, v79
	v_add_f32_e32 v68, 1.0, v68
	v_add_f32_e32 v69, 1.0, v69
	v_lshlrev_b32_e32 v82, 16, v169
	v_and_b32_e32 v83, 0xffff0000, v169
	v_rcp_f32_e32 v68, v68
	v_add_f32_e32 v64, 1.0, v64
	v_rcp_f32_e32 v69, v69
	v_add_f32_e32 v65, 1.0, v65
	v_pk_mul_f32 v[74:75], v[74:75], v[82:83]
	v_lshlrev_b32_e32 v82, 16, v171
	v_and_b32_e32 v83, 0xffff0000, v171
	v_pk_add_f32 v[70:71], v[70:71], v[134:135]
	v_rcp_f32_e32 v64, v64
	v_rcp_f32_e32 v65, v65
	v_pk_mul_f32 v[82:83], v[78:79], v[82:83]
	v_cvt_pk_bf16_f32 v78, v72, v73
	v_mad_i64_i32 v[72:73], s[20:21], v200, s40, v[196:197]
	v_mul_f32_e32 v70, 0xbfb8aa3b, v70
	v_cvt_pk_bf16_f32 v76, v76, v77
	v_cvt_pk_bf16_f32 v77, v74, v75
	v_lshl_add_u64 v[74:75], v[72:73], 0, v[194:195]
	v_lshlrev_b32_e32 v72, 16, v164
	v_and_b32_e32 v73, 0xffff0000, v164
	v_exp_f32_e32 v70, v70
	v_pk_add_f32 v[66:67], v[66:67], v[130:131]
	v_pk_mul_f32 v[68:69], v[68:69], v[72:73]
	v_lshlrev_b32_e32 v72, 16, v166
	v_and_b32_e32 v73, 0xffff0000, v166
	v_pk_mul_f32 v[72:73], v[64:65], v[72:73]
	v_mul_f32_e32 v65, 0xbfb8aa3b, v66
	v_exp_f32_e32 v65, v65
	v_mul_f32_e32 v66, 0xbfb8aa3b, v71
	v_add_f32_e32 v64, 1.0, v70
	v_exp_f32_e32 v70, v66
	v_mul_f32_e32 v67, 0xbfb8aa3b, v67
	v_exp_f32_e32 v67, v67
	v_add_f32_e32 v65, 1.0, v65
	v_rcp_f32_e32 v66, v65
	v_add_f32_e32 v65, 1.0, v70
	v_rcp_f32_e32 v64, v64
	v_rcp_f32_e32 v65, v65
	v_add_f32_e32 v67, 1.0, v67
	v_rcp_f32_e32 v67, v67
	v_lshlrev_b32_e32 v70, 16, v165
	v_and_b32_e32 v71, 0xffff0000, v165
	v_cvt_pk_bf16_f32 v79, v82, v83
	v_pk_mul_f32 v[70:71], v[64:65], v[70:71]
	v_lshlrev_b32_e32 v64, 16, v167
	v_and_b32_e32 v65, 0xffff0000, v167
	global_store_dwordx4 v[74:75], v[76:79], off offset:2048
	global_store_dwordx4 v[214:215], v[224:227], off offset:2048
	s_nop 0
	v_pk_mul_f32 v[76:77], v[66:67], v[64:65]
	v_cvt_pk_bf16_f32 v64, v68, v69
	v_mad_i64_i32 v[68:69], s[20:21], v198, s40, v[196:197]
	v_cvt_pk_bf16_f32 v65, v70, v71
	v_cvt_pk_bf16_f32 v66, v72, v73
	v_cvt_pk_bf16_f32 v67, v76, v77
	v_lshl_add_u64 v[72:73], v[68:69], 0, v[194:195]
	global_store_dwordx4 v[72:73], v[64:67], off offset:2048
	global_load_dwordx4 v[68:71], v[192:193], off offset:512
	s_nop 0
	global_load_dwordx4 v[64:67], v[192:193], off offset:528
	v_lshlrev_b32_e32 v76, 16, v160
	v_and_b32_e32 v77, 0xffff0000, v160
	s_mov_b64 s[20:21], s[14:15]
	s_waitcnt vmcnt(0)
; __device__ __forceinline__ float sigm(float x) { return __builtin_amdgcn_rcpf(1.0f + __builtin_amdgcn_exp2f(-1.4426950408889634f * x)); }
;     __device__ __forceinline__ void operator()(EPI_ARGS) const {
;     ...
;             for (int ai = 0; ai < 2; ++ai)
; #pragma unroll
;                 for (int m = 0; m < 4; ++m) { const size_t off = (size_t)(row0 + ai * 128 + m * 16) * 512 + col0 + bj * 128;
;                     f32x4 h0, h1; unpack8(hw[ai][m], h0, h1);
;                     f32x4 v0 = acc[ai][bj][m][0] + b0, v1 = acc[ai][bj][m][1] + b1;
; #pragma unroll
;                     for (int j = 0; j < 4; ++j) { v0[j] = h0[j] * sigm(v0[j]); v1[j] = h1[j] * sigm(v1[j]); }
;                     *(u32x4*)(O + (size_t)(row0 + ai * 128 + m * 16) * KAB + 1024 + col0 + bj * 128) = pack8(v0, v1); } }
	v_pk_add_f32 v[60:61], v[60:61], v[68:69]
	s_nop 0
	v_mul_f32_e32 v60, 0xbfb8aa3b, v60
	v_pk_add_f32 v[56:57], v[56:57], v[64:65]
	v_mul_f32_e32 v61, 0xbfb8aa3b, v61
	v_exp_f32_e32 v60, v60
	v_mul_f32_e32 v56, 0xbfb8aa3b, v56
	v_exp_f32_e32 v61, v61
	v_mul_f32_e32 v57, 0xbfb8aa3b, v57
	v_exp_f32_e32 v56, v56
	v_exp_f32_e32 v57, v57
	v_add_f32_e32 v60, 1.0, v60
	v_add_f32_e32 v61, 1.0, v61
	v_rcp_f32_e32 v60, v60
	v_add_f32_e32 v56, 1.0, v56
	v_rcp_f32_e32 v61, v61
	v_add_f32_e32 v57, 1.0, v57
	v_pk_add_f32 v[62:63], v[62:63], v[70:71]
	v_rcp_f32_e32 v56, v56
	v_rcp_f32_e32 v57, v57
	v_mul_f32_e32 v62, 0xbfb8aa3b, v62
	v_exp_f32_e32 v62, v62
	v_pk_add_f32 v[58:59], v[58:59], v[66:67]
	v_pk_mul_f32 v[60:61], v[60:61], v[76:77]
	v_lshlrev_b32_e32 v76, 16, v162
	v_and_b32_e32 v77, 0xffff0000, v162
	v_pk_mul_f32 v[76:77], v[56:57], v[76:77]
	v_mul_f32_e32 v57, 0xbfb8aa3b, v58
	v_exp_f32_e32 v57, v57
	v_mul_f32_e32 v58, 0xbfb8aa3b, v63
	v_add_f32_e32 v56, 1.0, v62
	v_exp_f32_e32 v62, v58
	v_mul_f32_e32 v59, 0xbfb8aa3b, v59
	v_exp_f32_e32 v59, v59
	v_pk_add_f32 v[52:53], v[52:53], v[68:69]
	v_add_f32_e32 v57, 1.0, v57
	v_mul_f32_e32 v52, 0xbfb8aa3b, v52
	v_pk_add_f32 v[48:49], v[48:49], v[64:65]
	v_mul_f32_e32 v53, 0xbfb8aa3b, v53
	v_rcp_f32_e32 v58, v57
	v_add_f32_e32 v57, 1.0, v62
	v_exp_f32_e32 v52, v52
	v_mul_f32_e32 v48, 0xbfb8aa3b, v48
	v_exp_f32_e32 v53, v53
	v_mul_f32_e32 v49, 0xbfb8aa3b, v49
	v_rcp_f32_e32 v56, v56
	v_rcp_f32_e32 v57, v57
	v_add_f32_e32 v59, 1.0, v59
	v_exp_f32_e32 v48, v48
	v_exp_f32_e32 v49, v49
	v_rcp_f32_e32 v59, v59
	v_lshlrev_b32_e32 v62, 16, v161
	v_and_b32_e32 v63, 0xffff0000, v161
	v_add_f32_e32 v52, 1.0, v52
	v_add_f32_e32 v53, 1.0, v53
	v_pk_mul_f32 v[62:63], v[56:57], v[62:63]
	v_lshlrev_b32_e32 v56, 16, v163
	v_and_b32_e32 v57, 0xffff0000, v163
	v_rcp_f32_e32 v52, v52
	v_add_f32_e32 v48, 1.0, v48
	v_rcp_f32_e32 v53, v53
	v_add_f32_e32 v49, 1.0, v49
	v_pk_mul_f32 v[78:79], v[58:59], v[56:57]
	v_pk_add_f32 v[54:55], v[54:55], v[70:71]
	v_rcp_f32_e32 v48, v48
	v_rcp_f32_e32 v49, v49
	v_cvt_pk_bf16_f32 v56, v60, v61
	v_cvt_pk_bf16_f32 v57, v62, v63
	v_cvt_pk_bf16_f32 v58, v76, v77
	v_cvt_pk_bf16_f32 v59, v78, v79
	v_mul_f32_e32 v54, 0xbfb8aa3b, v54
	global_store_dwordx4 v[214:215], v[56:59], off offset:2304
	v_exp_f32_e32 v54, v54
	v_pk_add_f32 v[50:51], v[50:51], v[66:67]
	v_lshlrev_b32_e32 v56, 16, v156
	v_and_b32_e32 v57, 0xffff0000, v156
	v_pk_mul_f32 v[52:53], v[52:53], v[56:57]
	v_lshlrev_b32_e32 v56, 16, v158
	v_and_b32_e32 v57, 0xffff0000, v158
	v_pk_mul_f32 v[56:57], v[48:49], v[56:57]
	v_mul_f32_e32 v49, 0xbfb8aa3b, v50
	v_exp_f32_e32 v49, v49
	v_mul_f32_e32 v50, 0xbfb8aa3b, v55
	v_add_f32_e32 v48, 1.0, v54
	v_exp_f32_e32 v54, v50
	v_mul_f32_e32 v51, 0xbfb8aa3b, v51
	v_exp_f32_e32 v51, v51
	v_pk_add_f32 v[44:45], v[44:45], v[68:69]
	v_add_f32_e32 v49, 1.0, v49
	v_mul_f32_e32 v44, 0xbfb8aa3b, v44
	v_pk_add_f32 v[40:41], v[40:41], v[64:65]
	v_mul_f32_e32 v45, 0xbfb8aa3b, v45
	v_rcp_f32_e32 v50, v49
	v_add_f32_e32 v49, 1.0, v54
	v_exp_f32_e32 v44, v44
	v_mul_f32_e32 v40, 0xbfb8aa3b, v40
	v_exp_f32_e32 v45, v45
	v_mul_f32_e32 v41, 0xbfb8aa3b, v41
	v_rcp_f32_e32 v48, v48
	v_rcp_f32_e32 v49, v49
	v_add_f32_e32 v51, 1.0, v51
	v_exp_f32_e32 v40, v40
	v_exp_f32_e32 v41, v41
	v_rcp_f32_e32 v51, v51
	v_lshlrev_b32_e32 v54, 16, v157
	v_and_b32_e32 v55, 0xffff0000, v157
	v_add_f32_e32 v44, 1.0, v44
	v_add_f32_e32 v45, 1.0, v45
	v_pk_mul_f32 v[54:55], v[48:49], v[54:55]
	v_lshlrev_b32_e32 v48, 16, v159
	v_and_b32_e32 v49, 0xffff0000, v159
	v_rcp_f32_e32 v44, v44
	v_add_f32_e32 v40, 1.0, v40
	v_rcp_f32_e32 v45, v45
	v_add_f32_e32 v41, 1.0, v41
	v_pk_mul_f32 v[58:59], v[50:51], v[48:49]
	v_pk_add_f32 v[46:47], v[46:47], v[70:71]
	v_rcp_f32_e32 v40, v40
	v_rcp_f32_e32 v41, v41
	v_cvt_pk_bf16_f32 v48, v52, v53
	v_cvt_pk_bf16_f32 v49, v54, v55
	v_cvt_pk_bf16_f32 v50, v56, v57
	v_cvt_pk_bf16_f32 v51, v58, v59
	v_mul_f32_e32 v46, 0xbfb8aa3b, v46
	global_store_dwordx4 v[112:113], v[48:51], off offset:2304
	v_exp_f32_e32 v46, v46
	v_pk_add_f32 v[42:43], v[42:43], v[66:67]
	v_lshlrev_b32_e32 v48, 16, v148
	v_and_b32_e32 v49, 0xffff0000, v148
	v_pk_mul_f32 v[44:45], v[44:45], v[48:49]
	v_lshlrev_b32_e32 v48, 16, v150
	v_and_b32_e32 v49, 0xffff0000, v150
	v_pk_mul_f32 v[48:49], v[40:41], v[48:49]
	v_mul_f32_e32 v41, 0xbfb8aa3b, v42
	v_exp_f32_e32 v41, v41
	v_mul_f32_e32 v42, 0xbfb8aa3b, v47
	v_add_f32_e32 v40, 1.0, v46
	v_exp_f32_e32 v46, v42
	v_mul_f32_e32 v43, 0xbfb8aa3b, v43
	v_exp_f32_e32 v43, v43
	v_pk_add_f32 v[36:37], v[36:37], v[68:69]
	v_add_f32_e32 v41, 1.0, v41
	v_mul_f32_e32 v36, 0xbfb8aa3b, v36
	v_pk_add_f32 v[32:33], v[32:33], v[64:65]
	v_mul_f32_e32 v37, 0xbfb8aa3b, v37
	v_rcp_f32_e32 v42, v41
	v_add_f32_e32 v41, 1.0, v46
	v_exp_f32_e32 v36, v36
	v_mul_f32_e32 v32, 0xbfb8aa3b, v32
	v_exp_f32_e32 v37, v37
	v_mul_f32_e32 v33, 0xbfb8aa3b, v33
	v_rcp_f32_e32 v40, v40
	v_rcp_f32_e32 v41, v41
	v_add_f32_e32 v43, 1.0, v43
	v_exp_f32_e32 v32, v32
	v_exp_f32_e32 v33, v33
	v_rcp_f32_e32 v43, v43
	v_lshlrev_b32_e32 v46, 16, v149
	v_and_b32_e32 v47, 0xffff0000, v149
	v_add_f32_e32 v36, 1.0, v36
	v_add_f32_e32 v37, 1.0, v37
	v_pk_mul_f32 v[46:47], v[40:41], v[46:47]
	v_lshlrev_b32_e32 v40, 16, v151
	v_and_b32_e32 v41, 0xffff0000, v151
	v_rcp_f32_e32 v36, v36
	v_add_f32_e32 v32, 1.0, v32
	v_rcp_f32_e32 v37, v37
	v_add_f32_e32 v33, 1.0, v33
	v_pk_mul_f32 v[50:51], v[42:43], v[40:41]
	v_pk_add_f32 v[38:39], v[38:39], v[70:71]
	v_rcp_f32_e32 v32, v32
	v_rcp_f32_e32 v33, v33
	v_cvt_pk_bf16_f32 v40, v44, v45
	v_cvt_pk_bf16_f32 v41, v46, v47
	v_cvt_pk_bf16_f32 v42, v48, v49
	v_cvt_pk_bf16_f32 v43, v50, v51
	v_mul_f32_e32 v38, 0xbfb8aa3b, v38
; __device__ __forceinline__ float sigm(float x) { return __builtin_amdgcn_rcpf(1.0f + __builtin_amdgcn_exp2f(-1.4426950408889634f * x)); }
;     __device__ __forceinline__ void operator()(EPI_ARGS) const {
;     ...
;             for (int ai = 0; ai < 2; ++ai)
; #pragma unroll
;                 for (int m = 0; m < 4; ++m) { const size_t off = (size_t)(row0 + ai * 128 + m * 16) * 512 + col0 + bj * 128;
;                     f32x4 h0, h1; unpack8(hw[ai][m], h0, h1);
;                     f32x4 v0 = acc[ai][bj][m][0] + b0, v1 = acc[ai][bj][m][1] + b1;
; #pragma unroll
;                     for (int j = 0; j < 4; ++j) { v0[j] = h0[j] * sigm(v0[j]); v1[j] = h1[j] * sigm(v1[j]); }
;                     *(u32x4*)(O + (size_t)(row0 + ai * 128 + m * 16) * KAB + 1024 + col0 + bj * 128) = pack8(v0, v1); } }
	global_store_dwordx4 v[104:105], v[40:43], off offset:2304
	v_exp_f32_e32 v38, v38
	v_pk_add_f32 v[34:35], v[34:35], v[66:67]
	v_lshlrev_b32_e32 v40, 16, v144
	v_and_b32_e32 v41, 0xffff0000, v144
	v_pk_mul_f32 v[36:37], v[36:37], v[40:41]
	v_lshlrev_b32_e32 v40, 16, v146
	v_and_b32_e32 v41, 0xffff0000, v146
	v_pk_mul_f32 v[40:41], v[32:33], v[40:41]
	v_mul_f32_e32 v33, 0xbfb8aa3b, v34
	v_exp_f32_e32 v33, v33
	v_mul_f32_e32 v34, 0xbfb8aa3b, v39
	v_add_f32_e32 v32, 1.0, v38
	v_exp_f32_e32 v38, v34
	v_mul_f32_e32 v35, 0xbfb8aa3b, v35
	v_exp_f32_e32 v35, v35
	v_pk_add_f32 v[28:29], v[28:29], v[68:69]
	v_add_f32_e32 v33, 1.0, v33
	v_mul_f32_e32 v28, 0xbfb8aa3b, v28
	v_pk_add_f32 v[24:25], v[24:25], v[64:65]
	v_mul_f32_e32 v29, 0xbfb8aa3b, v29
	v_rcp_f32_e32 v34, v33
	v_add_f32_e32 v33, 1.0, v38
	v_exp_f32_e32 v28, v28
	v_mul_f32_e32 v24, 0xbfb8aa3b, v24
	v_exp_f32_e32 v29, v29
	v_mul_f32_e32 v25, 0xbfb8aa3b, v25
	v_rcp_f32_e32 v32, v32
	v_rcp_f32_e32 v33, v33
	v_add_f32_e32 v35, 1.0, v35
	v_exp_f32_e32 v24, v24
	v_exp_f32_e32 v25, v25
	v_rcp_f32_e32 v35, v35
	v_lshlrev_b32_e32 v38, 16, v145
	v_and_b32_e32 v39, 0xffff0000, v145
	v_add_f32_e32 v28, 1.0, v28
	v_add_f32_e32 v29, 1.0, v29
	v_pk_mul_f32 v[38:39], v[32:33], v[38:39]
	v_lshlrev_b32_e32 v32, 16, v147
	v_and_b32_e32 v33, 0xffff0000, v147
	v_rcp_f32_e32 v28, v28
	v_add_f32_e32 v24, 1.0, v24
	v_rcp_f32_e32 v29, v29
	v_add_f32_e32 v25, 1.0, v25
	v_pk_mul_f32 v[42:43], v[34:35], v[32:33]
	v_pk_add_f32 v[30:31], v[30:31], v[70:71]
	v_rcp_f32_e32 v24, v24
	v_rcp_f32_e32 v25, v25
	v_cvt_pk_bf16_f32 v32, v36, v37
	v_cvt_pk_bf16_f32 v33, v38, v39
	v_cvt_pk_bf16_f32 v34, v40, v41
	v_cvt_pk_bf16_f32 v35, v42, v43
	v_mul_f32_e32 v30, 0xbfb8aa3b, v30
	global_store_dwordx4 v[96:97], v[32:35], off offset:2304
	v_exp_f32_e32 v30, v30
	v_pk_add_f32 v[26:27], v[26:27], v[66:67]
	v_lshlrev_b32_e32 v32, 16, v140
	v_and_b32_e32 v33, 0xffff0000, v140
	v_pk_mul_f32 v[28:29], v[28:29], v[32:33]
	v_lshlrev_b32_e32 v32, 16, v142
	v_and_b32_e32 v33, 0xffff0000, v142
	v_pk_mul_f32 v[32:33], v[24:25], v[32:33]
	v_mul_f32_e32 v25, 0xbfb8aa3b, v26
	v_exp_f32_e32 v25, v25
	v_mul_f32_e32 v26, 0xbfb8aa3b, v31
	v_add_f32_e32 v24, 1.0, v30
	v_exp_f32_e32 v30, v26
	v_mul_f32_e32 v27, 0xbfb8aa3b, v27
	v_exp_f32_e32 v27, v27
	v_pk_add_f32 v[20:21], v[20:21], v[68:69]
	v_add_f32_e32 v25, 1.0, v25
	v_mul_f32_e32 v20, 0xbfb8aa3b, v20
	v_pk_add_f32 v[16:17], v[16:17], v[64:65]
	v_mul_f32_e32 v21, 0xbfb8aa3b, v21
	v_rcp_f32_e32 v26, v25
	v_add_f32_e32 v25, 1.0, v30
	v_exp_f32_e32 v20, v20
	v_mul_f32_e32 v16, 0xbfb8aa3b, v16
	v_exp_f32_e32 v21, v21
	v_mul_f32_e32 v17, 0xbfb8aa3b, v17
	v_rcp_f32_e32 v24, v24
	v_rcp_f32_e32 v25, v25
	v_add_f32_e32 v27, 1.0, v27
	v_exp_f32_e32 v16, v16
	v_exp_f32_e32 v17, v17
	v_rcp_f32_e32 v27, v27
	v_lshlrev_b32_e32 v30, 16, v141
	v_and_b32_e32 v31, 0xffff0000, v141
	v_add_f32_e32 v20, 1.0, v20
	v_add_f32_e32 v21, 1.0, v21
	v_pk_mul_f32 v[30:31], v[24:25], v[30:31]
	v_lshlrev_b32_e32 v24, 16, v143
	v_and_b32_e32 v25, 0xffff0000, v143
	v_rcp_f32_e32 v20, v20
	v_add_f32_e32 v16, 1.0, v16
	v_rcp_f32_e32 v21, v21
	v_add_f32_e32 v17, 1.0, v17
	v_pk_mul_f32 v[34:35], v[26:27], v[24:25]
	v_pk_add_f32 v[22:23], v[22:23], v[70:71]
	v_rcp_f32_e32 v16, v16
	v_rcp_f32_e32 v17, v17
	v_cvt_pk_bf16_f32 v24, v28, v29
	v_cvt_pk_bf16_f32 v25, v30, v31
	v_cvt_pk_bf16_f32 v26, v32, v33
	v_cvt_pk_bf16_f32 v27, v34, v35
	v_mul_f32_e32 v22, 0xbfb8aa3b, v22
	global_store_dwordx4 v[88:89], v[24:27], off offset:2304
	v_exp_f32_e32 v22, v22
	v_pk_add_f32 v[18:19], v[18:19], v[66:67]
	v_lshlrev_b32_e32 v24, 16, v136
	v_and_b32_e32 v25, 0xffff0000, v136
	v_pk_mul_f32 v[20:21], v[20:21], v[24:25]
	v_lshlrev_b32_e32 v24, 16, v138
	v_and_b32_e32 v25, 0xffff0000, v138
	v_pk_mul_f32 v[24:25], v[16:17], v[24:25]
	v_mul_f32_e32 v17, 0xbfb8aa3b, v18
	v_exp_f32_e32 v17, v17
	v_mul_f32_e32 v18, 0xbfb8aa3b, v23
	v_add_f32_e32 v16, 1.0, v22
	v_exp_f32_e32 v22, v18
	v_mul_f32_e32 v19, 0xbfb8aa3b, v19
	v_exp_f32_e32 v19, v19
; __device__ __forceinline__ float sigm(float x) { return __builtin_amdgcn_rcpf(1.0f + __builtin_amdgcn_exp2f(-1.4426950408889634f * x)); }
; #define PG8_WAIT_V(n) asm volatile("s_waitcnt vmcnt(" #n ")" ::: "memory")
; #define PG8_BAR __builtin_amdgcn_s_barrier()
; template <class Epi>
; __device__ __forceinline__ void gemm_phase(ldsp lds, const Gemm g, const StaticOrder& S, const Epi& E) {
;     ...
;     PG8_WAIT_V(0);
;     if (wr == 0) PG8_BAR;
;     PG8_BAR;
;     __device__ __forceinline__ void operator()(EPI_ARGS) const {
;     ...
;             for (int ai = 0; ai < 2; ++ai)
; #pragma unroll
;                 for (int m = 0; m < 4; ++m) { const size_t off = (size_t)(row0 + ai * 128 + m * 16) * 512 + col0 + bj * 128;
;                     f32x4 h0, h1; unpack8(hw[ai][m], h0, h1);
;                     f32x4 v0 = acc[ai][bj][m][0] + b0, v1 = acc[ai][bj][m][1] + b1;
; #pragma unroll
;                     for (int j = 0; j < 4; ++j) { v0[j] = h0[j] * sigm(v0[j]); v1[j] = h1[j] * sigm(v1[j]); }
;                     *(u32x4*)(O + (size_t)(row0 + ai * 128 + m * 16) * KAB + 1024 + col0 + bj * 128) = pack8(v0, v1); } }
	v_pk_add_f32 v[12:13], v[12:13], v[68:69]
	v_add_f32_e32 v17, 1.0, v17
	v_mul_f32_e32 v12, 0xbfb8aa3b, v12
	v_pk_add_f32 v[8:9], v[8:9], v[64:65]
	v_mul_f32_e32 v13, 0xbfb8aa3b, v13
	v_rcp_f32_e32 v18, v17
	v_add_f32_e32 v17, 1.0, v22
	v_exp_f32_e32 v12, v12
	v_mul_f32_e32 v8, 0xbfb8aa3b, v8
	v_exp_f32_e32 v13, v13
	v_mul_f32_e32 v9, 0xbfb8aa3b, v9
	v_rcp_f32_e32 v16, v16
	v_rcp_f32_e32 v17, v17
	v_add_f32_e32 v19, 1.0, v19
	v_exp_f32_e32 v8, v8
	v_exp_f32_e32 v9, v9
	v_rcp_f32_e32 v19, v19
	v_lshlrev_b32_e32 v22, 16, v137
	v_and_b32_e32 v23, 0xffff0000, v137
	v_add_f32_e32 v12, 1.0, v12
	v_add_f32_e32 v13, 1.0, v13
	v_pk_mul_f32 v[22:23], v[16:17], v[22:23]
	v_lshlrev_b32_e32 v16, 16, v139
	v_and_b32_e32 v17, 0xffff0000, v139
	v_rcp_f32_e32 v12, v12
	v_add_f32_e32 v8, 1.0, v8
	v_rcp_f32_e32 v13, v13
	v_add_f32_e32 v9, 1.0, v9
	v_pk_mul_f32 v[26:27], v[18:19], v[16:17]
	v_pk_add_f32 v[14:15], v[14:15], v[70:71]
	v_rcp_f32_e32 v8, v8
	v_rcp_f32_e32 v9, v9
	v_cvt_pk_bf16_f32 v16, v20, v21
	v_cvt_pk_bf16_f32 v17, v22, v23
	v_cvt_pk_bf16_f32 v18, v24, v25
	v_cvt_pk_bf16_f32 v19, v26, v27
	v_mul_f32_e32 v14, 0xbfb8aa3b, v14
	global_store_dwordx4 v[80:81], v[16:19], off offset:2304
	v_exp_f32_e32 v14, v14
	v_pk_add_f32 v[10:11], v[10:11], v[66:67]
	v_lshlrev_b32_e32 v16, 16, v124
	v_and_b32_e32 v17, 0xffff0000, v124
	v_pk_mul_f32 v[12:13], v[12:13], v[16:17]
	v_lshlrev_b32_e32 v16, 16, v126
	v_and_b32_e32 v17, 0xffff0000, v126
	v_pk_mul_f32 v[16:17], v[8:9], v[16:17]
	v_mul_f32_e32 v9, 0xbfb8aa3b, v10
	v_exp_f32_e32 v9, v9
	v_mul_f32_e32 v10, 0xbfb8aa3b, v15
	v_add_f32_e32 v8, 1.0, v14
	v_exp_f32_e32 v14, v10
	v_mul_f32_e32 v11, 0xbfb8aa3b, v11
	v_exp_f32_e32 v11, v11
	v_pk_add_f32 v[4:5], v[4:5], v[68:69]
	v_add_f32_e32 v9, 1.0, v9
	v_mul_f32_e32 v4, 0xbfb8aa3b, v4
	v_pk_add_f32 v[0:1], v[0:1], v[64:65]
	v_mul_f32_e32 v5, 0xbfb8aa3b, v5
	v_rcp_f32_e32 v10, v9
	v_add_f32_e32 v9, 1.0, v14
	v_exp_f32_e32 v4, v4
	v_mul_f32_e32 v0, 0xbfb8aa3b, v0
	v_exp_f32_e32 v5, v5
	v_mul_f32_e32 v1, 0xbfb8aa3b, v1
	v_rcp_f32_e32 v8, v8
	v_rcp_f32_e32 v9, v9
	v_add_f32_e32 v11, 1.0, v11
	v_exp_f32_e32 v0, v0
	v_exp_f32_e32 v1, v1
	v_rcp_f32_e32 v11, v11
	v_lshlrev_b32_e32 v14, 16, v125
	v_and_b32_e32 v15, 0xffff0000, v125
	v_add_f32_e32 v4, 1.0, v4
	v_add_f32_e32 v5, 1.0, v5
	v_pk_mul_f32 v[14:15], v[8:9], v[14:15]
	v_lshlrev_b32_e32 v8, 16, v127
	v_and_b32_e32 v9, 0xffff0000, v127
	v_rcp_f32_e32 v4, v4
	v_add_f32_e32 v0, 1.0, v0
	v_rcp_f32_e32 v5, v5
	v_add_f32_e32 v1, 1.0, v1
	v_pk_mul_f32 v[18:19], v[10:11], v[8:9]
	v_pk_add_f32 v[6:7], v[6:7], v[70:71]
	v_rcp_f32_e32 v0, v0
	v_rcp_f32_e32 v1, v1
	v_cvt_pk_bf16_f32 v8, v12, v13
	v_cvt_pk_bf16_f32 v9, v14, v15
	v_cvt_pk_bf16_f32 v10, v16, v17
	v_cvt_pk_bf16_f32 v11, v18, v19
	v_mul_f32_e32 v6, 0xbfb8aa3b, v6
	global_store_dwordx4 v[74:75], v[8:11], off offset:2304
	v_exp_f32_e32 v6, v6
	v_pk_add_f32 v[2:3], v[2:3], v[66:67]
	v_lshlrev_b32_e32 v8, 16, v120
	v_and_b32_e32 v9, 0xffff0000, v120
	v_pk_mul_f32 v[4:5], v[4:5], v[8:9]
	v_lshlrev_b32_e32 v8, 16, v122
	v_and_b32_e32 v9, 0xffff0000, v122
	v_pk_mul_f32 v[8:9], v[0:1], v[8:9]
	v_mul_f32_e32 v1, 0xbfb8aa3b, v2
	v_exp_f32_e32 v1, v1
	v_mul_f32_e32 v2, 0xbfb8aa3b, v7
	v_add_f32_e32 v0, 1.0, v6
	v_exp_f32_e32 v6, v2
	v_mul_f32_e32 v3, 0xbfb8aa3b, v3
	v_exp_f32_e32 v3, v3
	v_add_f32_e32 v1, 1.0, v1
	v_rcp_f32_e32 v2, v1
	v_add_f32_e32 v1, 1.0, v6
	v_rcp_f32_e32 v0, v0
	v_rcp_f32_e32 v1, v1
	v_add_f32_e32 v3, 1.0, v3
	v_rcp_f32_e32 v3, v3
	v_lshlrev_b32_e32 v6, 16, v121
	v_and_b32_e32 v7, 0xffff0000, v121
	v_pk_mul_f32 v[6:7], v[0:1], v[6:7]
	v_lshlrev_b32_e32 v0, 16, v123
	v_and_b32_e32 v1, 0xffff0000, v123
	v_pk_mul_f32 v[10:11], v[2:3], v[0:1]
	v_cvt_pk_bf16_f32 v0, v4, v5
	v_cvt_pk_bf16_f32 v1, v6, v7
	v_cvt_pk_bf16_f32 v2, v8, v9
	v_cvt_pk_bf16_f32 v3, v10, v11
	global_store_dwordx4 v[72:73], v[0:3], off offset:2304
	s_cbranch_vccz .LBB0_567
	s_waitcnt vmcnt(0)
	s_cmpk_gt_u32 s26, 0xff
	s_cbranch_scc1 .LBB0_578
	s_barrier

; #define PG8_STAGE(bufoff, gbase, voff) do { _Pragma("unroll") for (int _i = 0; _i < 2; ++_i) \
;         __builtin_amdgcn_global_load_lds((const unsigned*)((const char*)(gbase) + (voff)[_i]), (LAS unsigned*)(lds + (bufoff) + ldsw + _i * 8192), 16, 0, 0); } while (0)
; #define PG8_WAIT_V(n) asm volatile("s_waitcnt vmcnt(" #n ")" ::: "memory")
; #define PG8_BAR __builtin_amdgcn_s_barrier()
; template <class Epi>
; __device__ __forceinline__ void gemm_phase(ldsp lds, const Gemm g, const StaticOrder& S, const Epi& E) {
;     ...
;     const int aoff = lds_byte(wr * 64 + fr, fq * 8), boff = lds_byte(wc * 32 + fr, fq * 8);
;     ...
;     PG8_WAIT_V(4); PG8_BAR;
;     PG8_STAGE(PG8_SB(1, 0), cB + kstep, voffB); PG8_STAGE(PG8_SA(1, 0), cA + kstep, voffA); PG8_STAGE(PG8_SB(1, 1), cB + hstep + kstep, voffB);
;     PG8_WAIT_V(6); PG8_BAR;
.LBB0_641:
	v_readlane_b32 s12, v246, 48
	v_readlane_b32 s13, v246, 49
	s_add_u32 s8, s12, 0x1f340000
	s_addc_u32 s9, s13, 0
	s_add_u32 s10, s12, 0x27340000
	s_addc_u32 s11, s13, 0
	s_lshl_b32 s2, s2, 5
	s_mov_b64 s[12:13], 0x80
	v_readlane_b32 s14, v246, 50
	s_and_b32 s5, s2, 0x60
	s_add_i32 m0, s36, 0x18000
	v_lshl_add_u64 v[6:7], v[6:7], 0, s[12:13]
	s_lshl_b32 s4, s0, 13
	s_lshl_b32 s14, s5, 7
	s_waitcnt vmcnt(4)
	s_barrier
	global_load_lds_dwordx4 v[6:7], off
	v_lshl_add_u64 v[4:5], v[4:5], 0, s[12:13]
	s_add_i32 m0, s36, 0x1a000
	s_add_i32 s41, s36, 0x8000
	s_add_i32 s42, s36, 0xa000
	global_load_lds_dwordx4 v[4:5], off
	v_lshl_add_u64 v[2:3], v[2:3], 0, s[12:13]
	s_mov_b32 m0, s41
	s_add_u32 s2, s24, 0x60080
	global_load_lds_dwordx4 v[2:3], off
	v_lshl_add_u64 v[0:1], v[0:1], 0, s[12:13]
	s_mov_b32 m0, s42
	s_addc_u32 s3, s25, 0
	global_load_lds_dwordx4 v[0:1], off
	s_add_i32 m0, s36, 0x1c000
	v_lshl_add_u64 v[0:1], s[2:3], 0, v[194:195]
	global_load_lds_dwordx4 v[0:1], off
	v_lshl_add_u64 v[0:1], s[2:3], 0, v[198:199]
	s_add_i32 m0, s36, 0x1e000
	v_lshlrev_b32_e32 v2, 2, v220
	global_load_lds_dwordx4 v[0:1], off
	v_and_b32_e32 v0, 15, v220
	v_lshlrev_b32_e32 v1, 1, v10
	v_lshl_or_b32 v221, s0, 6, v0
	v_lshl_or_b32 v0, v0, 6, v1
	v_and_b32_e32 v2, 32, v2
	v_bitop3_b32 v3, v0, s4, v2 bitop3:0xde
	v_lshlrev_b32_e32 v0, 6, v220
	s_movk_i32 s0, 0x3c0
	v_and_or_b32 v0, v0, s0, v1
	v_bitop3_b32 v222, s14, v0, v2 bitop3:0xf6
	v_add_u32_e32 v247, 0x10000, v222
	v_add_u16_e32 v0, v8, v9
	v_lshrrev_b16_e32 v2, 1, v0
	s_sext_i32_i8 s27, s1
	s_mov_b64 s[0:1], 0x60080
	s_waitcnt vmcnt(6)
	v_add_lshl_u32 v0, v11, v2, 1
	v_mov_b32_e32 v1, v195
	v_readlane_b32 s15, v246, 51
	v_lshl_add_u64 v[200:201], v[0:1], 0, s[0:1]
	v_add_lshl_u32 v0, v12, v2, 1
	s_ashr_i32 s43, s62, 31
	s_mov_b32 s44, s62
	v_or_b32_e32 v223, s5, v10
	v_lshl_add_u64 v[202:203], v[0:1], 0, s[0:1]
	v_mov_b64_e32 v[204:205], 0x400
	v_mov_b64_e32 v[206:207], 0x3ff
	s_add_i32 s45, 0, 0x10000
	v_add_u32_e32 v224, 0, v3
	s_add_i32 s46, 0, 0x14000
	s_mov_b64 s[14:15], 0x80000
	s_mov_b64 s[16:17], 0x90000
	s_mov_b64 s[18:19], 0xa0000
	s_mov_b64 s[20:21], 0xb0000
	s_barrier
	s_branch .LBB0_643

; #define PG8_STAGE(bufoff, gbase, voff) do { _Pragma("unroll") for (int _i = 0; _i < 2; ++_i) \
;         __builtin_amdgcn_global_load_lds((const unsigned*)((const char*)(gbase) + (voff)[_i]), (LAS unsigned*)(lds + (bufoff) + ldsw + _i * 8192), 16, 0, 0); } while (0)
; #define PG8_LDA(dst, b, h) do { _Pragma("unroll") for (int m = 0; m < 4; ++m) _Pragma("unroll") for (int k = 0; k < 2; ++k) dst[m][k] = *(const LAS bf16x8*)(lds + PG8_SA(b, h) + aoff + m * 2048 + k * 1024); } while (0)
; #define PG8_LDB(dst, b, h) do { _Pragma("unroll") for (int n = 0; n < 2; ++n) _Pragma("unroll") for (int k = 0; k < 2; ++k) dst[n][k] = *(const LAS bf16x8*)(lds + PG8_SB(b, h) + boff + n * 2048 + k * 1024); } while (0)
; #define PG8_MMA(ai, bj, At, Bt) do { __builtin_amdgcn_s_setprio(1); _Pragma("unroll") for (int m = 0; m < 4; ++m) _Pragma("unroll") for (int n = 0; n < 2; ++n) _Pragma("unroll") for (int k = 0; k < 2; ++k) \
;         acc[ai][bj][m][n] = __builtin_amdgcn_mfma_f32_16x16x32_bf16(Bt[n][k], At[m][k], acc[ai][bj][m][n], 0, 0, 0); __builtin_amdgcn_s_setprio(0); } while (0)
; #define PG8_WAIT_V(n) asm volatile("s_waitcnt vmcnt(" #n ")" ::: "memory")
; #define PG8_BAR __builtin_amdgcn_s_barrier()
; template <class Epi>
; __device__ __forceinline__ void gemm_phase(ldsp lds, const Gemm g, const StaticOrder& S, const Epi& E) {
;     ...
;             const bool last = (t == nt - 2);
;             const char* a1 = cA + (size_t)(t + 1) * kstep;
;             const char* a2 = last ? nA : cA + (size_t)(t + 2) * kstep; const char* b2 = last ? nB : cB + (size_t)(t + 2) * kstep;
;             const char* a3 = a2 + kstep; const char* b3 = b2 + kstep;
;             if constexpr (Epi::NPRE > 0) { if (last) E.pre(pre, cur, wr, fr); }
;             if constexpr (Epi::MID_T > 0) { if (t == Epi::MID_T) E.mid(acc, cur, wr, wc, fr, fq); }
;             PG8_LDB(B0, 0, 0); PG8_SCHED; PG8_LDA(At, 0, 0); PG8_STAGE(PG8_SA(1, 1), a1 + hstep, voffA);
;             PG8_WAIT_L(8); PG8_WAIT_V(10); PG8_BAR; PG8_WAIT_L(0); PG8_MMA(0, 0, At, B0); PG8_BAR; PG8_SCHED;
;             PG8_LDB(B1, 0, 1); PG8_STAGE(PG8_SB(0, 0), b2, voffB);
;             PG8_WAIT_V(10); PG8_BAR; PG8_WAIT_L(0); PG8_MMA(0, 1, At, B1); PG8_BAR;
;             PG8_LDA(At, 0, 1); PG8_STAGE(PG8_SA(0, 0), a2, voffA);
;             PG8_WAIT_V(10); PG8_BAR; PG8_WAIT_L(0); PG8_MMA(1, 0, At, B0); PG8_BAR; PG8_SCHED;
.LBB0_654:
	s_add_u32 s26, s22, s24
	ds_read_b128 v[128:131], v247 offset:0
	ds_read_b128 v[132:135], v247 offset:1024
	ds_read_b128 v[136:139], v247 offset:2048
	ds_read_b128 v[140:143], v247 offset:3072
	s_addc_u32 s27, s23, s25
	s_add_u32 s26, s26, 0x100
	s_addc_u32 s27, s27, 0
	s_add_u32 s54, s51, s24
	s_addc_u32 s55, s52, s25
	s_cmpk_eq_i32 s24, 0xb00
	s_cselect_b32 s29, s1, s27
	s_cselect_b32 s28, s0, s26
	s_cselect_b32 s27, s5, s55
	s_cselect_b32 s26, s4, s54
	v_lshl_add_u64 v[176:177], v[212:213], 0, s[24:25]
	s_add_i32 m0, s36, 0xc000
	s_waitcnt vmcnt(0)
	ds_read_b128 v[144:147], v224
	ds_read_b128 v[148:151], v224 offset:1024
	ds_read_b128 v[152:155], v224 offset:2048
	ds_read_b128 v[156:159], v224 offset:3072
	ds_read_b128 v[160:163], v224 offset:4096
	ds_read_b128 v[164:167], v224 offset:5120
	ds_read_b128 v[168:171], v224 offset:6144
	ds_read_b128 v[172:175], v224 offset:7168
	global_load_lds_dwordx4 v[176:177], off
	v_lshl_add_u64 v[176:177], v[214:215], 0, s[24:25]
	s_add_i32 m0, s36, 0xe000
	s_nop 0
	global_load_lds_dwordx4 v[176:177], off
	s_waitcnt lgkmcnt(8)
	s_waitcnt vmcnt(10)
	s_barrier
	s_waitcnt lgkmcnt(0)
	s_setprio 1
	s_waitcnt lgkmcnt(0)
	v_mfma_f32_16x16x32_bf16 v[124:127], v[128:131], v[144:147], v[124:127]
	v_mfma_f32_16x16x32_bf16 v[120:123], v[136:139], v[144:147], v[120:123]
	v_mfma_f32_16x16x32_bf16 v[116:119], v[128:131], v[152:155], v[116:119]
	v_mfma_f32_16x16x32_bf16 v[104:107], v[136:139], v[152:155], v[104:107]
	v_mfma_f32_16x16x32_bf16 v[96:99], v[128:131], v[160:163], v[96:99]
	v_mfma_f32_16x16x32_bf16 v[88:91], v[136:139], v[160:163], v[88:91]
	v_mfma_f32_16x16x32_bf16 v[80:83], v[128:131], v[168:171], v[80:83]
	v_mfma_f32_16x16x32_bf16 v[72:75], v[136:139], v[168:171], v[72:75]
	v_mfma_f32_16x16x32_bf16 v[124:127], v[132:135], v[148:151], v[124:127]
	v_mfma_f32_16x16x32_bf16 v[120:123], v[140:143], v[148:151], v[120:123]
	v_mfma_f32_16x16x32_bf16 v[116:119], v[132:135], v[156:159], v[116:119]
	v_mfma_f32_16x16x32_bf16 v[104:107], v[140:143], v[156:159], v[104:107]
	v_mfma_f32_16x16x32_bf16 v[96:99], v[132:135], v[164:167], v[96:99]
	v_mfma_f32_16x16x32_bf16 v[88:91], v[140:143], v[164:167], v[88:91]
	v_mfma_f32_16x16x32_bf16 v[80:83], v[132:135], v[172:175], v[80:83]
	s_barrier
	v_mfma_f32_16x16x32_bf16 v[72:75], v[140:143], v[172:175], v[72:75]
	s_setprio 0
	s_add_i32 s54, s45, s35
	s_add_u32 s98, s26, 0x80
	s_addc_u32 s99, s27, 0
	s_mov_b32 m0, s54
	ds_read_b128 v[176:179], v247 offset:16384
	ds_read_b128 v[180:183], v247 offset:17408
	ds_read_b128 v[184:187], v247 offset:18432
	ds_read_b128 v[188:191], v247 offset:19456
	global_load_lds_dwordx4 v194, s[26:27]
	s_add_i32 m0, s54, 0x2000
	s_nop 0
	global_load_lds_dwordx4 v198, s[26:27]
	s_waitcnt vmcnt(10)
	s_barrier
	s_waitcnt lgkmcnt(0)
	s_setprio 1
	s_waitcnt lgkmcnt(0)
	v_mfma_f32_16x16x32_bf16 v[112:115], v[176:179], v[144:147], v[112:115]
	v_mfma_f32_16x16x32_bf16 v[108:111], v[184:187], v[144:147], v[108:111]
	v_mfma_f32_16x16x32_bf16 v[100:103], v[176:179], v[152:155], v[100:103]
	v_mfma_f32_16x16x32_bf16 v[92:95], v[184:187], v[152:155], v[92:95]
	v_mfma_f32_16x16x32_bf16 v[84:87], v[176:179], v[160:163], v[84:87]
	v_mfma_f32_16x16x32_bf16 v[76:79], v[184:187], v[160:163], v[76:79]
	v_mfma_f32_16x16x32_bf16 v[68:71], v[176:179], v[168:171], v[68:71]
	v_mfma_f32_16x16x32_bf16 v[64:67], v[184:187], v[168:171], v[64:67]
	v_mfma_f32_16x16x32_bf16 v[112:115], v[180:183], v[148:151], v[112:115]
	v_mfma_f32_16x16x32_bf16 v[108:111], v[188:191], v[148:151], v[108:111]
	v_mfma_f32_16x16x32_bf16 v[100:103], v[180:183], v[156:159], v[100:103]
	v_mfma_f32_16x16x32_bf16 v[92:95], v[188:191], v[156:159], v[92:95]
	v_mfma_f32_16x16x32_bf16 v[84:87], v[180:183], v[164:167], v[84:87]
	v_mfma_f32_16x16x32_bf16 v[76:79], v[188:191], v[164:167], v[76:79]
	v_mfma_f32_16x16x32_bf16 v[68:71], v[180:183], v[172:175], v[68:71]
	s_barrier
	v_mfma_f32_16x16x32_bf16 v[64:67], v[188:191], v[172:175], v[64:67]
	s_setprio 0
	s_mov_b32 m0, s36
	s_add_u32 s100, s28, 0x80
	s_addc_u32 s101, s29, 0
	ds_read_b128 v[144:147], v224 offset:16384
	ds_read_b128 v[148:151], v224 offset:17408
	ds_read_b128 v[152:155], v224 offset:18432
	ds_read_b128 v[156:159], v224 offset:19456
	ds_read_b128 v[160:163], v224 offset:20480
	ds_read_b128 v[164:167], v224 offset:21504
	ds_read_b128 v[168:171], v224 offset:22528
	ds_read_b128 v[172:175], v224 offset:23552
	global_load_lds_dwordx4 v192, s[28:29]
	s_mov_b32 m0, s37
	s_nop 0
	global_load_lds_dwordx4 v196, s[28:29]
	s_waitcnt vmcnt(10)
	s_barrier
	s_waitcnt lgkmcnt(0)
	s_setprio 1
	s_waitcnt lgkmcnt(0)
	v_mfma_f32_16x16x32_bf16 v[60:63], v[128:131], v[144:147], v[60:63]
	v_mfma_f32_16x16x32_bf16 v[56:59], v[136:139], v[144:147], v[56:59]
	v_mfma_f32_16x16x32_bf16 v[48:51], v[128:131], v[152:155], v[48:51]
	v_mfma_f32_16x16x32_bf16 v[40:43], v[136:139], v[152:155], v[40:43]
	v_mfma_f32_16x16x32_bf16 v[32:35], v[128:131], v[160:163], v[32:35]
	v_mfma_f32_16x16x32_bf16 v[24:27], v[136:139], v[160:163], v[24:27]
	v_mfma_f32_16x16x32_bf16 v[16:19], v[128:131], v[168:171], v[16:19]
	v_mfma_f32_16x16x32_bf16 v[8:11], v[136:139], v[168:171], v[8:11]
	v_mfma_f32_16x16x32_bf16 v[60:63], v[132:135], v[148:151], v[60:63]
	v_mfma_f32_16x16x32_bf16 v[56:59], v[140:143], v[148:151], v[56:59]
	v_mfma_f32_16x16x32_bf16 v[48:51], v[132:135], v[156:159], v[48:51]
	v_mfma_f32_16x16x32_bf16 v[40:43], v[140:143], v[156:159], v[40:43]
	v_mfma_f32_16x16x32_bf16 v[32:35], v[132:135], v[164:167], v[32:35]
	v_mfma_f32_16x16x32_bf16 v[24:27], v[140:143], v[164:167], v[24:27]
	v_mfma_f32_16x16x32_bf16 v[16:19], v[132:135], v[172:175], v[16:19]
	s_barrier
; #define PG8_STAGE(bufoff, gbase, voff) do { _Pragma("unroll") for (int _i = 0; _i < 2; ++_i) \
;         __builtin_amdgcn_global_load_lds((const unsigned*)((const char*)(gbase) + (voff)[_i]), (LAS unsigned*)(lds + (bufoff) + ldsw + _i * 8192), 16, 0, 0); } while (0)
; #define PG8_LDA(dst, b, h) do { _Pragma("unroll") for (int m = 0; m < 4; ++m) _Pragma("unroll") for (int k = 0; k < 2; ++k) dst[m][k] = *(const LAS bf16x8*)(lds + PG8_SA(b, h) + aoff + m * 2048 + k * 1024); } while (0)
; #define PG8_LDB(dst, b, h) do { _Pragma("unroll") for (int n = 0; n < 2; ++n) _Pragma("unroll") for (int k = 0; k < 2; ++k) dst[n][k] = *(const LAS bf16x8*)(lds + PG8_SB(b, h) + boff + n * 2048 + k * 1024); } while (0)
; #define PG8_MMA(ai, bj, At, Bt) do { __builtin_amdgcn_s_setprio(1); _Pragma("unroll") for (int m = 0; m < 4; ++m) _Pragma("unroll") for (int n = 0; n < 2; ++n) _Pragma("unroll") for (int k = 0; k < 2; ++k) \
;         acc[ai][bj][m][n] = __builtin_amdgcn_mfma_f32_16x16x32_bf16(Bt[n][k], At[m][k], acc[ai][bj][m][n], 0, 0, 0); __builtin_amdgcn_s_setprio(0); } while (0)
; #define PG8_WAIT_V(n) asm volatile("s_waitcnt vmcnt(" #n ")" ::: "memory")
; #define PG8_WAIT_L(n) asm volatile("s_waitcnt lgkmcnt(" #n ")" ::: "memory")
; #define PG8_BAR __builtin_amdgcn_s_barrier()
; #define PG8_SCHED __builtin_amdgcn_sched_barrier(0)
; template <class Epi>
; __device__ __forceinline__ void gemm_phase(ldsp lds, const Gemm g, const StaticOrder& S, const Epi& E) {
;     ...
;             PG8_WAIT_V(10); PG8_BAR; PG8_WAIT_L(0); PG8_MMA(1, 0, At, B0); PG8_BAR; PG8_SCHED;
;             PG8_STAGE(PG8_SB(0, 1), b2 + hstep, voffB);
;             PG8_WAIT_V(10); PG8_BAR; PG8_MMA(1, 1, At, B1); PG8_BAR;
;             PG8_LDB(B0, 1, 0); PG8_SCHED; PG8_LDA(At, 1, 0); PG8_STAGE(PG8_SA(0, 1), a2 + hstep, voffA);
;             PG8_WAIT_L(8); PG8_WAIT_V(10); PG8_BAR; PG8_WAIT_L(0); PG8_MMA(0, 0, At, B0); PG8_BAR; PG8_SCHED;
;             PG8_LDB(B1, 1, 1); PG8_STAGE(PG8_SB(1, 0), b3, voffB);
;             PG8_WAIT_V(10); PG8_BAR; PG8_WAIT_L(0); PG8_MMA(0, 1, At, B1); PG8_BAR;
	v_mfma_f32_16x16x32_bf16 v[8:11], v[140:143], v[172:175], v[8:11]
	s_setprio 0
	s_add_u32 s54, s26, 0x60000
	s_addc_u32 s55, s27, 0
	s_add_i32 s56, s46, s35
	s_mov_b32 m0, s56
	s_nop 0
	global_load_lds_dwordx4 v194, s[54:55]
	s_add_i32 m0, s56, 0x2000
	s_nop 0
	global_load_lds_dwordx4 v198, s[54:55]
	s_waitcnt vmcnt(10)
	s_barrier
	s_setprio 1
	v_mfma_f32_16x16x32_bf16 v[52:55], v[176:179], v[144:147], v[52:55]
	v_mfma_f32_16x16x32_bf16 v[44:47], v[184:187], v[144:147], v[44:47]
	v_mfma_f32_16x16x32_bf16 v[36:39], v[176:179], v[152:155], v[36:39]
	v_mfma_f32_16x16x32_bf16 v[28:31], v[184:187], v[152:155], v[28:31]
	v_mfma_f32_16x16x32_bf16 v[20:23], v[176:179], v[160:163], v[20:23]
	v_mfma_f32_16x16x32_bf16 v[12:15], v[184:187], v[160:163], v[12:15]
	v_mfma_f32_16x16x32_bf16 v[4:7], v[176:179], v[168:171], v[4:7]
	v_mfma_f32_16x16x32_bf16 v[0:3], v[184:187], v[168:171], v[0:3]
	v_mfma_f32_16x16x32_bf16 v[52:55], v[180:183], v[148:151], v[52:55]
	v_mfma_f32_16x16x32_bf16 v[44:47], v[188:191], v[148:151], v[44:47]
	v_mfma_f32_16x16x32_bf16 v[36:39], v[180:183], v[156:159], v[36:39]
	v_mfma_f32_16x16x32_bf16 v[28:31], v[188:191], v[156:159], v[28:31]
	v_mfma_f32_16x16x32_bf16 v[20:23], v[180:183], v[164:167], v[20:23]
	v_mfma_f32_16x16x32_bf16 v[12:15], v[188:191], v[164:167], v[12:15]
	v_mfma_f32_16x16x32_bf16 v[4:7], v[180:183], v[172:175], v[4:7]
	s_barrier
	v_mfma_f32_16x16x32_bf16 v[0:3], v[188:191], v[172:175], v[0:3]
	s_setprio 0
	s_add_i32 s54, 0, 0x18000
	ds_read_b128 v[128:131], v247 offset:32768
	ds_read_b128 v[132:135], v247 offset:33792
	ds_read_b128 v[136:139], v247 offset:34816
	ds_read_b128 v[140:143], v247 offset:35840
	s_add_u32 s28, s28, 0x60000
	s_addc_u32 s29, s29, 0
	s_mov_b32 m0, s38
	ds_read_b128 v[144:147], v224 offset:32768
	ds_read_b128 v[148:151], v224 offset:33792
	ds_read_b128 v[152:155], v224 offset:34816
	ds_read_b128 v[156:159], v224 offset:35840
	ds_read_b128 v[160:163], v224 offset:36864
	ds_read_b128 v[164:167], v224 offset:37888
	ds_read_b128 v[168:171], v224 offset:38912
	ds_read_b128 v[172:175], v224 offset:39936
	global_load_lds_dwordx4 v192, s[28:29]
	s_mov_b32 m0, s39
	s_nop 0
	global_load_lds_dwordx4 v196, s[28:29]
	s_waitcnt lgkmcnt(8)
	s_waitcnt vmcnt(10)
	s_barrier
	s_waitcnt lgkmcnt(0)
	s_setprio 1
	s_waitcnt lgkmcnt(0)
	v_mfma_f32_16x16x32_bf16 v[124:127], v[128:131], v[144:147], v[124:127]
	v_mfma_f32_16x16x32_bf16 v[120:123], v[136:139], v[144:147], v[120:123]
	v_mfma_f32_16x16x32_bf16 v[116:119], v[128:131], v[152:155], v[116:119]
	v_mfma_f32_16x16x32_bf16 v[104:107], v[136:139], v[152:155], v[104:107]
	v_mfma_f32_16x16x32_bf16 v[96:99], v[128:131], v[160:163], v[96:99]
	v_mfma_f32_16x16x32_bf16 v[88:91], v[136:139], v[160:163], v[88:91]
	v_mfma_f32_16x16x32_bf16 v[80:83], v[128:131], v[168:171], v[80:83]
	v_mfma_f32_16x16x32_bf16 v[72:75], v[136:139], v[168:171], v[72:75]
	v_mfma_f32_16x16x32_bf16 v[124:127], v[132:135], v[148:151], v[124:127]
	v_mfma_f32_16x16x32_bf16 v[120:123], v[140:143], v[148:151], v[120:123]
	v_mfma_f32_16x16x32_bf16 v[116:119], v[132:135], v[156:159], v[116:119]
	v_mfma_f32_16x16x32_bf16 v[104:107], v[140:143], v[156:159], v[104:107]
	v_mfma_f32_16x16x32_bf16 v[96:99], v[132:135], v[164:167], v[96:99]
	v_mfma_f32_16x16x32_bf16 v[88:91], v[140:143], v[164:167], v[88:91]
	v_mfma_f32_16x16x32_bf16 v[80:83], v[132:135], v[172:175], v[80:83]
	s_barrier
	v_mfma_f32_16x16x32_bf16 v[72:75], v[140:143], v[172:175], v[72:75]
	s_setprio 0
	s_add_i32 s28, 0, 0x1c000
	s_add_i32 s29, s54, s35
	s_mov_b32 m0, s29
	ds_read_b128 v[176:179], v247 offset:49152
	ds_read_b128 v[180:183], v247 offset:50176
	ds_read_b128 v[184:187], v247 offset:51200
	ds_read_b128 v[188:191], v247 offset:52224
	global_load_lds_dwordx4 v194, s[98:99]
	s_add_i32 m0, s29, 0x2000
	s_nop 0
	global_load_lds_dwordx4 v198, s[98:99]
	s_waitcnt vmcnt(10)
	s_barrier
; #define PG8_STAGE(bufoff, gbase, voff) do { _Pragma("unroll") for (int _i = 0; _i < 2; ++_i) \
;         __builtin_amdgcn_global_load_lds((const unsigned*)((const char*)(gbase) + (voff)[_i]), (LAS unsigned*)(lds + (bufoff) + ldsw + _i * 8192), 16, 0, 0); } while (0)
; #define PG8_LDA(dst, b, h) do { _Pragma("unroll") for (int m = 0; m < 4; ++m) _Pragma("unroll") for (int k = 0; k < 2; ++k) dst[m][k] = *(const LAS bf16x8*)(lds + PG8_SA(b, h) + aoff + m * 2048 + k * 1024); } while (0)
; #define PG8_MMA(ai, bj, At, Bt) do { __builtin_amdgcn_s_setprio(1); _Pragma("unroll") for (int m = 0; m < 4; ++m) _Pragma("unroll") for (int n = 0; n < 2; ++n) _Pragma("unroll") for (int k = 0; k < 2; ++k) \
;         acc[ai][bj][m][n] = __builtin_amdgcn_mfma_f32_16x16x32_bf16(Bt[n][k], At[m][k], acc[ai][bj][m][n], 0, 0, 0); __builtin_amdgcn_s_setprio(0); } while (0)
; #define PG8_WAIT_V(n) asm volatile("s_waitcnt vmcnt(" #n ")" ::: "memory")
; #define PG8_WAIT_L(n) asm volatile("s_waitcnt lgkmcnt(" #n ")" ::: "memory")
; #define PG8_BAR __builtin_amdgcn_s_barrier()
; #define PG8_SCHED __builtin_amdgcn_sched_barrier(0)
; template <class Epi>
; __device__ __forceinline__ void gemm_phase(ldsp lds, const Gemm g, const StaticOrder& S, const Epi& E) {
;     ...
;             PG8_WAIT_V(10); PG8_BAR; PG8_WAIT_L(0); PG8_MMA(0, 1, At, B1); PG8_BAR;
;             PG8_LDA(At, 1, 1); PG8_STAGE(PG8_SA(1, 0), a3, voffA);
;             PG8_WAIT_V(10); PG8_BAR; PG8_WAIT_L(0); PG8_MMA(1, 0, At, B0); PG8_BAR; PG8_SCHED;
;             PG8_STAGE(PG8_SB(1, 1), b3 + hstep, voffB);
;             PG8_WAIT_V(10); PG8_BAR; PG8_MMA(1, 1, At, B1); PG8_BAR;
	s_waitcnt lgkmcnt(0)
	s_setprio 1
	s_waitcnt lgkmcnt(0)
	v_mfma_f32_16x16x32_bf16 v[112:115], v[176:179], v[144:147], v[112:115]
	v_mfma_f32_16x16x32_bf16 v[108:111], v[184:187], v[144:147], v[108:111]
	v_mfma_f32_16x16x32_bf16 v[100:103], v[176:179], v[152:155], v[100:103]
	v_mfma_f32_16x16x32_bf16 v[92:95], v[184:187], v[152:155], v[92:95]
	v_mfma_f32_16x16x32_bf16 v[84:87], v[176:179], v[160:163], v[84:87]
	v_mfma_f32_16x16x32_bf16 v[76:79], v[184:187], v[160:163], v[76:79]
	v_mfma_f32_16x16x32_bf16 v[68:71], v[176:179], v[168:171], v[68:71]
	v_mfma_f32_16x16x32_bf16 v[64:67], v[184:187], v[168:171], v[64:67]
	v_mfma_f32_16x16x32_bf16 v[112:115], v[180:183], v[148:151], v[112:115]
	v_mfma_f32_16x16x32_bf16 v[108:111], v[188:191], v[148:151], v[108:111]
	v_mfma_f32_16x16x32_bf16 v[100:103], v[180:183], v[156:159], v[100:103]
	v_mfma_f32_16x16x32_bf16 v[92:95], v[188:191], v[156:159], v[92:95]
	v_mfma_f32_16x16x32_bf16 v[84:87], v[180:183], v[164:167], v[84:87]
	v_mfma_f32_16x16x32_bf16 v[76:79], v[188:191], v[164:167], v[76:79]
	v_mfma_f32_16x16x32_bf16 v[68:71], v[180:183], v[172:175], v[68:71]
	s_barrier
	v_mfma_f32_16x16x32_bf16 v[64:67], v[188:191], v[172:175], v[64:67]
	s_setprio 0
	s_mov_b32 m0, s41
	ds_read_b128 v[144:147], v224 offset:49152
	ds_read_b128 v[148:151], v224 offset:50176
	ds_read_b128 v[152:155], v224 offset:51200
	ds_read_b128 v[156:159], v224 offset:52224
	ds_read_b128 v[160:163], v224 offset:53248
	ds_read_b128 v[164:167], v224 offset:54272
	ds_read_b128 v[168:171], v224 offset:55296
	ds_read_b128 v[172:175], v224 offset:56320
	global_load_lds_dwordx4 v192, s[100:101]
	s_mov_b32 m0, s42
	s_nop 0
	global_load_lds_dwordx4 v196, s[100:101]
	s_waitcnt vmcnt(10)
	s_barrier
	s_waitcnt lgkmcnt(0)
	s_setprio 1
	s_waitcnt lgkmcnt(0)
	v_mfma_f32_16x16x32_bf16 v[60:63], v[128:131], v[144:147], v[60:63]
	v_mfma_f32_16x16x32_bf16 v[56:59], v[136:139], v[144:147], v[56:59]
	v_mfma_f32_16x16x32_bf16 v[48:51], v[128:131], v[152:155], v[48:51]
	v_mfma_f32_16x16x32_bf16 v[40:43], v[136:139], v[152:155], v[40:43]
	v_mfma_f32_16x16x32_bf16 v[32:35], v[128:131], v[160:163], v[32:35]
	v_mfma_f32_16x16x32_bf16 v[24:27], v[136:139], v[160:163], v[24:27]
	v_mfma_f32_16x16x32_bf16 v[16:19], v[128:131], v[168:171], v[16:19]
	v_mfma_f32_16x16x32_bf16 v[8:11], v[136:139], v[168:171], v[8:11]
	v_mfma_f32_16x16x32_bf16 v[60:63], v[132:135], v[148:151], v[60:63]
	v_mfma_f32_16x16x32_bf16 v[56:59], v[140:143], v[148:151], v[56:59]
	v_mfma_f32_16x16x32_bf16 v[48:51], v[132:135], v[156:159], v[48:51]
	v_mfma_f32_16x16x32_bf16 v[40:43], v[140:143], v[156:159], v[40:43]
	v_mfma_f32_16x16x32_bf16 v[32:35], v[132:135], v[164:167], v[32:35]
	v_mfma_f32_16x16x32_bf16 v[24:27], v[140:143], v[164:167], v[24:27]
	v_mfma_f32_16x16x32_bf16 v[16:19], v[132:135], v[172:175], v[16:19]
	s_barrier
	v_mfma_f32_16x16x32_bf16 v[8:11], v[140:143], v[172:175], v[8:11]
	s_setprio 0
	s_add_u32 s26, s26, 0x60080
	s_addc_u32 s27, s27, 0
	s_add_i32 s28, s28, s35
	s_mov_b32 m0, s28
	s_nop 0
	global_load_lds_dwordx4 v194, s[26:27]
	s_add_i32 m0, s28, 0x2000
	s_nop 0
	global_load_lds_dwordx4 v198, s[26:27]
	s_waitcnt vmcnt(10)
	s_barrier
	s_setprio 1
	v_mfma_f32_16x16x32_bf16 v[52:55], v[176:179], v[144:147], v[52:55]
	v_mfma_f32_16x16x32_bf16 v[44:47], v[184:187], v[144:147], v[44:47]
	v_mfma_f32_16x16x32_bf16 v[36:39], v[176:179], v[152:155], v[36:39]
	v_mfma_f32_16x16x32_bf16 v[28:31], v[184:187], v[152:155], v[28:31]
	v_mfma_f32_16x16x32_bf16 v[20:23], v[176:179], v[160:163], v[20:23]
	v_mfma_f32_16x16x32_bf16 v[12:15], v[184:187], v[160:163], v[12:15]
	v_mfma_f32_16x16x32_bf16 v[4:7], v[176:179], v[168:171], v[4:7]
	v_mfma_f32_16x16x32_bf16 v[0:3], v[184:187], v[168:171], v[0:3]
	v_mfma_f32_16x16x32_bf16 v[52:55], v[180:183], v[148:151], v[52:55]
	v_mfma_f32_16x16x32_bf16 v[44:47], v[188:191], v[148:151], v[44:47]
	v_mfma_f32_16x16x32_bf16 v[36:39], v[180:183], v[156:159], v[36:39]
	v_mfma_f32_16x16x32_bf16 v[28:31], v[188:191], v[156:159], v[28:31]
	v_mfma_f32_16x16x32_bf16 v[20:23], v[180:183], v[164:167], v[20:23]
	v_mfma_f32_16x16x32_bf16 v[12:15], v[188:191], v[164:167], v[12:15]
	v_mfma_f32_16x16x32_bf16 v[4:7], v[180:183], v[172:175], v[4:7]
	s_barrier
	v_mfma_f32_16x16x32_bf16 v[0:3], v[188:191], v[172:175], v[0:3]
	s_setprio 0
	s_add_i32 s53, s53, 2
	s_add_u32 s24, s24, 0x100
	s_addc_u32 s25, s25, 0
	s_cmp_gt_u32 s53, 21
	s_cbranch_scc1 .LBB0_642

; #define PG8_STAGE(bufoff, gbase, voff) do { _Pragma("unroll") for (int _i = 0; _i < 2; ++_i) \
;         __builtin_amdgcn_global_load_lds((const unsigned*)((const char*)(gbase) + (voff)[_i]), (LAS unsigned*)(lds + (bufoff) + ldsw + _i * 8192), 16, 0, 0); } while (0)
; #define PG8_WAIT_V(n) asm volatile("s_waitcnt vmcnt(" #n ")" ::: "memory")
; #define PG8_BAR __builtin_amdgcn_s_barrier()
; template <class Epi>
; __device__ __forceinline__ void gemm_phase(ldsp lds, const Gemm g, const StaticOrder& S, const Epi& E) {
;     ...
;     const int aoff = lds_byte(wr * 64 + fr, fq * 8), boff = lds_byte(wc * 32 + fr, fq * 8);
;     ...
;     PG8_WAIT_V(4); PG8_BAR;
;     PG8_STAGE(PG8_SB(1, 0), cB + kstep, voffB); PG8_STAGE(PG8_SA(1, 0), cA + kstep, voffA); PG8_STAGE(PG8_SB(1, 1), cB + hstep + kstep, voffB);
;     PG8_WAIT_V(6); PG8_BAR;
.LBB0_724:
	s_lshl_b32 s3, s3, 5
	s_mov_b64 s[8:9], 0x80
	s_and_b32 s11, s3, 0x60
	s_add_i32 m0, s21, 0x18000
	v_lshl_add_u64 v[6:7], v[6:7], 0, s[8:9]
	s_lshl_b32 s10, s2, 13
	s_lshl_b32 s3, s11, 7
	s_waitcnt vmcnt(4)
	s_barrier
	global_load_lds_dwordx4 v[6:7], off
	v_lshl_add_u64 v[4:5], v[4:5], 0, s[8:9]
	s_add_i32 m0, s21, 0x1a000
	s_add_i32 s35, s21, 0x8000
	s_add_i32 s36, s21, 0xa000
	global_load_lds_dwordx4 v[4:5], off
	v_lshl_add_u64 v[2:3], v[2:3], 0, s[8:9]
	s_mov_b32 m0, s35
	s_add_u32 s4, s24, 0x80080
	global_load_lds_dwordx4 v[2:3], off
	v_lshl_add_u64 v[0:1], v[0:1], 0, s[8:9]
	s_mov_b32 m0, s36
	s_addc_u32 s5, s25, 0
	global_load_lds_dwordx4 v[0:1], off
	s_add_i32 m0, s21, 0x1c000
	v_lshl_add_u64 v[0:1], s[4:5], 0, v[178:179]
	global_load_lds_dwordx4 v[0:1], off
	v_lshl_add_u64 v[0:1], s[4:5], 0, v[182:183]
	s_add_i32 m0, s21, 0x1e000
	v_lshlrev_b32_e32 v3, 2, v220
	global_load_lds_dwordx4 v[0:1], off
	v_bfe_u32 v0, v220, 4, 2
	v_and_b32_e32 v1, 15, v220
	v_lshl_or_b32 v208, s2, 6, v1
	v_lshlrev_b32_e32 v2, 4, v0
	v_lshlrev_b32_e32 v4, 6, v220
	s_movk_i32 s2, 0x3c0
	v_lshl_or_b32 v1, v1, 6, v2
	v_and_b32_e32 v3, 32, v3
	v_and_or_b32 v2, v4, s2, v2
	v_bitop3_b32 v209, s3, v2, v3 bitop3:0xf6
	v_add_u32_e32 v247, 0x10000, v209
	v_cmp_eq_u32_e64 s[2:3], 0, v0
	v_lshl_or_b32 v210, v0, 3, s11
	v_lshlrev_b32_e32 v0, 9, v220
	v_and_b32_e32 v0, 0x70000, v0
	v_lshlrev_b32_e32 v2, 12, v10
	v_or3_b32 v0, v8, v0, v2
	v_add_u32_e32 v184, v0, v9
	v_lshlrev_b32_e32 v0, 5, v11
	v_and_b32_e32 v0, 0xf0000, v0
	s_waitcnt vmcnt(6)
	v_or3_b32 v0, v8, v0, v2
	v_bitop3_b32 v1, v1, s10, v3 bitop3:0xde
	v_add_u32_e32 v186, v0, v9
	s_add_i32 s40, 0, 0x10000
	s_add_i32 s41, 0, 0x14000
	v_mbcnt_lo_u32_b32 v0, -1, 0
	s_ashr_i32 s37, s62, 31
	s_mov_b32 s38, s62
	s_ashr_i32 s39, s96, 31
	v_mov_b32_e32 v185, v179
	v_mov_b32_e32 v187, v179
	v_mov_b64_e32 v[188:189], 0x400
	v_mov_b64_e32 v[190:191], 0x3ff
	v_add_u32_e32 v211, s40, v209
	v_add_u32_e32 v212, 0, v1
	v_add_u32_e32 v213, s41, v209
	v_mbcnt_hi_u32_b32 v214, -1, v0
	s_mov_b32 s42, 0x4b800000
	s_barrier
	s_branch .LBB0_726

; #define PG8_STAGE(bufoff, gbase, voff) do { _Pragma("unroll") for (int _i = 0; _i < 2; ++_i) \
;         __builtin_amdgcn_global_load_lds((const unsigned*)((const char*)(gbase) + (voff)[_i]), (LAS unsigned*)(lds + (bufoff) + ldsw + _i * 8192), 16, 0, 0); } while (0)
; #define PG8_LDA(dst, b, h) do { _Pragma("unroll") for (int m = 0; m < 4; ++m) _Pragma("unroll") for (int k = 0; k < 2; ++k) dst[m][k] = *(const LAS bf16x8*)(lds + PG8_SA(b, h) + aoff + m * 2048 + k * 1024); } while (0)
; #define PG8_LDB(dst, b, h) do { _Pragma("unroll") for (int n = 0; n < 2; ++n) _Pragma("unroll") for (int k = 0; k < 2; ++k) dst[n][k] = *(const LAS bf16x8*)(lds + PG8_SB(b, h) + boff + n * 2048 + k * 1024); } while (0)
; #define PG8_MMA(ai, bj, At, Bt) do { __builtin_amdgcn_s_setprio(1); _Pragma("unroll") for (int m = 0; m < 4; ++m) _Pragma("unroll") for (int n = 0; n < 2; ++n) _Pragma("unroll") for (int k = 0; k < 2; ++k) \
;         acc[ai][bj][m][n] = __builtin_amdgcn_mfma_f32_16x16x32_bf16(Bt[n][k], At[m][k], acc[ai][bj][m][n], 0, 0, 0); __builtin_amdgcn_s_setprio(0); } while (0)
; template <class Epi>
; __device__ __forceinline__ void gemm_phase(ldsp lds, const Gemm g, const StaticOrder& S, const Epi& E) {
;     ...
;             const bool last = (t == nt - 2);
;             const char* a1 = cA + (size_t)(t + 1) * kstep;
;             const char* a2 = last ? nA : cA + (size_t)(t + 2) * kstep; const char* b2 = last ? nB : cB + (size_t)(t + 2) * kstep;
;             const char* a3 = a2 + kstep; const char* b3 = b2 + kstep;
;             if constexpr (Epi::NPRE > 0) { if (last) E.pre(pre, cur, wr, fr); }
;             if constexpr (Epi::MID_T > 0) { if (t == Epi::MID_T) E.mid(acc, cur, wr, wc, fr, fq); }
;             PG8_LDB(B0, 0, 0); PG8_SCHED; PG8_LDA(At, 0, 0); PG8_STAGE(PG8_SA(1, 1), a1 + hstep, voffA);
;             PG8_WAIT_L(8); PG8_WAIT_V(10); PG8_BAR; PG8_WAIT_L(0); PG8_MMA(0, 0, At, B0); PG8_BAR; PG8_SCHED;
;             PG8_LDB(B1, 0, 1); PG8_STAGE(PG8_SB(0, 0), b2, voffB);
;             PG8_WAIT_V(10); PG8_BAR; PG8_WAIT_L(0); PG8_MMA(0, 1, At, B1); PG8_BAR;
;             PG8_LDA(At, 0, 1); PG8_STAGE(PG8_SA(0, 0), a2, voffA);
;             PG8_WAIT_V(10); PG8_BAR; PG8_WAIT_L(0); PG8_MMA(1, 0, At, B0); PG8_BAR; PG8_SCHED;
;             PG8_STAGE(PG8_SB(0, 1), b2 + hstep, voffB);
;             PG8_WAIT_V(10); PG8_BAR; PG8_MMA(1, 1, At, B1); PG8_BAR;
.LBB0_733:
	ds_read_b128 v[128:131], v211
	ds_read_b128 v[132:135], v211 offset:1024
	ds_read_b128 v[136:139], v211 offset:2048
	ds_read_b128 v[140:143], v211 offset:3072
	s_add_u32 s24, s22, 0xfff80080
	s_addc_u32 s25, s23, -1
	s_cmp_eq_u32 s46, 28
	s_cselect_b32 s27, s13, s25
	s_cselect_b32 s26, s19, s24
	s_cselect_b32 s25, s11, s45
	s_cselect_b32 s24, s43, s44
	s_add_i32 m0, s21, 0xc000
	ds_read_b128 v[144:147], v212
	ds_read_b128 v[148:151], v212 offset:1024
	ds_read_b128 v[152:155], v212 offset:2048
	ds_read_b128 v[156:159], v212 offset:3072
	ds_read_b128 v[160:163], v212 offset:4096
	ds_read_b128 v[164:167], v212 offset:5120
	ds_read_b128 v[168:171], v212 offset:6144
	ds_read_b128 v[172:175], v212 offset:7168
	global_load_lds_dwordx4 v184, s[22:23]
	s_add_i32 m0, s21, 0xe000
	s_nop 0
	global_load_lds_dwordx4 v186, s[22:23]
	s_waitcnt lgkmcnt(8)
	s_waitcnt vmcnt(10)
	s_barrier
	s_waitcnt lgkmcnt(0)
	s_setprio 1
	s_waitcnt lgkmcnt(0)
	v_mfma_f32_16x16x32_bf16 v[124:127], v[128:131], v[144:147], v[124:127]
	v_mfma_f32_16x16x32_bf16 v[120:123], v[136:139], v[144:147], v[120:123]
	v_mfma_f32_16x16x32_bf16 v[108:111], v[128:131], v[152:155], v[108:111]
	v_mfma_f32_16x16x32_bf16 v[104:107], v[136:139], v[152:155], v[104:107]
	v_mfma_f32_16x16x32_bf16 v[92:95], v[128:131], v[160:163], v[92:95]
	v_mfma_f32_16x16x32_bf16 v[88:91], v[136:139], v[160:163], v[88:91]
	v_mfma_f32_16x16x32_bf16 v[76:79], v[128:131], v[168:171], v[76:79]
	v_mfma_f32_16x16x32_bf16 v[72:75], v[136:139], v[168:171], v[72:75]
	v_mfma_f32_16x16x32_bf16 v[124:127], v[132:135], v[148:151], v[124:127]
	v_mfma_f32_16x16x32_bf16 v[120:123], v[140:143], v[148:151], v[120:123]
	v_mfma_f32_16x16x32_bf16 v[108:111], v[132:135], v[156:159], v[108:111]
	v_mfma_f32_16x16x32_bf16 v[104:107], v[140:143], v[156:159], v[104:107]
	v_mfma_f32_16x16x32_bf16 v[92:95], v[132:135], v[164:167], v[92:95]
	v_mfma_f32_16x16x32_bf16 v[88:91], v[140:143], v[164:167], v[88:91]
	v_mfma_f32_16x16x32_bf16 v[76:79], v[132:135], v[172:175], v[76:79]
	s_barrier
	v_mfma_f32_16x16x32_bf16 v[72:75], v[140:143], v[172:175], v[72:75]
	s_setprio 0
	s_add_i32 s47, s40, s29
	s_add_u32 s98, s24, 0x80
	s_addc_u32 s99, s25, 0
	s_mov_b32 m0, s47
	ds_read_b128 v[192:195], v213
	ds_read_b128 v[196:199], v213 offset:1024
	ds_read_b128 v[200:203], v213 offset:2048
	ds_read_b128 v[204:207], v213 offset:3072
	global_load_lds_dwordx4 v178, s[24:25]
	s_add_i32 m0, s47, 0x2000
	s_nop 0
	global_load_lds_dwordx4 v182, s[24:25]
	s_waitcnt vmcnt(10)
	s_barrier
	s_waitcnt lgkmcnt(0)
	s_setprio 1
	s_waitcnt lgkmcnt(0)
	v_mfma_f32_16x16x32_bf16 v[116:119], v[192:195], v[144:147], v[116:119]
	v_mfma_f32_16x16x32_bf16 v[112:115], v[200:203], v[144:147], v[112:115]
	v_mfma_f32_16x16x32_bf16 v[100:103], v[192:195], v[152:155], v[100:103]
	v_mfma_f32_16x16x32_bf16 v[96:99], v[200:203], v[152:155], v[96:99]
	v_mfma_f32_16x16x32_bf16 v[84:87], v[192:195], v[160:163], v[84:87]
	v_mfma_f32_16x16x32_bf16 v[80:83], v[200:203], v[160:163], v[80:83]
	v_mfma_f32_16x16x32_bf16 v[68:71], v[192:195], v[168:171], v[68:71]
	v_mfma_f32_16x16x32_bf16 v[64:67], v[200:203], v[168:171], v[64:67]
	v_mfma_f32_16x16x32_bf16 v[116:119], v[196:199], v[148:151], v[116:119]
	v_mfma_f32_16x16x32_bf16 v[112:115], v[204:207], v[148:151], v[112:115]
	v_mfma_f32_16x16x32_bf16 v[100:103], v[196:199], v[156:159], v[100:103]
	v_mfma_f32_16x16x32_bf16 v[96:99], v[204:207], v[156:159], v[96:99]
	v_mfma_f32_16x16x32_bf16 v[84:87], v[196:199], v[164:167], v[84:87]
	v_mfma_f32_16x16x32_bf16 v[80:83], v[204:207], v[164:167], v[80:83]
	v_mfma_f32_16x16x32_bf16 v[68:71], v[196:199], v[172:175], v[68:71]
	s_barrier
	v_mfma_f32_16x16x32_bf16 v[64:67], v[204:207], v[172:175], v[64:67]
	s_setprio 0
	s_mov_b32 m0, s21
	s_add_u32 s100, s26, 0x80
	s_addc_u32 s101, s27, 0
	ds_read_b128 v[144:147], v212 offset:16384
	ds_read_b128 v[148:151], v212 offset:17408
	ds_read_b128 v[152:155], v212 offset:18432
	ds_read_b128 v[156:159], v212 offset:19456
	ds_read_b128 v[160:163], v212 offset:20480
	ds_read_b128 v[164:167], v212 offset:21504
	ds_read_b128 v[168:171], v212 offset:22528
	ds_read_b128 v[172:175], v212 offset:23552
	global_load_lds_dwordx4 v176, s[26:27]
	s_mov_b32 m0, s30
	s_nop 0
	global_load_lds_dwordx4 v180, s[26:27]
	s_waitcnt vmcnt(10)
	s_barrier
	s_waitcnt lgkmcnt(0)
	s_setprio 1
	s_waitcnt lgkmcnt(0)
	v_mfma_f32_16x16x32_bf16 v[60:63], v[128:131], v[144:147], v[60:63]
	v_mfma_f32_16x16x32_bf16 v[56:59], v[136:139], v[144:147], v[56:59]
	v_mfma_f32_16x16x32_bf16 v[44:47], v[128:131], v[152:155], v[44:47]
	v_mfma_f32_16x16x32_bf16 v[40:43], v[136:139], v[152:155], v[40:43]
	v_mfma_f32_16x16x32_bf16 v[28:31], v[128:131], v[160:163], v[28:31]
	v_mfma_f32_16x16x32_bf16 v[24:27], v[136:139], v[160:163], v[24:27]
	v_mfma_f32_16x16x32_bf16 v[12:15], v[128:131], v[168:171], v[12:15]
	v_mfma_f32_16x16x32_bf16 v[8:11], v[136:139], v[168:171], v[8:11]
	v_mfma_f32_16x16x32_bf16 v[60:63], v[132:135], v[148:151], v[60:63]
	v_mfma_f32_16x16x32_bf16 v[56:59], v[140:143], v[148:151], v[56:59]
	v_mfma_f32_16x16x32_bf16 v[44:47], v[132:135], v[156:159], v[44:47]
	v_mfma_f32_16x16x32_bf16 v[40:43], v[140:143], v[156:159], v[40:43]
	v_mfma_f32_16x16x32_bf16 v[28:31], v[132:135], v[164:167], v[28:31]
	v_mfma_f32_16x16x32_bf16 v[24:27], v[140:143], v[164:167], v[24:27]
	v_mfma_f32_16x16x32_bf16 v[12:15], v[132:135], v[172:175], v[12:15]
	s_barrier
	v_mfma_f32_16x16x32_bf16 v[8:11], v[140:143], v[172:175], v[8:11]
	s_setprio 0
	s_add_u32 s50, s24, 0x80000
	s_addc_u32 s51, s25, 0
	s_add_i32 s47, s41, s29
	s_mov_b32 m0, s47
	s_nop 0
	global_load_lds_dwordx4 v178, s[50:51]
	s_add_i32 m0, s47, 0x2000
	s_nop 0
	global_load_lds_dwordx4 v182, s[50:51]
	s_waitcnt vmcnt(10)
	s_barrier
; #define PG8_STAGE(bufoff, gbase, voff) do { _Pragma("unroll") for (int _i = 0; _i < 2; ++_i) \
;         __builtin_amdgcn_global_load_lds((const unsigned*)((const char*)(gbase) + (voff)[_i]), (LAS unsigned*)(lds + (bufoff) + ldsw + _i * 8192), 16, 0, 0); } while (0)
; #define PG8_LDA(dst, b, h) do { _Pragma("unroll") for (int m = 0; m < 4; ++m) _Pragma("unroll") for (int k = 0; k < 2; ++k) dst[m][k] = *(const LAS bf16x8*)(lds + PG8_SA(b, h) + aoff + m * 2048 + k * 1024); } while (0)
; #define PG8_LDB(dst, b, h) do { _Pragma("unroll") for (int n = 0; n < 2; ++n) _Pragma("unroll") for (int k = 0; k < 2; ++k) dst[n][k] = *(const LAS bf16x8*)(lds + PG8_SB(b, h) + boff + n * 2048 + k * 1024); } while (0)
; #define PG8_MMA(ai, bj, At, Bt) do { __builtin_amdgcn_s_setprio(1); _Pragma("unroll") for (int m = 0; m < 4; ++m) _Pragma("unroll") for (int n = 0; n < 2; ++n) _Pragma("unroll") for (int k = 0; k < 2; ++k) \
;         acc[ai][bj][m][n] = __builtin_amdgcn_mfma_f32_16x16x32_bf16(Bt[n][k], At[m][k], acc[ai][bj][m][n], 0, 0, 0); __builtin_amdgcn_s_setprio(0); } while (0)
; #define PG8_WAIT_V(n) asm volatile("s_waitcnt vmcnt(" #n ")" ::: "memory")
; #define PG8_WAIT_L(n) asm volatile("s_waitcnt lgkmcnt(" #n ")" ::: "memory")
; #define PG8_BAR __builtin_amdgcn_s_barrier()
; #define PG8_SCHED __builtin_amdgcn_sched_barrier(0)
; template <class Epi>
; __device__ __forceinline__ void gemm_phase(ldsp lds, const Gemm g, const StaticOrder& S, const Epi& E) {
;     ...
;             PG8_WAIT_V(10); PG8_BAR; PG8_MMA(1, 1, At, B1); PG8_BAR;
;             PG8_LDB(B0, 1, 0); PG8_SCHED; PG8_LDA(At, 1, 0); PG8_STAGE(PG8_SA(0, 1), a2 + hstep, voffA);
;             PG8_WAIT_L(8); PG8_WAIT_V(10); PG8_BAR; PG8_WAIT_L(0); PG8_MMA(0, 0, At, B0); PG8_BAR; PG8_SCHED;
;             PG8_LDB(B1, 1, 1); PG8_STAGE(PG8_SB(1, 0), b3, voffB);
;             PG8_WAIT_V(10); PG8_BAR; PG8_WAIT_L(0); PG8_MMA(0, 1, At, B1); PG8_BAR;
;             PG8_LDA(At, 1, 1); PG8_STAGE(PG8_SA(1, 0), a3, voffA);
;             PG8_WAIT_V(10); PG8_BAR; PG8_WAIT_L(0); PG8_MMA(1, 0, At, B0); PG8_BAR; PG8_SCHED;
	s_setprio 1
	v_mfma_f32_16x16x32_bf16 v[52:55], v[192:195], v[144:147], v[52:55]
	v_mfma_f32_16x16x32_bf16 v[48:51], v[200:203], v[144:147], v[48:51]
	v_mfma_f32_16x16x32_bf16 v[36:39], v[192:195], v[152:155], v[36:39]
	v_mfma_f32_16x16x32_bf16 v[32:35], v[200:203], v[152:155], v[32:35]
	v_mfma_f32_16x16x32_bf16 v[20:23], v[192:195], v[160:163], v[20:23]
	v_mfma_f32_16x16x32_bf16 v[16:19], v[200:203], v[160:163], v[16:19]
	v_mfma_f32_16x16x32_bf16 v[4:7], v[192:195], v[168:171], v[4:7]
	v_mfma_f32_16x16x32_bf16 v[0:3], v[200:203], v[168:171], v[0:3]
	v_mfma_f32_16x16x32_bf16 v[52:55], v[196:199], v[148:151], v[52:55]
	v_mfma_f32_16x16x32_bf16 v[48:51], v[204:207], v[148:151], v[48:51]
	v_mfma_f32_16x16x32_bf16 v[36:39], v[196:199], v[156:159], v[36:39]
	v_mfma_f32_16x16x32_bf16 v[32:35], v[204:207], v[156:159], v[32:35]
	v_mfma_f32_16x16x32_bf16 v[20:23], v[196:199], v[164:167], v[20:23]
	v_mfma_f32_16x16x32_bf16 v[16:19], v[204:207], v[164:167], v[16:19]
	v_mfma_f32_16x16x32_bf16 v[4:7], v[196:199], v[172:175], v[4:7]
	s_barrier
	v_mfma_f32_16x16x32_bf16 v[0:3], v[204:207], v[172:175], v[0:3]
	s_setprio 0
	s_add_i32 s47, 0, 0x18000
	ds_read_b128 v[128:131], v247 offset:32768
	ds_read_b128 v[132:135], v247 offset:33792
	ds_read_b128 v[136:139], v247 offset:34816
	ds_read_b128 v[140:143], v247 offset:35840
	s_add_u32 s26, s26, 0x80000
	s_addc_u32 s27, s27, 0
	s_mov_b32 m0, s31
	ds_read_b128 v[144:147], v212 offset:32768
	ds_read_b128 v[148:151], v212 offset:33792
	ds_read_b128 v[152:155], v212 offset:34816
	ds_read_b128 v[156:159], v212 offset:35840
	ds_read_b128 v[160:163], v212 offset:36864
	ds_read_b128 v[164:167], v212 offset:37888
	ds_read_b128 v[168:171], v212 offset:38912
	ds_read_b128 v[172:175], v212 offset:39936
	global_load_lds_dwordx4 v176, s[26:27]
	s_mov_b32 m0, s33
	s_nop 0
	global_load_lds_dwordx4 v180, s[26:27]
	s_waitcnt lgkmcnt(8)
	s_waitcnt vmcnt(10)
	s_barrier
	s_waitcnt lgkmcnt(0)
	s_setprio 1
	s_waitcnt lgkmcnt(0)
	v_mfma_f32_16x16x32_bf16 v[124:127], v[128:131], v[144:147], v[124:127]
	v_mfma_f32_16x16x32_bf16 v[120:123], v[136:139], v[144:147], v[120:123]
	v_mfma_f32_16x16x32_bf16 v[108:111], v[128:131], v[152:155], v[108:111]
	v_mfma_f32_16x16x32_bf16 v[104:107], v[136:139], v[152:155], v[104:107]
	v_mfma_f32_16x16x32_bf16 v[92:95], v[128:131], v[160:163], v[92:95]
	v_mfma_f32_16x16x32_bf16 v[88:91], v[136:139], v[160:163], v[88:91]
	v_mfma_f32_16x16x32_bf16 v[76:79], v[128:131], v[168:171], v[76:79]
	v_mfma_f32_16x16x32_bf16 v[72:75], v[136:139], v[168:171], v[72:75]
	v_mfma_f32_16x16x32_bf16 v[124:127], v[132:135], v[148:151], v[124:127]
	v_mfma_f32_16x16x32_bf16 v[120:123], v[140:143], v[148:151], v[120:123]
	v_mfma_f32_16x16x32_bf16 v[108:111], v[132:135], v[156:159], v[108:111]
	v_mfma_f32_16x16x32_bf16 v[104:107], v[140:143], v[156:159], v[104:107]
	v_mfma_f32_16x16x32_bf16 v[92:95], v[132:135], v[164:167], v[92:95]
	v_mfma_f32_16x16x32_bf16 v[88:91], v[140:143], v[164:167], v[88:91]
	v_mfma_f32_16x16x32_bf16 v[76:79], v[132:135], v[172:175], v[76:79]
	s_barrier
	v_mfma_f32_16x16x32_bf16 v[72:75], v[140:143], v[172:175], v[72:75]
	s_setprio 0
	s_add_i32 s26, 0, 0x1c000
	s_add_i32 s27, s47, s29
	s_mov_b32 m0, s27
	ds_read_b128 v[192:195], v247 offset:49152
	ds_read_b128 v[196:199], v247 offset:50176
	ds_read_b128 v[200:203], v247 offset:51200
	ds_read_b128 v[204:207], v247 offset:52224
	global_load_lds_dwordx4 v178, s[98:99]
	s_add_i32 m0, s27, 0x2000
	s_nop 0
	global_load_lds_dwordx4 v182, s[98:99]
	s_waitcnt vmcnt(10)
	s_barrier
	s_waitcnt lgkmcnt(0)
	s_setprio 1
	s_waitcnt lgkmcnt(0)
	v_mfma_f32_16x16x32_bf16 v[116:119], v[192:195], v[144:147], v[116:119]
	v_mfma_f32_16x16x32_bf16 v[112:115], v[200:203], v[144:147], v[112:115]
	v_mfma_f32_16x16x32_bf16 v[100:103], v[192:195], v[152:155], v[100:103]
	v_mfma_f32_16x16x32_bf16 v[96:99], v[200:203], v[152:155], v[96:99]
	v_mfma_f32_16x16x32_bf16 v[84:87], v[192:195], v[160:163], v[84:87]
	v_mfma_f32_16x16x32_bf16 v[80:83], v[200:203], v[160:163], v[80:83]
	v_mfma_f32_16x16x32_bf16 v[68:71], v[192:195], v[168:171], v[68:71]
	v_mfma_f32_16x16x32_bf16 v[64:67], v[200:203], v[168:171], v[64:67]
	v_mfma_f32_16x16x32_bf16 v[116:119], v[196:199], v[148:151], v[116:119]
	v_mfma_f32_16x16x32_bf16 v[112:115], v[204:207], v[148:151], v[112:115]
	v_mfma_f32_16x16x32_bf16 v[100:103], v[196:199], v[156:159], v[100:103]
	v_mfma_f32_16x16x32_bf16 v[96:99], v[204:207], v[156:159], v[96:99]
	v_mfma_f32_16x16x32_bf16 v[84:87], v[196:199], v[164:167], v[84:87]
	v_mfma_f32_16x16x32_bf16 v[80:83], v[204:207], v[164:167], v[80:83]
	v_mfma_f32_16x16x32_bf16 v[68:71], v[196:199], v[172:175], v[68:71]
	s_barrier
	v_mfma_f32_16x16x32_bf16 v[64:67], v[204:207], v[172:175], v[64:67]
	s_setprio 0
	s_mov_b32 m0, s35
	ds_read_b128 v[144:147], v212 offset:49152
	ds_read_b128 v[148:151], v212 offset:50176
	ds_read_b128 v[152:155], v212 offset:51200
	ds_read_b128 v[156:159], v212 offset:52224
	ds_read_b128 v[160:163], v212 offset:53248
	ds_read_b128 v[164:167], v212 offset:54272
	ds_read_b128 v[168:171], v212 offset:55296
	ds_read_b128 v[172:175], v212 offset:56320
	global_load_lds_dwordx4 v176, s[100:101]
	s_mov_b32 m0, s36
	s_nop 0
	global_load_lds_dwordx4 v180, s[100:101]
	s_waitcnt vmcnt(10)
	s_barrier
; #define PG8_STAGE(bufoff, gbase, voff) do { _Pragma("unroll") for (int _i = 0; _i < 2; ++_i) \
;         __builtin_amdgcn_global_load_lds((const unsigned*)((const char*)(gbase) + (voff)[_i]), (LAS unsigned*)(lds + (bufoff) + ldsw + _i * 8192), 16, 0, 0); } while (0)
; #define PG8_MMA(ai, bj, At, Bt) do { __builtin_amdgcn_s_setprio(1); _Pragma("unroll") for (int m = 0; m < 4; ++m) _Pragma("unroll") for (int n = 0; n < 2; ++n) _Pragma("unroll") for (int k = 0; k < 2; ++k) \
;         acc[ai][bj][m][n] = __builtin_amdgcn_mfma_f32_16x16x32_bf16(Bt[n][k], At[m][k], acc[ai][bj][m][n], 0, 0, 0); __builtin_amdgcn_s_setprio(0); } while (0)
; #define PG8_WAIT_V(n) asm volatile("s_waitcnt vmcnt(" #n ")" ::: "memory")
; #define PG8_WAIT_L(n) asm volatile("s_waitcnt lgkmcnt(" #n ")" ::: "memory")
; #define PG8_BAR __builtin_amdgcn_s_barrier()
; #define PG8_SCHED __builtin_amdgcn_sched_barrier(0)
; template <class Epi>
; __device__ __forceinline__ void gemm_phase(ldsp lds, const Gemm g, const StaticOrder& S, const Epi& E) {
;     ...
;             PG8_WAIT_V(10); PG8_BAR; PG8_WAIT_L(0); PG8_MMA(1, 0, At, B0); PG8_BAR; PG8_SCHED;
;             PG8_STAGE(PG8_SB(1, 1), b3 + hstep, voffB);
;             PG8_WAIT_V(10); PG8_BAR; PG8_MMA(1, 1, At, B1); PG8_BAR;
	s_waitcnt lgkmcnt(0)
	s_setprio 1
	s_waitcnt lgkmcnt(0)
	v_mfma_f32_16x16x32_bf16 v[60:63], v[128:131], v[144:147], v[60:63]
	v_mfma_f32_16x16x32_bf16 v[56:59], v[136:139], v[144:147], v[56:59]
	v_mfma_f32_16x16x32_bf16 v[44:47], v[128:131], v[152:155], v[44:47]
	v_mfma_f32_16x16x32_bf16 v[40:43], v[136:139], v[152:155], v[40:43]
	v_mfma_f32_16x16x32_bf16 v[28:31], v[128:131], v[160:163], v[28:31]
	v_mfma_f32_16x16x32_bf16 v[24:27], v[136:139], v[160:163], v[24:27]
	v_mfma_f32_16x16x32_bf16 v[12:15], v[128:131], v[168:171], v[12:15]
	v_mfma_f32_16x16x32_bf16 v[8:11], v[136:139], v[168:171], v[8:11]
	v_mfma_f32_16x16x32_bf16 v[60:63], v[132:135], v[148:151], v[60:63]
	v_mfma_f32_16x16x32_bf16 v[56:59], v[140:143], v[148:151], v[56:59]
	v_mfma_f32_16x16x32_bf16 v[44:47], v[132:135], v[156:159], v[44:47]
	v_mfma_f32_16x16x32_bf16 v[40:43], v[140:143], v[156:159], v[40:43]
	v_mfma_f32_16x16x32_bf16 v[28:31], v[132:135], v[164:167], v[28:31]
	v_mfma_f32_16x16x32_bf16 v[24:27], v[140:143], v[164:167], v[24:27]
	v_mfma_f32_16x16x32_bf16 v[12:15], v[132:135], v[172:175], v[12:15]
	s_barrier
	v_mfma_f32_16x16x32_bf16 v[8:11], v[140:143], v[172:175], v[8:11]
	s_setprio 0
	s_add_u32 s24, s24, 0x80080
	s_addc_u32 s25, s25, 0
	s_add_i32 s26, s26, s29
	s_mov_b32 m0, s26
	s_nop 0
	global_load_lds_dwordx4 v178, s[24:25]
	s_add_i32 m0, s26, 0x2000
	s_nop 0
	global_load_lds_dwordx4 v182, s[24:25]
	s_waitcnt vmcnt(10)
	s_barrier
	s_setprio 1
	v_mfma_f32_16x16x32_bf16 v[52:55], v[192:195], v[144:147], v[52:55]
	v_mfma_f32_16x16x32_bf16 v[48:51], v[200:203], v[144:147], v[48:51]
	v_mfma_f32_16x16x32_bf16 v[36:39], v[192:195], v[152:155], v[36:39]
	v_mfma_f32_16x16x32_bf16 v[32:35], v[200:203], v[152:155], v[32:35]
	v_mfma_f32_16x16x32_bf16 v[20:23], v[192:195], v[160:163], v[20:23]
	v_mfma_f32_16x16x32_bf16 v[16:19], v[200:203], v[160:163], v[16:19]
	v_mfma_f32_16x16x32_bf16 v[4:7], v[192:195], v[168:171], v[4:7]
	v_mfma_f32_16x16x32_bf16 v[0:3], v[200:203], v[168:171], v[0:3]
	v_mfma_f32_16x16x32_bf16 v[52:55], v[196:199], v[148:151], v[52:55]
	v_mfma_f32_16x16x32_bf16 v[48:51], v[204:207], v[148:151], v[48:51]
	v_mfma_f32_16x16x32_bf16 v[36:39], v[196:199], v[156:159], v[36:39]
	v_mfma_f32_16x16x32_bf16 v[32:35], v[204:207], v[156:159], v[32:35]
	v_mfma_f32_16x16x32_bf16 v[20:23], v[196:199], v[164:167], v[20:23]
	v_mfma_f32_16x16x32_bf16 v[16:19], v[204:207], v[164:167], v[16:19]
	v_mfma_f32_16x16x32_bf16 v[4:7], v[196:199], v[172:175], v[4:7]
	s_barrier
	v_mfma_f32_16x16x32_bf16 v[0:3], v[204:207], v[172:175], v[0:3]
	s_setprio 0
	s_add_i32 s46, s46, 2
	s_add_u32 s22, s22, 0x100
	s_addc_u32 s23, s23, 0
	s_add_u32 s44, s44, 0x100
	s_addc_u32 s45, s45, 0
	s_cmp_gt_u32 s46, 29
	s_cbranch_scc0 .LBB0_733
;     __device__ __forceinline__ void ld(f32x4 (&xv)[2][2][2], int row0, int col0, int ai, int mh) const {
; #pragma unroll
;         for (int mm = 0; mm < 2; ++mm)
; #pragma unroll
;             for (int bj = 0; bj < 2; ++bj) { const size_t off = (size_t)(row0 + ai * 128 + (2 * mh + mm) * 16) * 2048 + col0 + bj * 128;
;                 xv[mm][bj][0] = *(const f32x4*)(base + off); xv[mm][bj][1] = *(const f32x4*)(base + off + 4); }
;     }
;     __device__ __forceinline__ void fin(const f32x4 (&acc)[2][2][4][2], const f32x4 (&xv)[2][2][2], int row0, int col0, int fq, int ai, int mh) const {
; #pragma unroll
;         for (int mm = 0; mm < 2; ++mm) { const int m = 2 * mh + mm; const int row = row0 + ai * 128 + m * 16; float sq = 0.f;
; #pragma unroll
;             for (int bj = 0; bj < 2; ++bj) { const size_t off = (size_t)row * 2048 + col0 + bj * 128;
;                 const f32x4 y0 = xv[mm][bj][0] + acc[ai][bj][m][0], y1 = xv[mm][bj][1] + acc[ai][bj][m][1];
;                 *(f32x4*)(out + off) = y0; *(f32x4*)(out + off + 4) = y1;
;                 if (ob) *(u32x4*)(ob + off) = pack8(y0, y1);
;                 sq += (y0[0] * y0[0] + y0[1] * y0[1]) + (y0[2] * y0[2] + y0[3] * y0[3]) + (y1[0] * y1[0] + y1[1] * y1[1]) + (y1[2] * y1[2] + y1[3] * y1[3]); }
;             sq += __shfl_xor(sq, 16); sq += __shfl_xor(sq, 32);
;             if (fq == 0) atomicAdd(ssq + row, (unsigned long long)(sq * 16777216.0f + 0.5f)); }
	v_lshl_add_u32 v194, s18, 8, v208
	v_lshl_or_b32 v192, s20, 8, v210
	v_ashrrev_i32_e32 v195, 31, v194
	v_ashrrev_i32_e32 v193, 31, v192
	v_lshlrev_b64 v[128:129], 11, v[194:195]
	v_lshl_add_u64 v[218:219], v[128:129], 0, v[192:193]
	v_lshlrev_b64 v[238:239], 2, v[218:219]
	v_lshl_add_u64 v[128:129], s[64:65], 0, v[238:239]
	global_load_dwordx4 v[222:225], v[128:129], off
	global_load_dwordx4 v[226:229], v[128:129], off offset:16
	global_load_dwordx4 v[230:233], v[128:129], off offset:512
	global_load_dwordx4 v[234:237], v[128:129], off offset:528
	v_or_b32_e32 v204, 16, v194
	v_or_b32_e32 v200, 32, v194
	v_or_b32_e32 v196, 48, v194
	v_ashrrev_i32_e32 v205, 31, v204
	v_ashrrev_i32_e32 v201, 31, v200
	v_ashrrev_i32_e32 v197, 31, v196
	v_lshlrev_b64 v[128:129], 11, v[204:205]
	v_lshlrev_b64 v[130:131], 11, v[200:201]
	v_lshlrev_b64 v[132:133], 11, v[196:197]
	v_lshl_add_u64 v[206:207], v[128:129], 0, v[192:193]
	v_lshl_add_u64 v[202:203], v[130:131], 0, v[192:193]
	v_lshl_add_u64 v[198:199], v[132:133], 0, v[192:193]
	v_lshl_add_u64 v[128:129], v[206:207], 2, s[64:65]
	v_lshl_add_u64 v[130:131], v[202:203], 2, s[64:65]
	v_lshl_add_u64 v[132:133], v[198:199], 2, s[64:65]
	global_load_dwordx4 v[168:171], v[128:129], off offset:16
	global_load_dwordx4 v[172:175], v[128:129], off
	global_load_dwordx4 v[160:163], v[128:129], off offset:528
	global_load_dwordx4 v[164:167], v[128:129], off offset:512
	global_load_dwordx4 v[152:155], v[130:131], off offset:16
	global_load_dwordx4 v[156:159], v[130:131], off
	global_load_dwordx4 v[144:147], v[130:131], off offset:528
	global_load_dwordx4 v[148:151], v[130:131], off offset:512
	global_load_dwordx4 v[136:139], v[132:133], off offset:16
	global_load_dwordx4 v[140:143], v[132:133], off
	s_nop 0
	global_load_dwordx4 v[128:131], v[132:133], off offset:528
	s_nop 0
	global_load_dwordx4 v[132:135], v[132:133], off offset:512
	v_and_b32_e32 v216, 64, v214
	v_xor_b32_e32 v215, 16, v214
	v_add_u32_e32 v216, 64, v216
	v_xor_b32_e32 v217, 32, v214
	v_cmp_lt_i32_e32 vcc, v215, v216
	v_lshl_add_u64 v[238:239], s[70:71], 0, v[238:239]
	v_lshlrev_b64 v[218:219], 1, v[218:219]
	v_cndmask_b32_e32 v215, v214, v215, vcc
	v_cmp_lt_i32_e32 vcc, v217, v216
	v_lshlrev_b32_e32 v216, 2, v215
	v_lshl_add_u64 v[240:241], s[58:59], 0, v[218:219]
	v_cndmask_b32_e32 v217, v214, v217, vcc
	v_lshlrev_b32_e32 v215, 2, v217
	v_or_b32_e32 v218, 0x100, v218
	s_waitcnt vmcnt(0)
	v_pk_add_f32 v[126:127], v[126:127], v[224:225]
	v_pk_add_f32 v[124:125], v[124:125], v[222:223]
	v_pk_add_f32 v[118:119], v[118:119], v[232:233]
	v_pk_add_f32 v[116:117], v[116:117], v[230:231]
	v_pk_add_f32 v[122:123], v[122:123], v[228:229]
	v_pk_add_f32 v[120:121], v[120:121], v[226:227]
	v_pk_add_f32 v[112:113], v[112:113], v[234:235]
	global_store_dwordx4 v[238:239], v[124:127], off
	global_store_dwordx4 v[238:239], v[120:123], off offset:16
	v_cvt_pk_bf16_f32 v222, v124, v125
	v_cvt_pk_bf16_f32 v223, v126, v127
	v_mul_f32_e32 v125, v125, v125
	v_mul_f32_e32 v127, v127, v127
	v_mul_f32_e32 v217, v117, v117
	v_mul_f32_e32 v221, v119, v119
	v_pk_add_f32 v[114:115], v[114:115], v[236:237]
	v_cvt_pk_bf16_f32 v224, v120, v121
	v_cvt_pk_bf16_f32 v225, v122, v123
	v_mul_f32_e32 v121, v121, v121
	v_mul_f32_e32 v123, v123, v123
	v_mul_f32_e32 v226, v113, v113
	v_fmac_f32_e32 v125, v124, v124
	v_fmac_f32_e32 v127, v126, v126
	v_fmac_f32_e32 v217, v116, v116
	v_fmac_f32_e32 v221, v118, v118
	v_mul_f32_e32 v227, v115, v115
	v_fmac_f32_e32 v121, v120, v120
	v_fmac_f32_e32 v123, v122, v122
	v_fmac_f32_e32 v226, v112, v112
	v_add_f32_e32 v120, v125, v127
	v_add_f32_e32 v122, v217, v221
	v_fmac_f32_e32 v227, v114, v114
	v_add_f32_e32 v120, v120, v121
	v_add_f32_e32 v121, v122, v226
	v_add_f32_e32 v120, v123, v120
	v_add_f32_e32 v121, v227, v121
	v_add_f32_e32 v120, v120, v121
	ds_bpermute_b32 v121, v216, v120
	global_store_dwordx4 v[240:241], v[222:225], off
	global_store_dwordx4 v[238:239], v[116:119], off offset:512
	global_store_dwordx4 v[238:239], v[112:115], off offset:528
	s_nop 0
	v_cvt_pk_bf16_f32 v116, v116, v117
	v_cvt_pk_bf16_f32 v117, v118, v119
	v_cvt_pk_bf16_f32 v118, v112, v113
	s_waitcnt lgkmcnt(0)
	v_add_f32_e32 v112, v120, v121
	ds_bpermute_b32 v113, v215, v112
	v_cvt_pk_bf16_f32 v119, v114, v115
	v_lshl_add_u64 v[114:115], s[58:59], 0, v[218:219]
	global_store_dwordx4 v[114:115], v[116:119], off
	s_and_saveexec_b64 s[18:19], s[2:3]
	s_cbranch_execz .LBB0_736
	s_waitcnt lgkmcnt(0)
	v_add_f32_e32 v112, v112, v113
	v_fma_f32 v112, v112, s42, 0.5
	v_trunc_f32_e32 v112, v112
	v_mul_f32_e32 v113, 0x2f800000, v112
	v_floor_f32_e32 v113, v113
	v_fmac_f32_e32 v112, 0xcf800000, v113
	v_cvt_u32_f32_e32 v112, v112
	v_cvt_u32_f32_e32 v113, v113
	v_lshl_add_u64 v[114:115], v[194:195], 3, s[0:1]
	global_atomic_add_x2 v[114:115], v[112:113], off

; #define PG8_STAGE(bufoff, gbase, voff) do { _Pragma("unroll") for (int _i = 0; _i < 2; ++_i) \
;         __builtin_amdgcn_global_load_lds((const unsigned*)((const char*)(gbase) + (voff)[_i]), (LAS unsigned*)(lds + (bufoff) + ldsw + _i * 8192), 16, 0, 0); } while (0)
; #define PG8_WAIT_V(n) asm volatile("s_waitcnt vmcnt(" #n ")" ::: "memory")
; #define PG8_BAR __builtin_amdgcn_s_barrier()
; template <class Epi>
; __device__ __forceinline__ void gemm_phase(ldsp lds, const Gemm g, const StaticOrder& S, const Epi& E) {
;     ...
;     const int aoff = lds_byte(wr * 64 + fr, fq * 8), boff = lds_byte(wc * 32 + fr, fq * 8);
;     ...
;     PG8_WAIT_V(4); PG8_BAR;
;     PG8_STAGE(PG8_SB(1, 0), cB + kstep, voffB); PG8_STAGE(PG8_SA(1, 0), cA + kstep, voffA); PG8_STAGE(PG8_SB(1, 1), cB + hstep + kstep, voffB);
;     PG8_WAIT_V(6); PG8_BAR;
.LBB0_811:
	s_lshl_b32 s6, s6, 5
	s_and_b32 s10, s6, 0x60
	s_mov_b64 s[6:7], 0x80
	s_add_i32 m0, s29, 0x18000
	v_lshl_add_u64 v[6:7], v[6:7], 0, s[6:7]
	s_lshl_b32 s8, s3, 13
	s_lshl_b32 s12, s10, 7
	s_waitcnt vmcnt(4)
	s_barrier
	global_load_lds_dwordx4 v[6:7], off
	v_lshl_add_u64 v[4:5], v[4:5], 0, s[6:7]
	s_add_i32 m0, s29, 0x1a000
	s_add_i32 s35, s29, 0x8000
	s_add_i32 s36, s29, 0xa000
	global_load_lds_dwordx4 v[4:5], off
	v_lshl_add_u64 v[2:3], v[2:3], 0, s[6:7]
	s_mov_b32 m0, s35
	s_add_u32 s14, s24, 0x80080
	global_load_lds_dwordx4 v[2:3], off
	v_lshl_add_u64 v[0:1], v[0:1], 0, s[6:7]
	s_mov_b32 m0, s36
	s_addc_u32 s15, s25, 0
	global_load_lds_dwordx4 v[0:1], off
	s_add_i32 m0, s29, 0x1c000
	v_lshl_add_u64 v[0:1], s[14:15], 0, v[132:133]
	global_load_lds_dwordx4 v[0:1], off
	v_lshl_add_u64 v[0:1], s[14:15], 0, v[128:129]
	s_add_i32 m0, s29, 0x1e000
	s_sext_i32_i16 s43, s2
	global_load_lds_dwordx4 v[0:1], off
	v_and_b32_e32 v0, 15, v220
	v_lshlrev_b32_e32 v1, 1, v11
	v_lshlrev_b32_e32 v2, 2, v220
	v_lshlrev_b32_e32 v3, 6, v220
	s_movk_i32 s2, 0x3c0
	v_lshl_or_b32 v174, s3, 6, v0
	v_lshl_or_b32 v0, v0, 6, v1
	v_and_b32_e32 v2, 32, v2
	v_and_or_b32 v1, v3, s2, v1
	v_bitop3_b32 v175, s12, v1, v2 bitop3:0xf6
	v_add_u32_e32 v247, 0x10000, v175
	v_lshlrev_b32_e32 v1, 9, v220
	v_bitop3_b32 v0, v0, s8, v2 bitop3:0xde
	v_and_b32_e32 v1, 0x70000, v1
	v_lshlrev_b32_e32 v2, 12, v12
	v_or3_b32 v1, v9, v1, v2
	v_add_u32_e32 v136, v1, v10
	v_lshlrev_b32_e32 v1, 5, v8
	s_waitcnt vmcnt(6)
	v_and_b32_e32 v1, 0xf0000, v1
	v_or3_b32 v1, v9, v1, v2
	s_ashr_i32 s37, s62, 31
	s_mov_b32 s38, s62
	v_or_b32_e32 v176, s10, v11
	v_mov_b32_e32 v137, v133
	v_add_u32_e32 v138, v1, v10
	v_mov_b32_e32 v139, v133
	v_mov_b64_e32 v[140:141], 0x1600
	v_mov_b64_e32 v[142:143], 0x15ff
	s_add_i32 s39, 0, 0x10000
	v_add_u32_e32 v177, 0, v0
	s_add_i32 s40, 0, 0x14000
	s_movk_i32 s41, 0x2c00
	s_mov_b32 s8, 0x33800000
	s_mov_b32 s10, 0x3a000000
	s_mov_b32 s12, 0x358637bd
	s_mov_b32 s42, 0x800000
	s_barrier
	s_branch .LBB0_813

; #define PG8_STAGE(bufoff, gbase, voff) do { _Pragma("unroll") for (int _i = 0; _i < 2; ++_i) \
;         __builtin_amdgcn_global_load_lds((const unsigned*)((const char*)(gbase) + (voff)[_i]), (LAS unsigned*)(lds + (bufoff) + ldsw + _i * 8192), 16, 0, 0); } while (0)
; #define PG8_LDA(dst, b, h) do { _Pragma("unroll") for (int m = 0; m < 4; ++m) _Pragma("unroll") for (int k = 0; k < 2; ++k) dst[m][k] = *(const LAS bf16x8*)(lds + PG8_SA(b, h) + aoff + m * 2048 + k * 1024); } while (0)
; #define PG8_LDB(dst, b, h) do { _Pragma("unroll") for (int n = 0; n < 2; ++n) _Pragma("unroll") for (int k = 0; k < 2; ++k) dst[n][k] = *(const LAS bf16x8*)(lds + PG8_SB(b, h) + boff + n * 2048 + k * 1024); } while (0)
; #define PG8_MMA(ai, bj, At, Bt) do { __builtin_amdgcn_s_setprio(1); _Pragma("unroll") for (int m = 0; m < 4; ++m) _Pragma("unroll") for (int n = 0; n < 2; ++n) _Pragma("unroll") for (int k = 0; k < 2; ++k) \
;         acc[ai][bj][m][n] = __builtin_amdgcn_mfma_f32_16x16x32_bf16(Bt[n][k], At[m][k], acc[ai][bj][m][n], 0, 0, 0); __builtin_amdgcn_s_setprio(0); } while (0)
; template <class Epi>
; __device__ __forceinline__ void gemm_phase(ldsp lds, const Gemm g, const StaticOrder& S, const Epi& E) {
;     ...
;             const bool last = (t == nt - 2);
;             const char* a1 = cA + (size_t)(t + 1) * kstep;
;             const char* a2 = last ? nA : cA + (size_t)(t + 2) * kstep; const char* b2 = last ? nB : cB + (size_t)(t + 2) * kstep;
;             const char* a3 = a2 + kstep; const char* b3 = b2 + kstep;
;             if constexpr (Epi::NPRE > 0) { if (last) E.pre(pre, cur, wr, fr); }
;             if constexpr (Epi::MID_T > 0) { if (t == Epi::MID_T) E.mid(acc, cur, wr, wc, fr, fq); }
;             PG8_LDB(B0, 0, 0); PG8_SCHED; PG8_LDA(At, 0, 0); PG8_STAGE(PG8_SA(1, 1), a1 + hstep, voffA);
;             PG8_WAIT_L(8); PG8_WAIT_V(10); PG8_BAR; PG8_WAIT_L(0); PG8_MMA(0, 0, At, B0); PG8_BAR; PG8_SCHED;
;             PG8_LDB(B1, 0, 1); PG8_STAGE(PG8_SB(0, 0), b2, voffB);
;             PG8_WAIT_V(10); PG8_BAR; PG8_WAIT_L(0); PG8_MMA(0, 1, At, B1); PG8_BAR;
;             PG8_LDA(At, 0, 1); PG8_STAGE(PG8_SA(0, 0), a2, voffA);
;             PG8_WAIT_V(10); PG8_BAR; PG8_WAIT_L(0); PG8_MMA(1, 0, At, B0); PG8_BAR; PG8_SCHED;
;             PG8_STAGE(PG8_SB(0, 1), b2 + hstep, voffB);
;             PG8_WAIT_V(10); PG8_BAR; PG8_MMA(1, 1, At, B1); PG8_BAR;
.LBB0_816:
	ds_read_b128 v[164:167], v247 offset:0
	ds_read_b128 v[168:171], v247 offset:1024
	ds_read_b128 v[178:181], v247 offset:2048
	ds_read_b128 v[182:185], v247 offset:3072
	s_add_u32 s26, s22, 0xfff80080
	s_addc_u32 s27, s23, -1
	s_and_b64 s[24:25], s[24:25], exec
	s_cselect_b32 s27, s17, s27
	s_cselect_b32 s26, s44, s26
	s_cselect_b32 s25, s15, s47
	s_cselect_b32 s24, s45, s46
	s_add_i32 m0, s29, 0xc000
	ds_read_b128 v[186:189], v177
	ds_read_b128 v[190:193], v177 offset:1024
	ds_read_b128 v[194:197], v177 offset:2048
	ds_read_b128 v[198:201], v177 offset:3072
	ds_read_b128 v[202:205], v177 offset:4096
	ds_read_b128 v[206:209], v177 offset:5120
	ds_read_b128 v[210:213], v177 offset:6144
	ds_read_b128 v[214:217], v177 offset:7168
	global_load_lds_dwordx4 v136, s[22:23]
	s_add_i32 m0, s29, 0xe000
	s_nop 0
	global_load_lds_dwordx4 v138, s[22:23]
	s_waitcnt lgkmcnt(8)
	s_waitcnt vmcnt(10)
	s_barrier
	s_waitcnt lgkmcnt(0)
	s_setprio 1
	s_waitcnt lgkmcnt(0)
	v_mfma_f32_16x16x32_bf16 v[124:127], v[164:167], v[186:189], v[124:127]
	v_mfma_f32_16x16x32_bf16 v[120:123], v[178:181], v[186:189], v[120:123]
	v_mfma_f32_16x16x32_bf16 v[112:115], v[164:167], v[194:197], v[112:115]
	v_mfma_f32_16x16x32_bf16 v[104:107], v[178:181], v[194:197], v[104:107]
	v_mfma_f32_16x16x32_bf16 v[92:95], v[164:167], v[202:205], v[92:95]
	v_mfma_f32_16x16x32_bf16 v[88:91], v[178:181], v[202:205], v[88:91]
	v_mfma_f32_16x16x32_bf16 v[80:83], v[164:167], v[210:213], v[80:83]
	v_mfma_f32_16x16x32_bf16 v[72:75], v[178:181], v[210:213], v[72:75]
	v_mfma_f32_16x16x32_bf16 v[124:127], v[168:171], v[190:193], v[124:127]
	v_mfma_f32_16x16x32_bf16 v[120:123], v[182:185], v[190:193], v[120:123]
	v_mfma_f32_16x16x32_bf16 v[112:115], v[168:171], v[198:201], v[112:115]
	v_mfma_f32_16x16x32_bf16 v[104:107], v[182:185], v[198:201], v[104:107]
	v_mfma_f32_16x16x32_bf16 v[92:95], v[168:171], v[206:209], v[92:95]
	v_mfma_f32_16x16x32_bf16 v[88:91], v[182:185], v[206:209], v[88:91]
	v_mfma_f32_16x16x32_bf16 v[80:83], v[168:171], v[214:217], v[80:83]
	s_barrier
	v_mfma_f32_16x16x32_bf16 v[72:75], v[182:185], v[214:217], v[72:75]
	s_setprio 0
	s_add_i32 s51, s39, s11
	s_add_u32 s98, s24, 0x80
	s_addc_u32 s99, s25, 0
	s_mov_b32 m0, s51
	ds_read_b128 v[222:225], v247 offset:16384
	ds_read_b128 v[226:229], v247 offset:17408
	ds_read_b128 v[230:233], v247 offset:18432
	ds_read_b128 v[234:237], v247 offset:19456
	global_load_lds_dwordx4 v132, s[24:25]
	s_add_i32 m0, s51, 0x2000
	s_nop 0
	global_load_lds_dwordx4 v128, s[24:25]
	s_waitcnt vmcnt(10)
	s_barrier
	s_waitcnt lgkmcnt(0)
	s_setprio 1
	s_waitcnt lgkmcnt(0)
	v_mfma_f32_16x16x32_bf16 v[116:119], v[222:225], v[186:189], v[116:119]
	v_mfma_f32_16x16x32_bf16 v[108:111], v[230:233], v[186:189], v[108:111]
	v_mfma_f32_16x16x32_bf16 v[100:103], v[222:225], v[194:197], v[100:103]
	v_mfma_f32_16x16x32_bf16 v[96:99], v[230:233], v[194:197], v[96:99]
	v_mfma_f32_16x16x32_bf16 v[84:87], v[222:225], v[202:205], v[84:87]
	v_mfma_f32_16x16x32_bf16 v[76:79], v[230:233], v[202:205], v[76:79]
	v_mfma_f32_16x16x32_bf16 v[68:71], v[222:225], v[210:213], v[68:71]
	v_mfma_f32_16x16x32_bf16 v[64:67], v[230:233], v[210:213], v[64:67]
	v_mfma_f32_16x16x32_bf16 v[116:119], v[226:229], v[190:193], v[116:119]
	v_mfma_f32_16x16x32_bf16 v[108:111], v[234:237], v[190:193], v[108:111]
	v_mfma_f32_16x16x32_bf16 v[100:103], v[226:229], v[198:201], v[100:103]
	v_mfma_f32_16x16x32_bf16 v[96:99], v[234:237], v[198:201], v[96:99]
	v_mfma_f32_16x16x32_bf16 v[84:87], v[226:229], v[206:209], v[84:87]
	v_mfma_f32_16x16x32_bf16 v[76:79], v[234:237], v[206:209], v[76:79]
	v_mfma_f32_16x16x32_bf16 v[68:71], v[226:229], v[214:217], v[68:71]
	s_barrier
	v_mfma_f32_16x16x32_bf16 v[64:67], v[234:237], v[214:217], v[64:67]
	s_setprio 0
	s_mov_b32 m0, s29
	s_add_u32 s100, s26, 0x80
	s_addc_u32 s101, s27, 0
	ds_read_b128 v[186:189], v177 offset:16384
	ds_read_b128 v[190:193], v177 offset:17408
	ds_read_b128 v[194:197], v177 offset:18432
	ds_read_b128 v[198:201], v177 offset:19456
	ds_read_b128 v[202:205], v177 offset:20480
	ds_read_b128 v[206:209], v177 offset:21504
	ds_read_b128 v[210:213], v177 offset:22528
	ds_read_b128 v[214:217], v177 offset:23552
	global_load_lds_dwordx4 v134, s[26:27]
	s_mov_b32 m0, s30
	s_nop 0
	global_load_lds_dwordx4 v130, s[26:27]
	s_waitcnt vmcnt(10)
	s_barrier
	s_waitcnt lgkmcnt(0)
	s_setprio 1
	s_waitcnt lgkmcnt(0)
	v_mfma_f32_16x16x32_bf16 v[60:63], v[164:167], v[186:189], v[60:63]
	v_mfma_f32_16x16x32_bf16 v[56:59], v[178:181], v[186:189], v[56:59]
	v_mfma_f32_16x16x32_bf16 v[48:51], v[164:167], v[194:197], v[48:51]
	v_mfma_f32_16x16x32_bf16 v[40:43], v[178:181], v[194:197], v[40:43]
	v_mfma_f32_16x16x32_bf16 v[28:31], v[164:167], v[202:205], v[28:31]
	v_mfma_f32_16x16x32_bf16 v[24:27], v[178:181], v[202:205], v[24:27]
	v_mfma_f32_16x16x32_bf16 v[16:19], v[164:167], v[210:213], v[16:19]
	v_mfma_f32_16x16x32_bf16 v[8:11], v[178:181], v[210:213], v[8:11]
	v_mfma_f32_16x16x32_bf16 v[60:63], v[168:171], v[190:193], v[60:63]
	v_mfma_f32_16x16x32_bf16 v[56:59], v[182:185], v[190:193], v[56:59]
	v_mfma_f32_16x16x32_bf16 v[48:51], v[168:171], v[198:201], v[48:51]
	v_mfma_f32_16x16x32_bf16 v[40:43], v[182:185], v[198:201], v[40:43]
	v_mfma_f32_16x16x32_bf16 v[28:31], v[168:171], v[206:209], v[28:31]
	v_mfma_f32_16x16x32_bf16 v[24:27], v[182:185], v[206:209], v[24:27]
	v_mfma_f32_16x16x32_bf16 v[16:19], v[168:171], v[214:217], v[16:19]
	s_barrier
	v_mfma_f32_16x16x32_bf16 v[8:11], v[182:185], v[214:217], v[8:11]
	s_setprio 0
	s_add_u32 s52, s24, 0x80000
	s_addc_u32 s53, s25, 0
	s_add_i32 s51, s40, s11
	s_mov_b32 m0, s51
	s_nop 0
	global_load_lds_dwordx4 v132, s[52:53]
	s_add_i32 m0, s51, 0x2000
	s_nop 0
	global_load_lds_dwordx4 v128, s[52:53]
	s_waitcnt vmcnt(10)
	s_barrier
; #define PG8_STAGE(bufoff, gbase, voff) do { _Pragma("unroll") for (int _i = 0; _i < 2; ++_i) \
;         __builtin_amdgcn_global_load_lds((const unsigned*)((const char*)(gbase) + (voff)[_i]), (LAS unsigned*)(lds + (bufoff) + ldsw + _i * 8192), 16, 0, 0); } while (0)
; #define PG8_LDA(dst, b, h) do { _Pragma("unroll") for (int m = 0; m < 4; ++m) _Pragma("unroll") for (int k = 0; k < 2; ++k) dst[m][k] = *(const LAS bf16x8*)(lds + PG8_SA(b, h) + aoff + m * 2048 + k * 1024); } while (0)
; #define PG8_LDB(dst, b, h) do { _Pragma("unroll") for (int n = 0; n < 2; ++n) _Pragma("unroll") for (int k = 0; k < 2; ++k) dst[n][k] = *(const LAS bf16x8*)(lds + PG8_SB(b, h) + boff + n * 2048 + k * 1024); } while (0)
; #define PG8_MMA(ai, bj, At, Bt) do { __builtin_amdgcn_s_setprio(1); _Pragma("unroll") for (int m = 0; m < 4; ++m) _Pragma("unroll") for (int n = 0; n < 2; ++n) _Pragma("unroll") for (int k = 0; k < 2; ++k) \
;         acc[ai][bj][m][n] = __builtin_amdgcn_mfma_f32_16x16x32_bf16(Bt[n][k], At[m][k], acc[ai][bj][m][n], 0, 0, 0); __builtin_amdgcn_s_setprio(0); } while (0)
; #define PG8_WAIT_V(n) asm volatile("s_waitcnt vmcnt(" #n ")" ::: "memory")
; #define PG8_WAIT_L(n) asm volatile("s_waitcnt lgkmcnt(" #n ")" ::: "memory")
; #define PG8_BAR __builtin_amdgcn_s_barrier()
; #define PG8_SCHED __builtin_amdgcn_sched_barrier(0)
; template <class Epi>
; __device__ __forceinline__ void gemm_phase(ldsp lds, const Gemm g, const StaticOrder& S, const Epi& E) {
;     ...
;             PG8_WAIT_V(10); PG8_BAR; PG8_MMA(1, 1, At, B1); PG8_BAR;
;             PG8_LDB(B0, 1, 0); PG8_SCHED; PG8_LDA(At, 1, 0); PG8_STAGE(PG8_SA(0, 1), a2 + hstep, voffA);
;             PG8_WAIT_L(8); PG8_WAIT_V(10); PG8_BAR; PG8_WAIT_L(0); PG8_MMA(0, 0, At, B0); PG8_BAR; PG8_SCHED;
;             PG8_LDB(B1, 1, 1); PG8_STAGE(PG8_SB(1, 0), b3, voffB);
;             PG8_WAIT_V(10); PG8_BAR; PG8_WAIT_L(0); PG8_MMA(0, 1, At, B1); PG8_BAR;
	s_setprio 1
	v_mfma_f32_16x16x32_bf16 v[52:55], v[222:225], v[186:189], v[52:55]
	v_mfma_f32_16x16x32_bf16 v[44:47], v[230:233], v[186:189], v[44:47]
	v_mfma_f32_16x16x32_bf16 v[36:39], v[222:225], v[194:197], v[36:39]
	v_mfma_f32_16x16x32_bf16 v[32:35], v[230:233], v[194:197], v[32:35]
	v_mfma_f32_16x16x32_bf16 v[20:23], v[222:225], v[202:205], v[20:23]
	v_mfma_f32_16x16x32_bf16 v[12:15], v[230:233], v[202:205], v[12:15]
	v_mfma_f32_16x16x32_bf16 v[4:7], v[222:225], v[210:213], v[4:7]
	v_mfma_f32_16x16x32_bf16 v[0:3], v[230:233], v[210:213], v[0:3]
	v_mfma_f32_16x16x32_bf16 v[52:55], v[226:229], v[190:193], v[52:55]
	v_mfma_f32_16x16x32_bf16 v[44:47], v[234:237], v[190:193], v[44:47]
	v_mfma_f32_16x16x32_bf16 v[36:39], v[226:229], v[198:201], v[36:39]
	v_mfma_f32_16x16x32_bf16 v[32:35], v[234:237], v[198:201], v[32:35]
	v_mfma_f32_16x16x32_bf16 v[20:23], v[226:229], v[206:209], v[20:23]
	v_mfma_f32_16x16x32_bf16 v[12:15], v[234:237], v[206:209], v[12:15]
	v_mfma_f32_16x16x32_bf16 v[4:7], v[226:229], v[214:217], v[4:7]
	s_barrier
	v_mfma_f32_16x16x32_bf16 v[0:3], v[234:237], v[214:217], v[0:3]
	s_setprio 0
	s_add_i32 s51, 0, 0x18000
	ds_read_b128 v[164:167], v247 offset:32768
	ds_read_b128 v[168:171], v247 offset:33792
	ds_read_b128 v[178:181], v247 offset:34816
	ds_read_b128 v[182:185], v247 offset:35840
	s_add_u32 s26, s26, 0x80000
	s_addc_u32 s27, s27, 0
	s_mov_b32 m0, s31
	ds_read_b128 v[186:189], v177 offset:32768
	ds_read_b128 v[190:193], v177 offset:33792
	ds_read_b128 v[194:197], v177 offset:34816
	ds_read_b128 v[198:201], v177 offset:35840
	ds_read_b128 v[202:205], v177 offset:36864
	ds_read_b128 v[206:209], v177 offset:37888
	ds_read_b128 v[210:213], v177 offset:38912
	ds_read_b128 v[214:217], v177 offset:39936
	global_load_lds_dwordx4 v134, s[26:27]
	s_mov_b32 m0, s33
	s_nop 0
	global_load_lds_dwordx4 v130, s[26:27]
	s_waitcnt lgkmcnt(8)
	s_waitcnt vmcnt(10)
	s_barrier
	s_waitcnt lgkmcnt(0)
	s_setprio 1
	s_waitcnt lgkmcnt(0)
	v_mfma_f32_16x16x32_bf16 v[124:127], v[164:167], v[186:189], v[124:127]
	v_mfma_f32_16x16x32_bf16 v[120:123], v[178:181], v[186:189], v[120:123]
	v_mfma_f32_16x16x32_bf16 v[112:115], v[164:167], v[194:197], v[112:115]
	v_mfma_f32_16x16x32_bf16 v[104:107], v[178:181], v[194:197], v[104:107]
	v_mfma_f32_16x16x32_bf16 v[92:95], v[164:167], v[202:205], v[92:95]
	v_mfma_f32_16x16x32_bf16 v[88:91], v[178:181], v[202:205], v[88:91]
	v_mfma_f32_16x16x32_bf16 v[80:83], v[164:167], v[210:213], v[80:83]
	v_mfma_f32_16x16x32_bf16 v[72:75], v[178:181], v[210:213], v[72:75]
	v_mfma_f32_16x16x32_bf16 v[124:127], v[168:171], v[190:193], v[124:127]
	v_mfma_f32_16x16x32_bf16 v[120:123], v[182:185], v[190:193], v[120:123]
	v_mfma_f32_16x16x32_bf16 v[112:115], v[168:171], v[198:201], v[112:115]
	v_mfma_f32_16x16x32_bf16 v[104:107], v[182:185], v[198:201], v[104:107]
	v_mfma_f32_16x16x32_bf16 v[92:95], v[168:171], v[206:209], v[92:95]
	v_mfma_f32_16x16x32_bf16 v[88:91], v[182:185], v[206:209], v[88:91]
	v_mfma_f32_16x16x32_bf16 v[80:83], v[168:171], v[214:217], v[80:83]
	s_barrier
	v_mfma_f32_16x16x32_bf16 v[72:75], v[182:185], v[214:217], v[72:75]
	s_setprio 0
	s_add_i32 s26, 0, 0x1c000
	s_add_i32 s27, s51, s11
	s_mov_b32 m0, s27
	ds_read_b128 v[222:225], v247 offset:49152
	ds_read_b128 v[226:229], v247 offset:50176
	ds_read_b128 v[230:233], v247 offset:51200
	ds_read_b128 v[234:237], v247 offset:52224
	global_load_lds_dwordx4 v132, s[98:99]
	s_add_i32 m0, s27, 0x2000
	s_nop 0
	global_load_lds_dwordx4 v128, s[98:99]
	s_waitcnt vmcnt(10)
	s_barrier
; #define PG8_STAGE(bufoff, gbase, voff) do { _Pragma("unroll") for (int _i = 0; _i < 2; ++_i) \
;         __builtin_amdgcn_global_load_lds((const unsigned*)((const char*)(gbase) + (voff)[_i]), (LAS unsigned*)(lds + (bufoff) + ldsw + _i * 8192), 16, 0, 0); } while (0)
; #define PG8_LDA(dst, b, h) do { _Pragma("unroll") for (int m = 0; m < 4; ++m) _Pragma("unroll") for (int k = 0; k < 2; ++k) dst[m][k] = *(const LAS bf16x8*)(lds + PG8_SA(b, h) + aoff + m * 2048 + k * 1024); } while (0)
; #define PG8_MMA(ai, bj, At, Bt) do { __builtin_amdgcn_s_setprio(1); _Pragma("unroll") for (int m = 0; m < 4; ++m) _Pragma("unroll") for (int n = 0; n < 2; ++n) _Pragma("unroll") for (int k = 0; k < 2; ++k) \
;         acc[ai][bj][m][n] = __builtin_amdgcn_mfma_f32_16x16x32_bf16(Bt[n][k], At[m][k], acc[ai][bj][m][n], 0, 0, 0); __builtin_amdgcn_s_setprio(0); } while (0)
; #define PG8_WAIT_V(n) asm volatile("s_waitcnt vmcnt(" #n ")" ::: "memory")
; #define PG8_WAIT_L(n) asm volatile("s_waitcnt lgkmcnt(" #n ")" ::: "memory")
; #define PG8_BAR __builtin_amdgcn_s_barrier()
; #define PG8_SCHED __builtin_amdgcn_sched_barrier(0)
; template <class Epi>
; __device__ __forceinline__ void gemm_phase(ldsp lds, const Gemm g, const StaticOrder& S, const Epi& E) {
;     ...
;             PG8_WAIT_V(10); PG8_BAR; PG8_WAIT_L(0); PG8_MMA(0, 1, At, B1); PG8_BAR;
;             PG8_LDA(At, 1, 1); PG8_STAGE(PG8_SA(1, 0), a3, voffA);
;             PG8_WAIT_V(10); PG8_BAR; PG8_WAIT_L(0); PG8_MMA(1, 0, At, B0); PG8_BAR; PG8_SCHED;
;             PG8_STAGE(PG8_SB(1, 1), b3 + hstep, voffB);
;             PG8_WAIT_V(10); PG8_BAR; PG8_MMA(1, 1, At, B1); PG8_BAR;
	s_waitcnt lgkmcnt(0)
	s_setprio 1
	s_waitcnt lgkmcnt(0)
	v_mfma_f32_16x16x32_bf16 v[116:119], v[222:225], v[186:189], v[116:119]
	v_mfma_f32_16x16x32_bf16 v[108:111], v[230:233], v[186:189], v[108:111]
	v_mfma_f32_16x16x32_bf16 v[100:103], v[222:225], v[194:197], v[100:103]
	v_mfma_f32_16x16x32_bf16 v[96:99], v[230:233], v[194:197], v[96:99]
	v_mfma_f32_16x16x32_bf16 v[84:87], v[222:225], v[202:205], v[84:87]
	v_mfma_f32_16x16x32_bf16 v[76:79], v[230:233], v[202:205], v[76:79]
	v_mfma_f32_16x16x32_bf16 v[68:71], v[222:225], v[210:213], v[68:71]
	v_mfma_f32_16x16x32_bf16 v[64:67], v[230:233], v[210:213], v[64:67]
	v_mfma_f32_16x16x32_bf16 v[116:119], v[226:229], v[190:193], v[116:119]
	v_mfma_f32_16x16x32_bf16 v[108:111], v[234:237], v[190:193], v[108:111]
	v_mfma_f32_16x16x32_bf16 v[100:103], v[226:229], v[198:201], v[100:103]
	v_mfma_f32_16x16x32_bf16 v[96:99], v[234:237], v[198:201], v[96:99]
	v_mfma_f32_16x16x32_bf16 v[84:87], v[226:229], v[206:209], v[84:87]
	v_mfma_f32_16x16x32_bf16 v[76:79], v[234:237], v[206:209], v[76:79]
	v_mfma_f32_16x16x32_bf16 v[68:71], v[226:229], v[214:217], v[68:71]
	s_barrier
	v_mfma_f32_16x16x32_bf16 v[64:67], v[234:237], v[214:217], v[64:67]
	s_setprio 0
	s_mov_b32 m0, s35
	ds_read_b128 v[186:189], v177 offset:49152
	ds_read_b128 v[190:193], v177 offset:50176
	ds_read_b128 v[194:197], v177 offset:51200
	ds_read_b128 v[198:201], v177 offset:52224
	ds_read_b128 v[202:205], v177 offset:53248
	ds_read_b128 v[206:209], v177 offset:54272
	ds_read_b128 v[210:213], v177 offset:55296
	ds_read_b128 v[214:217], v177 offset:56320
	global_load_lds_dwordx4 v134, s[100:101]
	s_mov_b32 m0, s36
	s_nop 0
	global_load_lds_dwordx4 v130, s[100:101]
	s_waitcnt vmcnt(10)
	s_barrier
	s_waitcnt lgkmcnt(0)
	s_setprio 1
	s_waitcnt lgkmcnt(0)
	v_mfma_f32_16x16x32_bf16 v[60:63], v[164:167], v[186:189], v[60:63]
	v_mfma_f32_16x16x32_bf16 v[56:59], v[178:181], v[186:189], v[56:59]
	v_mfma_f32_16x16x32_bf16 v[48:51], v[164:167], v[194:197], v[48:51]
	v_mfma_f32_16x16x32_bf16 v[40:43], v[178:181], v[194:197], v[40:43]
	v_mfma_f32_16x16x32_bf16 v[28:31], v[164:167], v[202:205], v[28:31]
	v_mfma_f32_16x16x32_bf16 v[24:27], v[178:181], v[202:205], v[24:27]
	v_mfma_f32_16x16x32_bf16 v[16:19], v[164:167], v[210:213], v[16:19]
	v_mfma_f32_16x16x32_bf16 v[8:11], v[178:181], v[210:213], v[8:11]
	v_mfma_f32_16x16x32_bf16 v[60:63], v[168:171], v[190:193], v[60:63]
	v_mfma_f32_16x16x32_bf16 v[56:59], v[182:185], v[190:193], v[56:59]
	v_mfma_f32_16x16x32_bf16 v[48:51], v[168:171], v[198:201], v[48:51]
	v_mfma_f32_16x16x32_bf16 v[40:43], v[182:185], v[198:201], v[40:43]
	v_mfma_f32_16x16x32_bf16 v[28:31], v[168:171], v[206:209], v[28:31]
	v_mfma_f32_16x16x32_bf16 v[24:27], v[182:185], v[206:209], v[24:27]
	v_mfma_f32_16x16x32_bf16 v[16:19], v[168:171], v[214:217], v[16:19]
	s_barrier
	v_mfma_f32_16x16x32_bf16 v[8:11], v[182:185], v[214:217], v[8:11]
	s_setprio 0
	s_add_u32 s24, s24, 0x80080
	s_addc_u32 s25, s25, 0
	s_add_i32 s26, s26, s11
	s_mov_b32 m0, s26
	s_nop 0
	global_load_lds_dwordx4 v132, s[24:25]
	s_add_i32 m0, s26, 0x2000
	s_nop 0
	global_load_lds_dwordx4 v128, s[24:25]
	s_waitcnt vmcnt(10)
	s_barrier
	s_setprio 1
	v_mfma_f32_16x16x32_bf16 v[52:55], v[222:225], v[186:189], v[52:55]
	v_mfma_f32_16x16x32_bf16 v[44:47], v[230:233], v[186:189], v[44:47]
	v_mfma_f32_16x16x32_bf16 v[36:39], v[222:225], v[194:197], v[36:39]
	v_mfma_f32_16x16x32_bf16 v[32:35], v[230:233], v[194:197], v[32:35]
	v_mfma_f32_16x16x32_bf16 v[20:23], v[222:225], v[202:205], v[20:23]
	v_mfma_f32_16x16x32_bf16 v[12:15], v[230:233], v[202:205], v[12:15]
	v_mfma_f32_16x16x32_bf16 v[4:7], v[222:225], v[210:213], v[4:7]
	v_mfma_f32_16x16x32_bf16 v[0:3], v[230:233], v[210:213], v[0:3]
	v_mfma_f32_16x16x32_bf16 v[52:55], v[226:229], v[190:193], v[52:55]
	v_mfma_f32_16x16x32_bf16 v[44:47], v[234:237], v[190:193], v[44:47]
	v_mfma_f32_16x16x32_bf16 v[36:39], v[226:229], v[198:201], v[36:39]
	v_mfma_f32_16x16x32_bf16 v[32:35], v[234:237], v[198:201], v[32:35]
	v_mfma_f32_16x16x32_bf16 v[20:23], v[226:229], v[206:209], v[20:23]
	v_mfma_f32_16x16x32_bf16 v[12:15], v[234:237], v[206:209], v[12:15]
	v_mfma_f32_16x16x32_bf16 v[4:7], v[226:229], v[214:217], v[4:7]
	s_barrier
	v_mfma_f32_16x16x32_bf16 v[0:3], v[234:237], v[214:217], v[0:3]
	s_setprio 0
	s_add_i32 s50, s50, 2
	s_add_u32 s22, s22, 0x100
	s_addc_u32 s23, s23, 0
	s_add_u32 s46, s46, 0x100
	s_addc_u32 s47, s47, 0
	s_cmp_gt_u32 s50, 29
	s_cbranch_scc1 .LBB0_812

; #define PG8_STAGE(bufoff, gbase, voff) do { _Pragma("unroll") for (int _i = 0; _i < 2; ++_i) \
;         __builtin_amdgcn_global_load_lds((const unsigned*)((const char*)(gbase) + (voff)[_i]), (LAS unsigned*)(lds + (bufoff) + ldsw + _i * 8192), 16, 0, 0); } while (0)
; #define PG8_WAIT_V(n) asm volatile("s_waitcnt vmcnt(" #n ")" ::: "memory")
; #define PG8_BAR __builtin_amdgcn_s_barrier()
; template <class Epi>
; __device__ __forceinline__ void gemm_phase(ldsp lds, const Gemm g, const StaticOrder& S, const Epi& E) {
;     ...
;     const int aoff = lds_byte(wr * 64 + fr, fq * 8), boff = lds_byte(wc * 32 + fr, fq * 8);
;     ...
;     PG8_WAIT_V(4); PG8_BAR;
;     PG8_STAGE(PG8_SB(1, 0), cB + kstep, voffB); PG8_STAGE(PG8_SA(1, 0), cA + kstep, voffA); PG8_STAGE(PG8_SB(1, 1), cB + hstep + kstep, voffB);
;     PG8_WAIT_V(6); PG8_BAR;
.LBB0_886:
	s_lshl_b32 s1, s1, 5
	s_mov_b64 s[12:13], 0x80
	s_and_b32 s1, s1, 0x60
	s_add_i32 m0, s22, 0x18000
	v_lshl_add_u64 v[6:7], v[6:7], 0, s[12:13]
	s_lshl_b32 s4, s0, 13
	s_lshl_b32 s5, s1, 7
	s_waitcnt vmcnt(4)
	s_barrier
	global_load_lds_dwordx4 v[6:7], off
	v_lshl_add_u64 v[4:5], v[4:5], 0, s[12:13]
	s_add_i32 m0, s22, 0x1a000
	s_add_i32 s27, s22, 0x8000
	s_add_i32 s28, s22, 0xa000
	global_load_lds_dwordx4 v[4:5], off
	v_lshl_add_u64 v[2:3], v[2:3], 0, s[12:13]
	s_mov_b32 m0, s27
	s_add_u32 s2, s16, 0x160080
	global_load_lds_dwordx4 v[2:3], off
	v_lshl_add_u64 v[0:1], v[0:1], 0, s[12:13]
	s_mov_b32 m0, s28
	s_addc_u32 s3, s17, 0
	global_load_lds_dwordx4 v[0:1], off
	s_add_i32 m0, s22, 0x1c000
	v_lshl_add_u64 v[0:1], s[2:3], 0, v[178:179]
	global_load_lds_dwordx4 v[0:1], off
	v_lshl_add_u64 v[0:1], s[2:3], 0, v[182:183]
	s_add_i32 m0, s22, 0x1e000
	v_lshlrev_b32_e32 v3, 2, v220
	global_load_lds_dwordx4 v[0:1], off
	v_bfe_u32 v0, v220, 4, 2
	v_and_b32_e32 v1, 15, v220
	v_lshl_or_b32 v208, s0, 6, v1
	v_lshlrev_b32_e32 v2, 4, v0
	v_lshlrev_b32_e32 v4, 6, v220
	s_movk_i32 s0, 0x3c0
	v_cmp_eq_u32_e64 s[2:3], 0, v0
	v_lshl_or_b32 v210, v0, 3, s1
	v_add_u16_e32 v0, v8, v9
	v_lshl_or_b32 v1, v1, 6, v2
	v_and_b32_e32 v3, 32, v3
	v_and_or_b32 v2, v4, s0, v2
	s_waitcnt vmcnt(6)
	v_lshrrev_b16_e32 v0, 1, v0
	v_bitop3_b32 v1, v1, s4, v3 bitop3:0xde
	v_bitop3_b32 v209, s5, v2, v3 bitop3:0xf6
	v_add_u32_e32 v247, 0x10000, v209
	v_add_lshl_u32 v184, v10, v0, 1
	v_add_lshl_u32 v186, v11, v0, 1
	s_add_i32 s33, 0, 0x10000
	s_add_i32 s34, 0, 0x14000
	v_mbcnt_lo_u32_b32 v0, -1, 0
	s_ashr_i32 s29, s62, 31
	s_mov_b32 s30, s62
	s_ashr_i32 s31, s96, 31
	v_mov_b32_e32 v185, v179
	v_mov_b32_e32 v187, v179
	v_mov_b64_e32 v[188:189], 0x400
	v_mov_b64_e32 v[190:191], 0x3ff
	v_add_u32_e32 v211, s33, v209
	v_add_u32_e32 v212, 0, v1
	v_add_u32_e32 v213, s34, v209
	v_mbcnt_hi_u32_b32 v214, -1, v0
	s_mov_b32 s35, 0x4b800000
	s_barrier
	s_branch .LBB0_888

; #define PG8_STAGE(bufoff, gbase, voff) do { _Pragma("unroll") for (int _i = 0; _i < 2; ++_i) \
;         __builtin_amdgcn_global_load_lds((const unsigned*)((const char*)(gbase) + (voff)[_i]), (LAS unsigned*)(lds + (bufoff) + ldsw + _i * 8192), 16, 0, 0); } while (0)
; #define PG8_LDA(dst, b, h) do { _Pragma("unroll") for (int m = 0; m < 4; ++m) _Pragma("unroll") for (int k = 0; k < 2; ++k) dst[m][k] = *(const LAS bf16x8*)(lds + PG8_SA(b, h) + aoff + m * 2048 + k * 1024); } while (0)
; #define PG8_LDB(dst, b, h) do { _Pragma("unroll") for (int n = 0; n < 2; ++n) _Pragma("unroll") for (int k = 0; k < 2; ++k) dst[n][k] = *(const LAS bf16x8*)(lds + PG8_SB(b, h) + boff + n * 2048 + k * 1024); } while (0)
; #define PG8_MMA(ai, bj, At, Bt) do { __builtin_amdgcn_s_setprio(1); _Pragma("unroll") for (int m = 0; m < 4; ++m) _Pragma("unroll") for (int n = 0; n < 2; ++n) _Pragma("unroll") for (int k = 0; k < 2; ++k) \
;         acc[ai][bj][m][n] = __builtin_amdgcn_mfma_f32_16x16x32_bf16(Bt[n][k], At[m][k], acc[ai][bj][m][n], 0, 0, 0); __builtin_amdgcn_s_setprio(0); } while (0)
; template <class Epi>
; __device__ __forceinline__ void gemm_phase(ldsp lds, const Gemm g, const StaticOrder& S, const Epi& E) {
;     ...
;             const bool last = (t == nt - 2);
;             const char* a1 = cA + (size_t)(t + 1) * kstep;
;             const char* a2 = last ? nA : cA + (size_t)(t + 2) * kstep; const char* b2 = last ? nB : cB + (size_t)(t + 2) * kstep;
;             const char* a3 = a2 + kstep; const char* b3 = b2 + kstep;
;             if constexpr (Epi::NPRE > 0) { if (last) E.pre(pre, cur, wr, fr); }
;             if constexpr (Epi::MID_T > 0) { if (t == Epi::MID_T) E.mid(acc, cur, wr, wc, fr, fq); }
;             PG8_LDB(B0, 0, 0); PG8_SCHED; PG8_LDA(At, 0, 0); PG8_STAGE(PG8_SA(1, 1), a1 + hstep, voffA);
;             PG8_WAIT_L(8); PG8_WAIT_V(10); PG8_BAR; PG8_WAIT_L(0); PG8_MMA(0, 0, At, B0); PG8_BAR; PG8_SCHED;
;             PG8_LDB(B1, 0, 1); PG8_STAGE(PG8_SB(0, 0), b2, voffB);
;             PG8_WAIT_V(10); PG8_BAR; PG8_WAIT_L(0); PG8_MMA(0, 1, At, B1); PG8_BAR;
;             PG8_LDA(At, 0, 1); PG8_STAGE(PG8_SA(0, 0), a2, voffA);
;             PG8_WAIT_V(10); PG8_BAR; PG8_WAIT_L(0); PG8_MMA(1, 0, At, B0); PG8_BAR; PG8_SCHED;
;             PG8_STAGE(PG8_SB(0, 1), b2 + hstep, voffB);
;             PG8_WAIT_V(10); PG8_BAR; PG8_MMA(1, 1, At, B1); PG8_BAR;
.LBB0_899:
	ds_read_b128 v[128:131], v211
	ds_read_b128 v[132:135], v211 offset:1024
	ds_read_b128 v[136:139], v211 offset:2048
	ds_read_b128 v[140:143], v211 offset:3072
	s_add_u32 s16, s14, 0xffea0080
	s_addc_u32 s17, s15, -1
	s_cmpk_eq_i32 s42, 0x54
	s_cselect_b32 s19, s1, s17
	s_cselect_b32 s18, s0, s16
	s_cselect_b32 s17, s7, s41
	s_cselect_b32 s16, s6, s40
	s_add_i32 m0, s22, 0xc000
	ds_read_b128 v[144:147], v212
	ds_read_b128 v[148:151], v212 offset:1024
	ds_read_b128 v[152:155], v212 offset:2048
	ds_read_b128 v[156:159], v212 offset:3072
	ds_read_b128 v[160:163], v212 offset:4096
	ds_read_b128 v[164:167], v212 offset:5120
	ds_read_b128 v[168:171], v212 offset:6144
	ds_read_b128 v[172:175], v212 offset:7168
	global_load_lds_dwordx4 v184, s[14:15]
	s_add_i32 m0, s22, 0xe000
	s_nop 0
	global_load_lds_dwordx4 v186, s[14:15]
	s_waitcnt lgkmcnt(8)
	s_waitcnt vmcnt(10)
	s_barrier
	s_waitcnt lgkmcnt(0)
	s_setprio 1
	s_waitcnt lgkmcnt(0)
	v_mfma_f32_16x16x32_bf16 v[124:127], v[128:131], v[144:147], v[124:127]
	v_mfma_f32_16x16x32_bf16 v[120:123], v[136:139], v[144:147], v[120:123]
	v_mfma_f32_16x16x32_bf16 v[108:111], v[128:131], v[152:155], v[108:111]
	v_mfma_f32_16x16x32_bf16 v[104:107], v[136:139], v[152:155], v[104:107]
	v_mfma_f32_16x16x32_bf16 v[92:95], v[128:131], v[160:163], v[92:95]
	v_mfma_f32_16x16x32_bf16 v[88:91], v[136:139], v[160:163], v[88:91]
	v_mfma_f32_16x16x32_bf16 v[76:79], v[128:131], v[168:171], v[76:79]
	v_mfma_f32_16x16x32_bf16 v[72:75], v[136:139], v[168:171], v[72:75]
	v_mfma_f32_16x16x32_bf16 v[124:127], v[132:135], v[148:151], v[124:127]
	v_mfma_f32_16x16x32_bf16 v[120:123], v[140:143], v[148:151], v[120:123]
	v_mfma_f32_16x16x32_bf16 v[108:111], v[132:135], v[156:159], v[108:111]
	v_mfma_f32_16x16x32_bf16 v[104:107], v[140:143], v[156:159], v[104:107]
	v_mfma_f32_16x16x32_bf16 v[92:95], v[132:135], v[164:167], v[92:95]
	v_mfma_f32_16x16x32_bf16 v[88:91], v[140:143], v[164:167], v[88:91]
	v_mfma_f32_16x16x32_bf16 v[76:79], v[132:135], v[172:175], v[76:79]
	s_barrier
	v_mfma_f32_16x16x32_bf16 v[72:75], v[140:143], v[172:175], v[72:75]
	s_setprio 0
	s_add_i32 s43, s33, s21
	s_add_u32 s98, s16, 0x80
	s_addc_u32 s99, s17, 0
	s_mov_b32 m0, s43
	ds_read_b128 v[192:195], v213
	ds_read_b128 v[196:199], v213 offset:1024
	ds_read_b128 v[200:203], v213 offset:2048
	ds_read_b128 v[204:207], v213 offset:3072
	global_load_lds_dwordx4 v178, s[16:17]
	s_add_i32 m0, s43, 0x2000
	s_nop 0
	global_load_lds_dwordx4 v182, s[16:17]
	s_waitcnt vmcnt(10)
	s_barrier
	s_waitcnt lgkmcnt(0)
	s_setprio 1
	s_waitcnt lgkmcnt(0)
	v_mfma_f32_16x16x32_bf16 v[116:119], v[192:195], v[144:147], v[116:119]
	v_mfma_f32_16x16x32_bf16 v[112:115], v[200:203], v[144:147], v[112:115]
	v_mfma_f32_16x16x32_bf16 v[100:103], v[192:195], v[152:155], v[100:103]
	v_mfma_f32_16x16x32_bf16 v[96:99], v[200:203], v[152:155], v[96:99]
	v_mfma_f32_16x16x32_bf16 v[84:87], v[192:195], v[160:163], v[84:87]
	v_mfma_f32_16x16x32_bf16 v[80:83], v[200:203], v[160:163], v[80:83]
	v_mfma_f32_16x16x32_bf16 v[68:71], v[192:195], v[168:171], v[68:71]
	v_mfma_f32_16x16x32_bf16 v[64:67], v[200:203], v[168:171], v[64:67]
	v_mfma_f32_16x16x32_bf16 v[116:119], v[196:199], v[148:151], v[116:119]
	v_mfma_f32_16x16x32_bf16 v[112:115], v[204:207], v[148:151], v[112:115]
	v_mfma_f32_16x16x32_bf16 v[100:103], v[196:199], v[156:159], v[100:103]
	v_mfma_f32_16x16x32_bf16 v[96:99], v[204:207], v[156:159], v[96:99]
	v_mfma_f32_16x16x32_bf16 v[84:87], v[196:199], v[164:167], v[84:87]
	v_mfma_f32_16x16x32_bf16 v[80:83], v[204:207], v[164:167], v[80:83]
	v_mfma_f32_16x16x32_bf16 v[68:71], v[196:199], v[172:175], v[68:71]
	s_barrier
	v_mfma_f32_16x16x32_bf16 v[64:67], v[204:207], v[172:175], v[64:67]
	s_setprio 0
	s_mov_b32 m0, s22
	s_add_u32 s100, s18, 0x80
	s_addc_u32 s101, s19, 0
	ds_read_b128 v[144:147], v212 offset:16384
	ds_read_b128 v[148:151], v212 offset:17408
	ds_read_b128 v[152:155], v212 offset:18432
	ds_read_b128 v[156:159], v212 offset:19456
	ds_read_b128 v[160:163], v212 offset:20480
	ds_read_b128 v[164:167], v212 offset:21504
	ds_read_b128 v[168:171], v212 offset:22528
	ds_read_b128 v[172:175], v212 offset:23552
	global_load_lds_dwordx4 v176, s[18:19]
	s_mov_b32 m0, s23
	s_nop 0
	global_load_lds_dwordx4 v180, s[18:19]
	s_waitcnt vmcnt(10)
	s_barrier
	s_waitcnt lgkmcnt(0)
	s_setprio 1
	s_waitcnt lgkmcnt(0)
	v_mfma_f32_16x16x32_bf16 v[60:63], v[128:131], v[144:147], v[60:63]
	v_mfma_f32_16x16x32_bf16 v[56:59], v[136:139], v[144:147], v[56:59]
	v_mfma_f32_16x16x32_bf16 v[44:47], v[128:131], v[152:155], v[44:47]
	v_mfma_f32_16x16x32_bf16 v[40:43], v[136:139], v[152:155], v[40:43]
	v_mfma_f32_16x16x32_bf16 v[28:31], v[128:131], v[160:163], v[28:31]
	v_mfma_f32_16x16x32_bf16 v[24:27], v[136:139], v[160:163], v[24:27]
	v_mfma_f32_16x16x32_bf16 v[12:15], v[128:131], v[168:171], v[12:15]
	v_mfma_f32_16x16x32_bf16 v[8:11], v[136:139], v[168:171], v[8:11]
	v_mfma_f32_16x16x32_bf16 v[60:63], v[132:135], v[148:151], v[60:63]
	v_mfma_f32_16x16x32_bf16 v[56:59], v[140:143], v[148:151], v[56:59]
	v_mfma_f32_16x16x32_bf16 v[44:47], v[132:135], v[156:159], v[44:47]
	v_mfma_f32_16x16x32_bf16 v[40:43], v[140:143], v[156:159], v[40:43]
	v_mfma_f32_16x16x32_bf16 v[28:31], v[132:135], v[164:167], v[28:31]
	v_mfma_f32_16x16x32_bf16 v[24:27], v[140:143], v[164:167], v[24:27]
	v_mfma_f32_16x16x32_bf16 v[12:15], v[132:135], v[172:175], v[12:15]
	s_barrier
	v_mfma_f32_16x16x32_bf16 v[8:11], v[140:143], v[172:175], v[8:11]
	s_setprio 0
	s_add_u32 s44, s16, 0x160000
	s_addc_u32 s45, s17, 0
	s_add_i32 s43, s34, s21
	s_mov_b32 m0, s43
	s_nop 0
	global_load_lds_dwordx4 v178, s[44:45]
	s_add_i32 m0, s43, 0x2000
	s_nop 0
	global_load_lds_dwordx4 v182, s[44:45]
	s_waitcnt vmcnt(10)
	s_barrier
; #define PG8_STAGE(bufoff, gbase, voff) do { _Pragma("unroll") for (int _i = 0; _i < 2; ++_i) \
;         __builtin_amdgcn_global_load_lds((const unsigned*)((const char*)(gbase) + (voff)[_i]), (LAS unsigned*)(lds + (bufoff) + ldsw + _i * 8192), 16, 0, 0); } while (0)
; #define PG8_LDA(dst, b, h) do { _Pragma("unroll") for (int m = 0; m < 4; ++m) _Pragma("unroll") for (int k = 0; k < 2; ++k) dst[m][k] = *(const LAS bf16x8*)(lds + PG8_SA(b, h) + aoff + m * 2048 + k * 1024); } while (0)
; #define PG8_LDB(dst, b, h) do { _Pragma("unroll") for (int n = 0; n < 2; ++n) _Pragma("unroll") for (int k = 0; k < 2; ++k) dst[n][k] = *(const LAS bf16x8*)(lds + PG8_SB(b, h) + boff + n * 2048 + k * 1024); } while (0)
; #define PG8_MMA(ai, bj, At, Bt) do { __builtin_amdgcn_s_setprio(1); _Pragma("unroll") for (int m = 0; m < 4; ++m) _Pragma("unroll") for (int n = 0; n < 2; ++n) _Pragma("unroll") for (int k = 0; k < 2; ++k) \
;         acc[ai][bj][m][n] = __builtin_amdgcn_mfma_f32_16x16x32_bf16(Bt[n][k], At[m][k], acc[ai][bj][m][n], 0, 0, 0); __builtin_amdgcn_s_setprio(0); } while (0)
; #define PG8_WAIT_V(n) asm volatile("s_waitcnt vmcnt(" #n ")" ::: "memory")
; #define PG8_WAIT_L(n) asm volatile("s_waitcnt lgkmcnt(" #n ")" ::: "memory")
; #define PG8_BAR __builtin_amdgcn_s_barrier()
; #define PG8_SCHED __builtin_amdgcn_sched_barrier(0)
; template <class Epi>
; __device__ __forceinline__ void gemm_phase(ldsp lds, const Gemm g, const StaticOrder& S, const Epi& E) {
;     ...
;             PG8_WAIT_V(10); PG8_BAR; PG8_MMA(1, 1, At, B1); PG8_BAR;
;             PG8_LDB(B0, 1, 0); PG8_SCHED; PG8_LDA(At, 1, 0); PG8_STAGE(PG8_SA(0, 1), a2 + hstep, voffA);
;             PG8_WAIT_L(8); PG8_WAIT_V(10); PG8_BAR; PG8_WAIT_L(0); PG8_MMA(0, 0, At, B0); PG8_BAR; PG8_SCHED;
;             PG8_LDB(B1, 1, 1); PG8_STAGE(PG8_SB(1, 0), b3, voffB);
;             PG8_WAIT_V(10); PG8_BAR; PG8_WAIT_L(0); PG8_MMA(0, 1, At, B1); PG8_BAR;
;             PG8_LDA(At, 1, 1); PG8_STAGE(PG8_SA(1, 0), a3, voffA);
;             PG8_WAIT_V(10); PG8_BAR; PG8_WAIT_L(0); PG8_MMA(1, 0, At, B0); PG8_BAR; PG8_SCHED;
	s_setprio 1
	v_mfma_f32_16x16x32_bf16 v[52:55], v[192:195], v[144:147], v[52:55]
	v_mfma_f32_16x16x32_bf16 v[48:51], v[200:203], v[144:147], v[48:51]
	v_mfma_f32_16x16x32_bf16 v[36:39], v[192:195], v[152:155], v[36:39]
	v_mfma_f32_16x16x32_bf16 v[32:35], v[200:203], v[152:155], v[32:35]
	v_mfma_f32_16x16x32_bf16 v[20:23], v[192:195], v[160:163], v[20:23]
	v_mfma_f32_16x16x32_bf16 v[16:19], v[200:203], v[160:163], v[16:19]
	v_mfma_f32_16x16x32_bf16 v[4:7], v[192:195], v[168:171], v[4:7]
	v_mfma_f32_16x16x32_bf16 v[0:3], v[200:203], v[168:171], v[0:3]
	v_mfma_f32_16x16x32_bf16 v[52:55], v[196:199], v[148:151], v[52:55]
	v_mfma_f32_16x16x32_bf16 v[48:51], v[204:207], v[148:151], v[48:51]
	v_mfma_f32_16x16x32_bf16 v[36:39], v[196:199], v[156:159], v[36:39]
	v_mfma_f32_16x16x32_bf16 v[32:35], v[204:207], v[156:159], v[32:35]
	v_mfma_f32_16x16x32_bf16 v[20:23], v[196:199], v[164:167], v[20:23]
	v_mfma_f32_16x16x32_bf16 v[16:19], v[204:207], v[164:167], v[16:19]
	v_mfma_f32_16x16x32_bf16 v[4:7], v[196:199], v[172:175], v[4:7]
	s_barrier
	v_mfma_f32_16x16x32_bf16 v[0:3], v[204:207], v[172:175], v[0:3]
	s_setprio 0
	s_add_i32 s43, 0, 0x18000
	ds_read_b128 v[128:131], v247 offset:32768
	ds_read_b128 v[132:135], v247 offset:33792
	ds_read_b128 v[136:139], v247 offset:34816
	ds_read_b128 v[140:143], v247 offset:35840
	s_add_u32 s18, s18, 0x160000
	s_addc_u32 s19, s19, 0
	s_mov_b32 m0, s24
	ds_read_b128 v[144:147], v212 offset:32768
	ds_read_b128 v[148:151], v212 offset:33792
	ds_read_b128 v[152:155], v212 offset:34816
	ds_read_b128 v[156:159], v212 offset:35840
	ds_read_b128 v[160:163], v212 offset:36864
	ds_read_b128 v[164:167], v212 offset:37888
	ds_read_b128 v[168:171], v212 offset:38912
	ds_read_b128 v[172:175], v212 offset:39936
	global_load_lds_dwordx4 v176, s[18:19]
	s_mov_b32 m0, s25
	s_nop 0
	global_load_lds_dwordx4 v180, s[18:19]
	s_waitcnt lgkmcnt(8)
	s_waitcnt vmcnt(10)
	s_barrier
	s_waitcnt lgkmcnt(0)
	s_setprio 1
	s_waitcnt lgkmcnt(0)
	v_mfma_f32_16x16x32_bf16 v[124:127], v[128:131], v[144:147], v[124:127]
	v_mfma_f32_16x16x32_bf16 v[120:123], v[136:139], v[144:147], v[120:123]
	v_mfma_f32_16x16x32_bf16 v[108:111], v[128:131], v[152:155], v[108:111]
	v_mfma_f32_16x16x32_bf16 v[104:107], v[136:139], v[152:155], v[104:107]
	v_mfma_f32_16x16x32_bf16 v[92:95], v[128:131], v[160:163], v[92:95]
	v_mfma_f32_16x16x32_bf16 v[88:91], v[136:139], v[160:163], v[88:91]
	v_mfma_f32_16x16x32_bf16 v[76:79], v[128:131], v[168:171], v[76:79]
	v_mfma_f32_16x16x32_bf16 v[72:75], v[136:139], v[168:171], v[72:75]
	v_mfma_f32_16x16x32_bf16 v[124:127], v[132:135], v[148:151], v[124:127]
	v_mfma_f32_16x16x32_bf16 v[120:123], v[140:143], v[148:151], v[120:123]
	v_mfma_f32_16x16x32_bf16 v[108:111], v[132:135], v[156:159], v[108:111]
	v_mfma_f32_16x16x32_bf16 v[104:107], v[140:143], v[156:159], v[104:107]
	v_mfma_f32_16x16x32_bf16 v[92:95], v[132:135], v[164:167], v[92:95]
	v_mfma_f32_16x16x32_bf16 v[88:91], v[140:143], v[164:167], v[88:91]
	v_mfma_f32_16x16x32_bf16 v[76:79], v[132:135], v[172:175], v[76:79]
	s_barrier
	v_mfma_f32_16x16x32_bf16 v[72:75], v[140:143], v[172:175], v[72:75]
	s_setprio 0
	s_add_i32 s18, 0, 0x1c000
	s_add_i32 s19, s43, s21
	s_mov_b32 m0, s19
	ds_read_b128 v[192:195], v247 offset:49152
	ds_read_b128 v[196:199], v247 offset:50176
	ds_read_b128 v[200:203], v247 offset:51200
	ds_read_b128 v[204:207], v247 offset:52224
	global_load_lds_dwordx4 v178, s[98:99]
	s_add_i32 m0, s19, 0x2000
	s_nop 0
	global_load_lds_dwordx4 v182, s[98:99]
	s_waitcnt vmcnt(10)
	s_barrier
	s_waitcnt lgkmcnt(0)
	s_setprio 1
	s_waitcnt lgkmcnt(0)
	v_mfma_f32_16x16x32_bf16 v[116:119], v[192:195], v[144:147], v[116:119]
	v_mfma_f32_16x16x32_bf16 v[112:115], v[200:203], v[144:147], v[112:115]
	v_mfma_f32_16x16x32_bf16 v[100:103], v[192:195], v[152:155], v[100:103]
	v_mfma_f32_16x16x32_bf16 v[96:99], v[200:203], v[152:155], v[96:99]
	v_mfma_f32_16x16x32_bf16 v[84:87], v[192:195], v[160:163], v[84:87]
	v_mfma_f32_16x16x32_bf16 v[80:83], v[200:203], v[160:163], v[80:83]
	v_mfma_f32_16x16x32_bf16 v[68:71], v[192:195], v[168:171], v[68:71]
	v_mfma_f32_16x16x32_bf16 v[64:67], v[200:203], v[168:171], v[64:67]
	v_mfma_f32_16x16x32_bf16 v[116:119], v[196:199], v[148:151], v[116:119]
	v_mfma_f32_16x16x32_bf16 v[112:115], v[204:207], v[148:151], v[112:115]
	v_mfma_f32_16x16x32_bf16 v[100:103], v[196:199], v[156:159], v[100:103]
	v_mfma_f32_16x16x32_bf16 v[96:99], v[204:207], v[156:159], v[96:99]
	v_mfma_f32_16x16x32_bf16 v[84:87], v[196:199], v[164:167], v[84:87]
	v_mfma_f32_16x16x32_bf16 v[80:83], v[204:207], v[164:167], v[80:83]
	v_mfma_f32_16x16x32_bf16 v[68:71], v[196:199], v[172:175], v[68:71]
	s_barrier
	v_mfma_f32_16x16x32_bf16 v[64:67], v[204:207], v[172:175], v[64:67]
	s_setprio 0
	s_mov_b32 m0, s27
	ds_read_b128 v[144:147], v212 offset:49152
	ds_read_b128 v[148:151], v212 offset:50176
	ds_read_b128 v[152:155], v212 offset:51200
	ds_read_b128 v[156:159], v212 offset:52224
	ds_read_b128 v[160:163], v212 offset:53248
	ds_read_b128 v[164:167], v212 offset:54272
	ds_read_b128 v[168:171], v212 offset:55296
	ds_read_b128 v[172:175], v212 offset:56320
	global_load_lds_dwordx4 v176, s[100:101]
	s_mov_b32 m0, s28
	s_nop 0
	global_load_lds_dwordx4 v180, s[100:101]
	s_waitcnt vmcnt(10)
	s_barrier
; #define PG8_STAGE(bufoff, gbase, voff) do { _Pragma("unroll") for (int _i = 0; _i < 2; ++_i) \
;         __builtin_amdgcn_global_load_lds((const unsigned*)((const char*)(gbase) + (voff)[_i]), (LAS unsigned*)(lds + (bufoff) + ldsw + _i * 8192), 16, 0, 0); } while (0)
; #define PG8_MMA(ai, bj, At, Bt) do { __builtin_amdgcn_s_setprio(1); _Pragma("unroll") for (int m = 0; m < 4; ++m) _Pragma("unroll") for (int n = 0; n < 2; ++n) _Pragma("unroll") for (int k = 0; k < 2; ++k) \
;         acc[ai][bj][m][n] = __builtin_amdgcn_mfma_f32_16x16x32_bf16(Bt[n][k], At[m][k], acc[ai][bj][m][n], 0, 0, 0); __builtin_amdgcn_s_setprio(0); } while (0)
; template <class Epi>
; __device__ __forceinline__ void gemm_phase(ldsp lds, const Gemm g, const StaticOrder& S, const Epi& E) {
;     ...
;             PG8_WAIT_V(10); PG8_BAR; PG8_WAIT_L(0); PG8_MMA(1, 0, At, B0); PG8_BAR; PG8_SCHED;
;             PG8_STAGE(PG8_SB(1, 1), b3 + hstep, voffB);
;             PG8_WAIT_V(10); PG8_BAR; PG8_MMA(1, 1, At, B1); PG8_BAR;
;     __device__ __forceinline__ void ld(f32x4 (&xv)[2][2][2], int row0, int col0, int ai, int mh) const {
;     ...
;             for (int bj = 0; bj < 2; ++bj) { const size_t off = (size_t)(row0 + ai * 128 + (2 * mh + mm) * 16) * 2048 + col0 + bj * 128;
;                 xv[mm][bj][0] = *(const f32x4*)(base + off); xv[mm][bj][1] = *(const f32x4*)(base + off + 4); }
;     }
;     __device__ __forceinline__ void fin(const f32x4 (&acc)[2][2][4][2], const f32x4 (&xv)[2][2][2], int row0, int col0, int fq, int ai, int mh) const {
; #pragma unroll
;         for (int mm = 0; mm < 2; ++mm) { const int m = 2 * mh + mm; const int row = row0 + ai * 128 + m * 16; float sq = 0.f;
; #pragma unroll
;             for (int bj = 0; bj < 2; ++bj) { const size_t off = (size_t)row * 2048 + col0 + bj * 128;
;                 const f32x4 y0 = xv[mm][bj][0] + acc[ai][bj][m][0], y1 = xv[mm][bj][1] + acc[ai][bj][m][1];
;                 *(f32x4*)(out + off) = y0; *(f32x4*)(out + off + 4) = y1;
;                 if (ob) *(u32x4*)(ob + off) = pack8(y0, y1);
;                 sq += (y0[0] * y0[0] + y0[1] * y0[1]) + (y0[2] * y0[2] + y0[3] * y0[3]) + (y1[0] * y1[0] + y1[1] * y1[1]) + (y1[2] * y1[2] + y1[3] * y1[3]); }
;             sq += __shfl_xor(sq, 16); sq += __shfl_xor(sq, 32);
;             if (fq == 0) atomicAdd(ssq + row, (unsigned long long)(sq * 16777216.0f + 0.5f)); }
	s_waitcnt lgkmcnt(0)
	s_setprio 1
	s_waitcnt lgkmcnt(0)
	v_mfma_f32_16x16x32_bf16 v[60:63], v[128:131], v[144:147], v[60:63]
	v_mfma_f32_16x16x32_bf16 v[56:59], v[136:139], v[144:147], v[56:59]
	v_mfma_f32_16x16x32_bf16 v[44:47], v[128:131], v[152:155], v[44:47]
	v_mfma_f32_16x16x32_bf16 v[40:43], v[136:139], v[152:155], v[40:43]
	v_mfma_f32_16x16x32_bf16 v[28:31], v[128:131], v[160:163], v[28:31]
	v_mfma_f32_16x16x32_bf16 v[24:27], v[136:139], v[160:163], v[24:27]
	v_mfma_f32_16x16x32_bf16 v[12:15], v[128:131], v[168:171], v[12:15]
	v_mfma_f32_16x16x32_bf16 v[8:11], v[136:139], v[168:171], v[8:11]
	v_mfma_f32_16x16x32_bf16 v[60:63], v[132:135], v[148:151], v[60:63]
	v_mfma_f32_16x16x32_bf16 v[56:59], v[140:143], v[148:151], v[56:59]
	v_mfma_f32_16x16x32_bf16 v[44:47], v[132:135], v[156:159], v[44:47]
	v_mfma_f32_16x16x32_bf16 v[40:43], v[140:143], v[156:159], v[40:43]
	v_mfma_f32_16x16x32_bf16 v[28:31], v[132:135], v[164:167], v[28:31]
	v_mfma_f32_16x16x32_bf16 v[24:27], v[140:143], v[164:167], v[24:27]
	v_mfma_f32_16x16x32_bf16 v[12:15], v[132:135], v[172:175], v[12:15]
	s_barrier
	v_mfma_f32_16x16x32_bf16 v[8:11], v[140:143], v[172:175], v[8:11]
	s_setprio 0
	s_add_u32 s16, s16, 0x160080
	s_addc_u32 s17, s17, 0
	s_add_i32 s18, s18, s21
	s_mov_b32 m0, s18
	s_nop 0
	global_load_lds_dwordx4 v178, s[16:17]
	s_add_i32 m0, s18, 0x2000
	s_nop 0
	global_load_lds_dwordx4 v182, s[16:17]
	s_waitcnt vmcnt(10)
	s_barrier
	s_setprio 1
	v_mfma_f32_16x16x32_bf16 v[52:55], v[192:195], v[144:147], v[52:55]
	v_mfma_f32_16x16x32_bf16 v[48:51], v[200:203], v[144:147], v[48:51]
	v_mfma_f32_16x16x32_bf16 v[36:39], v[192:195], v[152:155], v[36:39]
	v_mfma_f32_16x16x32_bf16 v[32:35], v[200:203], v[152:155], v[32:35]
	v_mfma_f32_16x16x32_bf16 v[20:23], v[192:195], v[160:163], v[20:23]
	v_mfma_f32_16x16x32_bf16 v[16:19], v[200:203], v[160:163], v[16:19]
	v_mfma_f32_16x16x32_bf16 v[4:7], v[192:195], v[168:171], v[4:7]
	v_mfma_f32_16x16x32_bf16 v[0:3], v[200:203], v[168:171], v[0:3]
	v_mfma_f32_16x16x32_bf16 v[52:55], v[196:199], v[148:151], v[52:55]
	v_mfma_f32_16x16x32_bf16 v[48:51], v[204:207], v[148:151], v[48:51]
	v_mfma_f32_16x16x32_bf16 v[36:39], v[196:199], v[156:159], v[36:39]
	v_mfma_f32_16x16x32_bf16 v[32:35], v[204:207], v[156:159], v[32:35]
	v_mfma_f32_16x16x32_bf16 v[20:23], v[196:199], v[164:167], v[20:23]
	v_mfma_f32_16x16x32_bf16 v[16:19], v[204:207], v[164:167], v[16:19]
	v_mfma_f32_16x16x32_bf16 v[4:7], v[196:199], v[172:175], v[4:7]
	s_barrier
	v_mfma_f32_16x16x32_bf16 v[0:3], v[204:207], v[172:175], v[0:3]
	s_setprio 0
	s_add_i32 s42, s42, 2
	s_add_u32 s14, s14, 0x100
	s_addc_u32 s15, s15, 0
	s_add_u32 s40, s40, 0x100
	s_addc_u32 s41, s41, 0
	s_cmpk_gt_u32 s42, 0x55
	s_cbranch_scc0 .LBB0_899
	v_lshl_add_u32 v192, s38, 8, v208
	v_lshl_or_b32 v128, s39, 8, v210
	v_ashrrev_i32_e32 v193, 31, v192
	v_ashrrev_i32_e32 v129, 31, v128
	v_lshlrev_b64 v[130:131], 13, v[192:193]
	v_lshl_add_u64 v[130:131], s[70:71], 0, v[130:131]
	v_lshlrev_b64 v[194:195], 2, v[128:129]
	v_lshl_add_u64 v[234:235], v[130:131], 0, v[194:195]
	global_load_dwordx4 v[216:219], v[234:235], off
	global_load_dwordx4 v[222:225], v[234:235], off offset:16
	global_load_dwordx4 v[226:229], v[234:235], off offset:512
	global_load_dwordx4 v[230:233], v[234:235], off offset:528
	v_or_b32_e32 v204, 16, v192
	v_or_b32_e32 v200, 32, v192
	v_or_b32_e32 v196, 48, v192
	v_ashrrev_i32_e32 v205, 31, v204
	v_ashrrev_i32_e32 v201, 31, v200
	v_ashrrev_i32_e32 v197, 31, v196
	v_lshlrev_b64 v[128:129], 13, v[204:205]
	v_lshlrev_b64 v[130:131], 13, v[200:201]
	v_lshlrev_b64 v[132:133], 13, v[196:197]
	v_lshl_add_u64 v[128:129], s[70:71], 0, v[128:129]
	v_lshl_add_u64 v[130:131], s[70:71], 0, v[130:131]
	v_lshl_add_u64 v[132:133], s[70:71], 0, v[132:133]
	v_lshl_add_u64 v[206:207], v[128:129], 0, v[194:195]
	v_lshl_add_u64 v[202:203], v[130:131], 0, v[194:195]
	v_lshl_add_u64 v[198:199], v[132:133], 0, v[194:195]
	global_load_dwordx4 v[168:171], v[206:207], off offset:16
	global_load_dwordx4 v[172:175], v[206:207], off
	global_load_dwordx4 v[160:163], v[206:207], off offset:528
	global_load_dwordx4 v[164:167], v[206:207], off offset:512
	global_load_dwordx4 v[152:155], v[202:203], off offset:16
	global_load_dwordx4 v[156:159], v[202:203], off
	global_load_dwordx4 v[144:147], v[202:203], off offset:528
	global_load_dwordx4 v[148:151], v[202:203], off offset:512
	global_load_dwordx4 v[136:139], v[198:199], off offset:16
	global_load_dwordx4 v[140:143], v[198:199], off
	global_load_dwordx4 v[128:131], v[198:199], off offset:528
	global_load_dwordx4 v[132:135], v[198:199], off offset:512
	v_and_b32_e32 v221, 64, v214
	v_xor_b32_e32 v215, 16, v214
	v_add_u32_e32 v221, 64, v221
	v_cmp_lt_i32_e32 vcc, v215, v221
	s_waitcnt vmcnt(0)
	v_pk_add_f32 v[126:127], v[126:127], v[218:219]
	v_pk_add_f32 v[124:125], v[124:125], v[216:217]
	v_pk_add_f32 v[118:119], v[118:119], v[228:229]
	v_pk_add_f32 v[116:117], v[116:117], v[226:227]
	v_pk_add_f32 v[120:121], v[120:121], v[222:223]
	v_pk_add_f32 v[222:223], v[112:113], v[230:231]
	v_mul_f32_e32 v112, v125, v125
	v_mul_f32_e32 v113, v127, v127
	v_mul_f32_e32 v216, v117, v117
	v_mul_f32_e32 v217, v119, v119
	v_pk_add_f32 v[122:123], v[122:123], v[224:225]
	v_pk_add_f32 v[224:225], v[114:115], v[232:233]
	v_mul_f32_e32 v114, v121, v121
	v_mul_f32_e32 v218, v223, v223
	v_fmac_f32_e32 v112, v124, v124
	v_fmac_f32_e32 v113, v126, v126
	v_fmac_f32_e32 v216, v116, v116
	v_fmac_f32_e32 v217, v118, v118
	v_mul_f32_e32 v115, v123, v123
	v_mul_f32_e32 v219, v225, v225
	v_fmac_f32_e32 v114, v120, v120
	v_fmac_f32_e32 v218, v222, v222
	v_add_f32_e32 v112, v112, v113
	v_add_f32_e32 v113, v216, v217
	v_fmac_f32_e32 v115, v122, v122
	v_fmac_f32_e32 v219, v224, v224
	v_add_f32_e32 v112, v112, v114
	v_add_f32_e32 v113, v113, v218
	v_cndmask_b32_e32 v215, v214, v215, vcc
	v_add_f32_e32 v112, v115, v112
	v_add_f32_e32 v113, v219, v113
	v_lshlrev_b32_e32 v215, 2, v215
	v_add_f32_e32 v112, v112, v113
	ds_bpermute_b32 v113, v215, v112
	v_xor_b32_e32 v114, 32, v214
	v_cmp_lt_i32_e32 vcc, v114, v221
	global_store_dwordx4 v[234:235], v[124:127], off
	global_store_dwordx4 v[234:235], v[120:123], off offset:16
	global_store_dwordx4 v[234:235], v[116:119], off offset:512
	global_store_dwordx4 v[234:235], v[222:225], off offset:528
	v_cndmask_b32_e32 v114, v214, v114, vcc
	v_lshlrev_b32_e32 v216, 2, v114
	s_waitcnt lgkmcnt(0)
	v_add_f32_e32 v112, v112, v113
	ds_bpermute_b32 v113, v216, v112
	s_and_saveexec_b64 s[14:15], s[2:3]
	s_cbranch_execz .LBB0_902
	s_waitcnt lgkmcnt(0)
	v_add_f32_e32 v112, v112, v113
	v_fma_f32 v112, v112, s35, 0.5
	v_trunc_f32_e32 v112, v112
	v_mul_f32_e32 v113, 0x2f800000, v112
	v_floor_f32_e32 v113, v113
	v_fmac_f32_e32 v112, 0xcf800000, v113
	v_cvt_u32_f32_e32 v112, v112
	v_cvt_u32_f32_e32 v113, v113
	v_lshl_add_u64 v[114:115], v[192:193], 3, s[8:9]
	global_atomic_add_x2 v[114:115], v[112:113], off
